# GEMM K-loops: per-cluster s_setprio flips deleted, one static s_setprio 1 for waves 4-7 before each K loop (static priority raise for the younger half)
# speedup vs baseline: 1.0047x; 1.0013x over previous
; #define PG8_STAGE(bufoff, gbase, voff) do { _Pragma("unroll") for (int _i = 0; _i < 2; ++_i) \
;         __builtin_amdgcn_global_load_lds((const unsigned*)((const char*)(gbase) + (voff)[_i]), (PG8_LAS unsigned*)(lds + (bufoff) + ldsw + _i * 8192), 16, 0, 0); } while (0)
; #define PG8_LDA(dst, b, h) do { _Pragma("unroll") for (int m = 0; m < 4; ++m) _Pragma("unroll") for (int k = 0; k < 2; ++k) dst[m][k] = *(const PG8_LAS bf16x8*)(lds + PG8_SA(b, h) + aoff + m * 2048 + k * 1024); } while (0)
; #define PG8_LDB(dst, b, h) do { _Pragma("unroll") for (int n = 0; n < 2; ++n) _Pragma("unroll") for (int k = 0; k < 2; ++k) dst[n][k] = *(const PG8_LAS bf16x8*)(lds + PG8_SB(b, h) + boff + n * 2048 + k * 1024); } while (0)
; #define PG8_MMA(ai, bj, At, Bt) do { __builtin_amdgcn_s_setprio(1); _Pragma("unroll") for (int m = 0; m < 4; ++m) _Pragma("unroll") for (int n = 0; n < 2; ++n) _Pragma("unroll") for (int k = 0; k < 2; ++k) \
;         acc[ai][bj][m][n] = __builtin_amdgcn_mfma_f32_16x16x32_bf16(Bt[n][k], At[m][k], acc[ai][bj][m][n], 0, 0, 0); __builtin_amdgcn_s_setprio(0); } while (0)
; #define PG8_WAIT_V(n) asm volatile("s_waitcnt vmcnt(" #n ")" ::: "memory")
; #define PG8_WAIT_L(n) asm volatile("s_waitcnt lgkmcnt(" #n ")" ::: "memory")
; #define PG8_BAR __builtin_amdgcn_s_barrier()
; #define PG8_SCHED __builtin_amdgcn_sched_barrier(0)
; template <class Epi, class Sched, bool ALIGN_EPI = false, bool SP2 = false>
; __device__ __forceinline__ void gemm_phase(PG8_LAS unsigned char* lds, const Gemm g, const Sched& S, const Epi& E) {
;     ...
;             PG8_LDB(B0, 0, 0); PG8_LDB(B1, 0, 1); PG8_SCHED; PG8_LDA(At, 0, 0); PG8_STAGE(PG8_SA(1, 1), a1 + hstep, voffA);
;             PG8_WAIT_V(8); PG8_WAIT_L(0); PG8_BAR; PG8_MMA(0, 0, At, B0); PG8_MMA(0, 1, At, B1); PG8_BAR; PG8_SCHED;
;     ...
; #pragma unroll
;         for (int a = 0; a < 2; ++a)
; #pragma unroll
;             for (int b = 0; b < 2; ++b)
; #pragma unroll
;                 for (int m = 0; m < 4; ++m)
; #pragma unroll
;                     for (int n = 0; n < 2; ++n) acc[a][b][m][n] = (f32x4){0.f, 0.f, 0.f, 0.f};
.LBB0_187:
	s_ashr_i32 s27, s26, 31
	s_lshl_b64 s[28:29], s[26:27], 19
	s_add_u32 s28, s48, s28
	s_addc_u32 s29, s49, s29
	s_and_b64 s[30:31], s[2:3], exec
	s_cselect_b32 s27, s29, s37
	s_cselect_b32 s87, s28, s36
	s_ashr_i32 s25, s24, 31
	s_lshl_b64 s[30:31], s[24:25], 19
	s_add_u32 s30, s6, s30
	s_addc_u32 s31, s7, s31
	s_and_b64 s[46:47], s[2:3], exec
	s_cselect_b32 s25, s31, s45
	s_cselect_b32 s88, s30, s44
	s_add_u32 s36, s36, 0x40080
	s_addc_u32 s37, s37, 0
	s_add_u32 s89, s44, 0x100
	v_mov_b32_e32 v0, 0
	s_addc_u32 s90, s45, 0
	s_mov_b32 s91, -2
	v_mov_b32_e32 v1, v0
	v_mov_b32_e32 v2, v0
	v_mov_b32_e32 v3, v0
	v_mov_b32_e32 v4, v0
	v_mov_b32_e32 v5, v0
	v_mov_b32_e32 v6, v0
	v_mov_b32_e32 v7, v0
	v_mov_b32_e32 v16, v0
	v_mov_b32_e32 v17, v0
	v_mov_b32_e32 v18, v0
	v_mov_b32_e32 v19, v0
	v_mov_b32_e32 v20, v0
	v_mov_b32_e32 v21, v0
	v_mov_b32_e32 v22, v0
	v_mov_b32_e32 v23, v0
	v_mov_b32_e32 v32, v0
	v_mov_b32_e32 v33, v0
	v_mov_b32_e32 v34, v0
	v_mov_b32_e32 v35, v0
	v_mov_b32_e32 v36, v0
	v_mov_b32_e32 v37, v0
	v_mov_b32_e32 v38, v0
	v_mov_b32_e32 v39, v0
	v_mov_b32_e32 v48, v0
	v_mov_b32_e32 v49, v0
	v_mov_b32_e32 v50, v0
	v_mov_b32_e32 v51, v0
	v_mov_b32_e32 v52, v0
	v_mov_b32_e32 v53, v0
	v_mov_b32_e32 v54, v0
	v_mov_b32_e32 v55, v0
	v_mov_b32_e32 v8, v0
	v_mov_b32_e32 v9, v0
	v_mov_b32_e32 v10, v0
	v_mov_b32_e32 v11, v0
	v_mov_b32_e32 v12, v0
	v_mov_b32_e32 v13, v0
	v_mov_b32_e32 v14, v0
	v_mov_b32_e32 v15, v0
	v_mov_b32_e32 v24, v0
	v_mov_b32_e32 v25, v0
	v_mov_b32_e32 v26, v0
	v_mov_b32_e32 v27, v0
	v_mov_b32_e32 v28, v0
	v_mov_b32_e32 v29, v0
	v_mov_b32_e32 v30, v0
	v_mov_b32_e32 v31, v0
	v_mov_b32_e32 v40, v0
	v_mov_b32_e32 v41, v0
	v_mov_b32_e32 v42, v0
	v_mov_b32_e32 v43, v0
	v_mov_b32_e32 v44, v0
	v_mov_b32_e32 v45, v0
	v_mov_b32_e32 v46, v0
	v_mov_b32_e32 v47, v0
	v_mov_b32_e32 v56, v0
	v_mov_b32_e32 v57, v0
	v_mov_b32_e32 v58, v0
	v_mov_b32_e32 v59, v0
	v_mov_b32_e32 v60, v0
	v_mov_b32_e32 v61, v0
	v_mov_b32_e32 v62, v0
	v_mov_b32_e32 v63, v0
	v_mov_b32_e32 v64, v0
	v_mov_b32_e32 v65, v0
	v_mov_b32_e32 v66, v0
	v_mov_b32_e32 v67, v0
	v_mov_b32_e32 v68, v0
	v_mov_b32_e32 v69, v0
	v_mov_b32_e32 v70, v0
	v_mov_b32_e32 v71, v0
	v_mov_b32_e32 v80, v0
	v_mov_b32_e32 v81, v0
	v_mov_b32_e32 v82, v0
	v_mov_b32_e32 v83, v0
	v_mov_b32_e32 v84, v0
	v_mov_b32_e32 v85, v0
	v_mov_b32_e32 v86, v0
	v_mov_b32_e32 v87, v0
	v_mov_b32_e32 v96, v0
	v_mov_b32_e32 v97, v0
	v_mov_b32_e32 v98, v0
	v_mov_b32_e32 v99, v0
	v_mov_b32_e32 v100, v0
	v_mov_b32_e32 v101, v0
	v_mov_b32_e32 v102, v0
	v_mov_b32_e32 v103, v0
	v_mov_b32_e32 v112, v0
	v_mov_b32_e32 v113, v0
	v_mov_b32_e32 v114, v0
	v_mov_b32_e32 v115, v0
	v_mov_b32_e32 v116, v0
	v_mov_b32_e32 v117, v0
	v_mov_b32_e32 v118, v0
	v_mov_b32_e32 v119, v0
	v_mov_b32_e32 v72, v0
	v_mov_b32_e32 v73, v0
	v_mov_b32_e32 v74, v0
	v_mov_b32_e32 v75, v0
	v_mov_b32_e32 v76, v0
	v_mov_b32_e32 v77, v0
	v_mov_b32_e32 v78, v0
	v_mov_b32_e32 v79, v0
	v_mov_b32_e32 v88, v0
	v_mov_b32_e32 v89, v0
	v_mov_b32_e32 v90, v0
	v_mov_b32_e32 v91, v0
	v_mov_b32_e32 v92, v0
	v_mov_b32_e32 v93, v0
	v_mov_b32_e32 v94, v0
	v_mov_b32_e32 v95, v0
	v_mov_b32_e32 v104, v0
	v_mov_b32_e32 v105, v0
	v_mov_b32_e32 v106, v0
	v_mov_b32_e32 v107, v0
	v_mov_b32_e32 v108, v0
	v_mov_b32_e32 v109, v0
	v_mov_b32_e32 v110, v0
	v_mov_b32_e32 v111, v0
	v_mov_b32_e32 v120, v0
	v_mov_b32_e32 v121, v0
	v_mov_b32_e32 v122, v0
	v_mov_b32_e32 v123, v0
	v_mov_b32_e32 v124, v0
	v_mov_b32_e32 v125, v0
	v_mov_b32_e32 v126, v0
	v_mov_b32_e32 v127, v0
	s_bitcmp1_b32 s60, 2
	s_cbranch_scc0 .Lgprio_0
	s_setprio 1
.Lgprio_0:
.LBB0_188:
	ds_read_b128 v[144:147], v154
	ds_read_b128 v[158:161], v154 offset:1024
	ds_read_b128 v[162:165], v154 offset:2048
	ds_read_b128 v[166:169], v154 offset:3072
	ds_read_b128 v[170:173], v155
	ds_read_b128 v[174:177], v155 offset:1024
	ds_read_b128 v[178:181], v155 offset:2048
	ds_read_b128 v[186:189], v155 offset:3072
	s_add_u32 s44, s36, 0xfffc0080
	s_addc_u32 s45, s37, -1
	s_cmp_eq_u32 s91, 12
	s_cselect_b32 s47, s27, s45
	s_cselect_b32 s46, s87, s44
	s_cselect_b32 s45, s25, s90
	s_cselect_b32 s44, s88, s89
	v_lshl_add_u64 v[182:183], s[36:37], 0, v[136:137]
	s_add_i32 m0, s69, 0xc000
	ds_read_b128 v[190:193], v156
	ds_read_b128 v[194:197], v156 offset:1024
	ds_read_b128 v[198:201], v156 offset:2048
	ds_read_b128 v[202:205], v156 offset:3072
	ds_read_b128 v[206:209], v156 offset:4096
	ds_read_b128 v[210:213], v156 offset:5120
	ds_read_b128 v[214:217], v156 offset:6144
	ds_read_b128 v[218:221], v156 offset:7168
	global_load_lds_dwordx4 v[182:183], off
	v_lshl_add_u64 v[182:183], s[36:37], 0, v[138:139]
	s_add_i32 m0, s69, 0xe000
	s_nop 0
	global_load_lds_dwordx4 v[182:183], off
	s_waitcnt vmcnt(8)
	s_waitcnt lgkmcnt(0)
	s_barrier
; #define PG8_STAGE(bufoff, gbase, voff) do { _Pragma("unroll") for (int _i = 0; _i < 2; ++_i) \
;         __builtin_amdgcn_global_load_lds((const unsigned*)((const char*)(gbase) + (voff)[_i]), (PG8_LAS unsigned*)(lds + (bufoff) + ldsw + _i * 8192), 16, 0, 0); } while (0)
; #define PG8_LDA(dst, b, h) do { _Pragma("unroll") for (int m = 0; m < 4; ++m) _Pragma("unroll") for (int k = 0; k < 2; ++k) dst[m][k] = *(const PG8_LAS bf16x8*)(lds + PG8_SA(b, h) + aoff + m * 2048 + k * 1024); } while (0)
; #define PG8_MMA(ai, bj, At, Bt) do { __builtin_amdgcn_s_setprio(1); _Pragma("unroll") for (int m = 0; m < 4; ++m) _Pragma("unroll") for (int n = 0; n < 2; ++n) _Pragma("unroll") for (int k = 0; k < 2; ++k) \
;         acc[ai][bj][m][n] = __builtin_amdgcn_mfma_f32_16x16x32_bf16(Bt[n][k], At[m][k], acc[ai][bj][m][n], 0, 0, 0); __builtin_amdgcn_s_setprio(0); } while (0)
; #define PG8_WAIT_V(n) asm volatile("s_waitcnt vmcnt(" #n ")" ::: "memory")
; #define PG8_WAIT_L(n) asm volatile("s_waitcnt lgkmcnt(" #n ")" ::: "memory")
; #define PG8_BAR __builtin_amdgcn_s_barrier()
; #define PG8_SCHED __builtin_amdgcn_sched_barrier(0)
; template <class Epi, class Sched, bool ALIGN_EPI = false, bool SP2 = false>
; __device__ __forceinline__ void gemm_phase(PG8_LAS unsigned char* lds, const Gemm g, const Sched& S, const Epi& E) {
;     ...
;             PG8_WAIT_V(8); PG8_WAIT_L(0); PG8_BAR; PG8_MMA(0, 0, At, B0); PG8_MMA(0, 1, At, B1); PG8_BAR; PG8_SCHED;
;             PG8_LDA(At, 0, 1); PG8_STAGE(PG8_SB(0, 0), b2, voffB); PG8_STAGE(PG8_SB(0, 1), b2 + hstep, voffB); PG8_STAGE(PG8_SA(0, 0), a2, voffA);
;             PG8_WAIT_V(8); PG8_WAIT_L(0); PG8_BAR; PG8_MMA(1, 0, At, B0); PG8_MMA(1, 1, At, B1); PG8_BAR; PG8_SCHED;
	s_waitcnt lgkmcnt(0)
	v_mfma_f32_16x16x32_bf16 v[124:127], v[144:147], v[190:193], v[124:127]
	v_mfma_f32_16x16x32_bf16 v[120:123], v[162:165], v[190:193], v[120:123]
	v_mfma_f32_16x16x32_bf16 v[108:111], v[144:147], v[198:201], v[108:111]
	v_mfma_f32_16x16x32_bf16 v[104:107], v[162:165], v[198:201], v[104:107]
	v_mfma_f32_16x16x32_bf16 v[92:95], v[144:147], v[206:209], v[92:95]
	v_mfma_f32_16x16x32_bf16 v[88:91], v[162:165], v[206:209], v[88:91]
	v_mfma_f32_16x16x32_bf16 v[76:79], v[144:147], v[214:217], v[76:79]
	v_mfma_f32_16x16x32_bf16 v[72:75], v[162:165], v[214:217], v[72:75]
	v_mfma_f32_16x16x32_bf16 v[124:127], v[158:161], v[194:197], v[124:127]
	v_mfma_f32_16x16x32_bf16 v[120:123], v[166:169], v[194:197], v[120:123]
	v_mfma_f32_16x16x32_bf16 v[108:111], v[158:161], v[202:205], v[108:111]
	v_mfma_f32_16x16x32_bf16 v[104:107], v[166:169], v[202:205], v[104:107]
	v_mfma_f32_16x16x32_bf16 v[92:95], v[158:161], v[210:213], v[92:95]
	v_mfma_f32_16x16x32_bf16 v[88:91], v[166:169], v[210:213], v[88:91]
	v_mfma_f32_16x16x32_bf16 v[76:79], v[158:161], v[218:221], v[76:79]
	v_mfma_f32_16x16x32_bf16 v[72:75], v[166:169], v[218:221], v[72:75]
	v_mfma_f32_16x16x32_bf16 v[116:119], v[170:173], v[190:193], v[116:119]
	v_mfma_f32_16x16x32_bf16 v[112:115], v[178:181], v[190:193], v[112:115]
	v_mfma_f32_16x16x32_bf16 v[100:103], v[170:173], v[198:201], v[100:103]
	v_mfma_f32_16x16x32_bf16 v[96:99], v[178:181], v[198:201], v[96:99]
	v_mfma_f32_16x16x32_bf16 v[84:87], v[170:173], v[206:209], v[84:87]
	v_mfma_f32_16x16x32_bf16 v[80:83], v[178:181], v[206:209], v[80:83]
	v_mfma_f32_16x16x32_bf16 v[68:71], v[170:173], v[214:217], v[68:71]
	v_mfma_f32_16x16x32_bf16 v[64:67], v[178:181], v[214:217], v[64:67]
	v_mfma_f32_16x16x32_bf16 v[116:119], v[174:177], v[194:197], v[116:119]
	v_mfma_f32_16x16x32_bf16 v[112:115], v[186:189], v[194:197], v[112:115]
	v_mfma_f32_16x16x32_bf16 v[100:103], v[174:177], v[202:205], v[100:103]
	v_mfma_f32_16x16x32_bf16 v[96:99], v[186:189], v[202:205], v[96:99]
	v_mfma_f32_16x16x32_bf16 v[84:87], v[174:177], v[210:213], v[84:87]
	v_mfma_f32_16x16x32_bf16 v[80:83], v[186:189], v[210:213], v[80:83]
	v_mfma_f32_16x16x32_bf16 v[68:71], v[174:177], v[218:221], v[68:71]
	v_mfma_f32_16x16x32_bf16 v[64:67], v[186:189], v[218:221], v[64:67]
	s_barrier
	s_add_i32 s92, s82, s50
	v_lshl_add_u64 v[182:183], s[44:45], 0, v[132:133]
	s_mov_b32 m0, s92
	ds_read_b128 v[190:193], v156 offset:16384
	ds_read_b128 v[194:197], v156 offset:17408
	ds_read_b128 v[198:201], v156 offset:18432
	ds_read_b128 v[202:205], v156 offset:19456
	ds_read_b128 v[206:209], v156 offset:20480
	ds_read_b128 v[210:213], v156 offset:21504
	ds_read_b128 v[214:217], v156 offset:22528
	ds_read_b128 v[218:221], v156 offset:23552
	global_load_lds_dwordx4 v[182:183], off
	s_add_i32 m0, s92, 0x2000
	s_add_u32 s92, s44, 0x40000
	v_lshl_add_u64 v[222:223], s[44:45], 0, v[128:129]
	s_addc_u32 s93, s45, 0
	s_add_i32 s94, s83, s50
	global_load_lds_dwordx4 v[222:223], off
	v_lshl_add_u64 v[224:225], s[92:93], 0, v[132:133]
	s_mov_b32 m0, s94
	v_lshl_add_u64 v[226:227], s[46:47], 0, v[130:131]
	global_load_lds_dwordx4 v[224:225], off
	v_lshl_add_u64 v[224:225], s[92:93], 0, v[128:129]
	s_add_i32 m0, s94, 0x2000
	s_nop 0
	global_load_lds_dwordx4 v[224:225], off
	v_lshl_add_u64 v[224:225], s[46:47], 0, v[134:135]
	s_mov_b32 m0, s69
	s_nop 0
	global_load_lds_dwordx4 v[224:225], off
	s_mov_b32 m0, s70
	s_nop 0
	global_load_lds_dwordx4 v[226:227], off
	s_waitcnt vmcnt(8)
	s_waitcnt lgkmcnt(0)
	s_barrier
	s_waitcnt lgkmcnt(0)
	v_mfma_f32_16x16x32_bf16 v[60:63], v[144:147], v[190:193], v[60:63]
	v_mfma_f32_16x16x32_bf16 v[56:59], v[162:165], v[190:193], v[56:59]
	v_mfma_f32_16x16x32_bf16 v[44:47], v[144:147], v[198:201], v[44:47]
	v_mfma_f32_16x16x32_bf16 v[40:43], v[162:165], v[198:201], v[40:43]
	v_mfma_f32_16x16x32_bf16 v[28:31], v[144:147], v[206:209], v[28:31]
	v_mfma_f32_16x16x32_bf16 v[24:27], v[162:165], v[206:209], v[24:27]
	v_mfma_f32_16x16x32_bf16 v[12:15], v[144:147], v[214:217], v[12:15]
	v_mfma_f32_16x16x32_bf16 v[8:11], v[162:165], v[214:217], v[8:11]
	v_mfma_f32_16x16x32_bf16 v[60:63], v[158:161], v[194:197], v[60:63]
	v_mfma_f32_16x16x32_bf16 v[56:59], v[166:169], v[194:197], v[56:59]
	v_mfma_f32_16x16x32_bf16 v[44:47], v[158:161], v[202:205], v[44:47]
	v_mfma_f32_16x16x32_bf16 v[40:43], v[166:169], v[202:205], v[40:43]
	v_mfma_f32_16x16x32_bf16 v[28:31], v[158:161], v[210:213], v[28:31]
	v_mfma_f32_16x16x32_bf16 v[24:27], v[166:169], v[210:213], v[24:27]
	v_mfma_f32_16x16x32_bf16 v[12:15], v[158:161], v[218:221], v[12:15]
	v_mfma_f32_16x16x32_bf16 v[8:11], v[166:169], v[218:221], v[8:11]
	v_mfma_f32_16x16x32_bf16 v[52:55], v[170:173], v[190:193], v[52:55]
	v_mfma_f32_16x16x32_bf16 v[48:51], v[178:181], v[190:193], v[48:51]
	v_mfma_f32_16x16x32_bf16 v[36:39], v[170:173], v[198:201], v[36:39]
	v_mfma_f32_16x16x32_bf16 v[32:35], v[178:181], v[198:201], v[32:35]
	v_mfma_f32_16x16x32_bf16 v[20:23], v[170:173], v[206:209], v[20:23]
	v_mfma_f32_16x16x32_bf16 v[16:19], v[178:181], v[206:209], v[16:19]
	v_mfma_f32_16x16x32_bf16 v[4:7], v[170:173], v[214:217], v[4:7]
	v_mfma_f32_16x16x32_bf16 v[0:3], v[178:181], v[214:217], v[0:3]
	v_mfma_f32_16x16x32_bf16 v[52:55], v[174:177], v[194:197], v[52:55]
	v_mfma_f32_16x16x32_bf16 v[48:51], v[186:189], v[194:197], v[48:51]
	v_mfma_f32_16x16x32_bf16 v[36:39], v[174:177], v[202:205], v[36:39]
	v_mfma_f32_16x16x32_bf16 v[32:35], v[186:189], v[202:205], v[32:35]
	v_mfma_f32_16x16x32_bf16 v[20:23], v[174:177], v[210:213], v[20:23]
	v_mfma_f32_16x16x32_bf16 v[16:19], v[186:189], v[210:213], v[16:19]
	v_mfma_f32_16x16x32_bf16 v[4:7], v[174:177], v[218:221], v[4:7]
	v_mfma_f32_16x16x32_bf16 v[0:3], v[186:189], v[218:221], v[0:3]
	s_barrier
; #define PG8_STAGE(bufoff, gbase, voff) do { _Pragma("unroll") for (int _i = 0; _i < 2; ++_i) \
;         __builtin_amdgcn_global_load_lds((const unsigned*)((const char*)(gbase) + (voff)[_i]), (PG8_LAS unsigned*)(lds + (bufoff) + ldsw + _i * 8192), 16, 0, 0); } while (0)
; #define PG8_LDA(dst, b, h) do { _Pragma("unroll") for (int m = 0; m < 4; ++m) _Pragma("unroll") for (int k = 0; k < 2; ++k) dst[m][k] = *(const PG8_LAS bf16x8*)(lds + PG8_SA(b, h) + aoff + m * 2048 + k * 1024); } while (0)
; #define PG8_LDB(dst, b, h) do { _Pragma("unroll") for (int n = 0; n < 2; ++n) _Pragma("unroll") for (int k = 0; k < 2; ++k) dst[n][k] = *(const PG8_LAS bf16x8*)(lds + PG8_SB(b, h) + boff + n * 2048 + k * 1024); } while (0)
; #define PG8_MMA(ai, bj, At, Bt) do { __builtin_amdgcn_s_setprio(1); _Pragma("unroll") for (int m = 0; m < 4; ++m) _Pragma("unroll") for (int n = 0; n < 2; ++n) _Pragma("unroll") for (int k = 0; k < 2; ++k) \
;         acc[ai][bj][m][n] = __builtin_amdgcn_mfma_f32_16x16x32_bf16(Bt[n][k], At[m][k], acc[ai][bj][m][n], 0, 0, 0); __builtin_amdgcn_s_setprio(0); } while (0)
; #define PG8_WAIT_V(n) asm volatile("s_waitcnt vmcnt(" #n ")" ::: "memory")
; #define PG8_WAIT_L(n) asm volatile("s_waitcnt lgkmcnt(" #n ")" ::: "memory")
; #define PG8_BAR __builtin_amdgcn_s_barrier()
; #define PG8_SCHED __builtin_amdgcn_sched_barrier(0)
; template <class Epi, class Sched, bool ALIGN_EPI = false, bool SP2 = false>
; __device__ __forceinline__ void gemm_phase(PG8_LAS unsigned char* lds, const Gemm g, const Sched& S, const Epi& E) {
;     ...
;             PG8_LDB(B0, 1, 0); PG8_LDB(B1, 1, 1); PG8_SCHED; PG8_LDA(At, 1, 0); PG8_STAGE(PG8_SA(0, 1), a2 + hstep, voffA);
;             PG8_WAIT_V(8); PG8_WAIT_L(0); PG8_BAR; PG8_MMA(0, 0, At, B0); PG8_MMA(0, 1, At, B1); PG8_BAR; PG8_SCHED;
	s_add_i32 s92, 0, 0x18000
	v_add_u32_e32 v148, s92, v151
	s_add_i32 s93, 0, 0x1c000
	ds_read_b128 v[144:147], v148
	ds_read_b128 v[158:161], v148 offset:1024
	ds_read_b128 v[162:165], v148 offset:2048
	ds_read_b128 v[166:169], v148 offset:3072
	v_add_u32_e32 v148, s93, v151
	ds_read_b128 v[170:173], v148
	ds_read_b128 v[174:177], v148 offset:1024
	ds_read_b128 v[178:181], v148 offset:2048
	ds_read_b128 v[186:189], v148 offset:3072
	s_add_u32 s46, s46, 0x40000
	s_addc_u32 s47, s47, 0
	s_mov_b32 m0, s71
	v_lshl_add_u64 v[228:229], s[46:47], 0, v[134:135]
	ds_read_b128 v[190:193], v156 offset:32768
	ds_read_b128 v[194:197], v156 offset:33792
	ds_read_b128 v[198:201], v156 offset:34816
	ds_read_b128 v[202:205], v156 offset:35840
	ds_read_b128 v[206:209], v156 offset:36864
	ds_read_b128 v[210:213], v156 offset:37888
	ds_read_b128 v[214:217], v156 offset:38912
	ds_read_b128 v[218:221], v156 offset:39936
	global_load_lds_dwordx4 v[228:229], off
	v_lshl_add_u64 v[228:229], s[46:47], 0, v[130:131]
	s_mov_b32 m0, s72
	s_nop 0
	global_load_lds_dwordx4 v[228:229], off
	s_waitcnt vmcnt(8)
	s_waitcnt lgkmcnt(0)
	s_barrier
	s_waitcnt lgkmcnt(0)
	v_mfma_f32_16x16x32_bf16 v[124:127], v[144:147], v[190:193], v[124:127]
	v_mfma_f32_16x16x32_bf16 v[120:123], v[162:165], v[190:193], v[120:123]
	v_mfma_f32_16x16x32_bf16 v[108:111], v[144:147], v[198:201], v[108:111]
	v_mfma_f32_16x16x32_bf16 v[104:107], v[162:165], v[198:201], v[104:107]
	v_mfma_f32_16x16x32_bf16 v[92:95], v[144:147], v[206:209], v[92:95]
	v_mfma_f32_16x16x32_bf16 v[88:91], v[162:165], v[206:209], v[88:91]
	v_mfma_f32_16x16x32_bf16 v[76:79], v[144:147], v[214:217], v[76:79]
	v_mfma_f32_16x16x32_bf16 v[72:75], v[162:165], v[214:217], v[72:75]
	v_mfma_f32_16x16x32_bf16 v[124:127], v[158:161], v[194:197], v[124:127]
	v_mfma_f32_16x16x32_bf16 v[120:123], v[166:169], v[194:197], v[120:123]
	v_mfma_f32_16x16x32_bf16 v[108:111], v[158:161], v[202:205], v[108:111]
	v_mfma_f32_16x16x32_bf16 v[104:107], v[166:169], v[202:205], v[104:107]
	v_mfma_f32_16x16x32_bf16 v[92:95], v[158:161], v[210:213], v[92:95]
	v_mfma_f32_16x16x32_bf16 v[88:91], v[166:169], v[210:213], v[88:91]
	v_mfma_f32_16x16x32_bf16 v[76:79], v[158:161], v[218:221], v[76:79]
	v_mfma_f32_16x16x32_bf16 v[72:75], v[166:169], v[218:221], v[72:75]
	v_mfma_f32_16x16x32_bf16 v[116:119], v[170:173], v[190:193], v[116:119]
	v_mfma_f32_16x16x32_bf16 v[112:115], v[178:181], v[190:193], v[112:115]
	v_mfma_f32_16x16x32_bf16 v[100:103], v[170:173], v[198:201], v[100:103]
	v_mfma_f32_16x16x32_bf16 v[96:99], v[178:181], v[198:201], v[96:99]
	v_mfma_f32_16x16x32_bf16 v[84:87], v[170:173], v[206:209], v[84:87]
	v_mfma_f32_16x16x32_bf16 v[80:83], v[178:181], v[206:209], v[80:83]
	v_mfma_f32_16x16x32_bf16 v[68:71], v[170:173], v[214:217], v[68:71]
	v_mfma_f32_16x16x32_bf16 v[64:67], v[178:181], v[214:217], v[64:67]
	v_mfma_f32_16x16x32_bf16 v[116:119], v[174:177], v[194:197], v[116:119]
	v_mfma_f32_16x16x32_bf16 v[112:115], v[186:189], v[194:197], v[112:115]
	v_mfma_f32_16x16x32_bf16 v[100:103], v[174:177], v[202:205], v[100:103]
	v_mfma_f32_16x16x32_bf16 v[96:99], v[186:189], v[202:205], v[96:99]
	v_mfma_f32_16x16x32_bf16 v[84:87], v[174:177], v[210:213], v[84:87]
	v_mfma_f32_16x16x32_bf16 v[80:83], v[186:189], v[210:213], v[80:83]
	v_mfma_f32_16x16x32_bf16 v[68:71], v[174:177], v[218:221], v[68:71]
	v_mfma_f32_16x16x32_bf16 v[64:67], v[186:189], v[218:221], v[64:67]
	s_barrier
; #define PG8_STAGE(bufoff, gbase, voff) do { _Pragma("unroll") for (int _i = 0; _i < 2; ++_i) \
;         __builtin_amdgcn_global_load_lds((const unsigned*)((const char*)(gbase) + (voff)[_i]), (PG8_LAS unsigned*)(lds + (bufoff) + ldsw + _i * 8192), 16, 0, 0); } while (0)
; #define PG8_LDA(dst, b, h) do { _Pragma("unroll") for (int m = 0; m < 4; ++m) _Pragma("unroll") for (int k = 0; k < 2; ++k) dst[m][k] = *(const PG8_LAS bf16x8*)(lds + PG8_SA(b, h) + aoff + m * 2048 + k * 1024); } while (0)
; #define PG8_MMA(ai, bj, At, Bt) do { __builtin_amdgcn_s_setprio(1); _Pragma("unroll") for (int m = 0; m < 4; ++m) _Pragma("unroll") for (int n = 0; n < 2; ++n) _Pragma("unroll") for (int k = 0; k < 2; ++k) \
;         acc[ai][bj][m][n] = __builtin_amdgcn_mfma_f32_16x16x32_bf16(Bt[n][k], At[m][k], acc[ai][bj][m][n], 0, 0, 0); __builtin_amdgcn_s_setprio(0); } while (0)
; #define PG8_WAIT_V(n) asm volatile("s_waitcnt vmcnt(" #n ")" ::: "memory")
; #define PG8_WAIT_L(n) asm volatile("s_waitcnt lgkmcnt(" #n ")" ::: "memory")
; #define PG8_BAR __builtin_amdgcn_s_barrier()
; #define PG8_SCHED __builtin_amdgcn_sched_barrier(0)
; template <class Epi, class Sched, bool ALIGN_EPI = false, bool SP2 = false>
; __device__ __forceinline__ void gemm_phase(PG8_LAS unsigned char* lds, const Gemm g, const Sched& S, const Epi& E) {
;     ...
;             PG8_LDA(At, 1, 1); PG8_STAGE(PG8_SB(1, 0), b3, voffB); PG8_STAGE(PG8_SB(1, 1), b3 + hstep, voffB); PG8_STAGE(PG8_SA(1, 0), a3, voffA);
;             PG8_WAIT_V(8); PG8_WAIT_L(0); PG8_BAR; PG8_MMA(1, 0, At, B0); PG8_MMA(1, 1, At, B1); PG8_BAR; PG8_SCHED;
;     ...
;         if constexpr (ALIGN_EPI) { if (wr == 0) PG8_BAR; }
	s_add_i32 s46, s92, s50
	v_lshl_add_u64 v[182:183], v[182:183], 0, s[20:21]
	s_mov_b32 m0, s46
	ds_read_b128 v[190:193], v156 offset:49152
	ds_read_b128 v[194:197], v156 offset:50176
	ds_read_b128 v[198:201], v156 offset:51200
	ds_read_b128 v[202:205], v156 offset:52224
	ds_read_b128 v[206:209], v156 offset:53248
	ds_read_b128 v[210:213], v156 offset:54272
	ds_read_b128 v[214:217], v156 offset:55296
	ds_read_b128 v[218:221], v156 offset:56320
	global_load_lds_dwordx4 v[182:183], off
	s_add_i32 m0, s46, 0x2000
	s_add_u32 s44, s44, 0x40080
	v_lshl_add_u64 v[182:183], v[222:223], 0, s[20:21]
	s_addc_u32 s45, s45, 0
	s_add_i32 s46, s93, s50
	global_load_lds_dwordx4 v[182:183], off
	v_lshl_add_u64 v[182:183], s[44:45], 0, v[132:133]
	s_mov_b32 m0, s46
	s_nop 0
	global_load_lds_dwordx4 v[182:183], off
	v_lshl_add_u64 v[182:183], s[44:45], 0, v[128:129]
	s_add_i32 m0, s46, 0x2000
	s_nop 0
	global_load_lds_dwordx4 v[182:183], off
	v_lshl_add_u64 v[182:183], v[224:225], 0, s[20:21]
	s_mov_b32 m0, s78
	s_nop 0
	global_load_lds_dwordx4 v[182:183], off
	v_lshl_add_u64 v[182:183], v[226:227], 0, s[20:21]
	s_mov_b32 m0, s79
	s_nop 0
	global_load_lds_dwordx4 v[182:183], off
	s_waitcnt vmcnt(8)
	s_waitcnt lgkmcnt(0)
	s_barrier
	s_waitcnt lgkmcnt(0)
	v_mfma_f32_16x16x32_bf16 v[60:63], v[144:147], v[190:193], v[60:63]
	v_mfma_f32_16x16x32_bf16 v[56:59], v[162:165], v[190:193], v[56:59]
	v_mfma_f32_16x16x32_bf16 v[44:47], v[144:147], v[198:201], v[44:47]
	v_mfma_f32_16x16x32_bf16 v[40:43], v[162:165], v[198:201], v[40:43]
	v_mfma_f32_16x16x32_bf16 v[28:31], v[144:147], v[206:209], v[28:31]
	v_mfma_f32_16x16x32_bf16 v[24:27], v[162:165], v[206:209], v[24:27]
	v_mfma_f32_16x16x32_bf16 v[12:15], v[144:147], v[214:217], v[12:15]
	v_mfma_f32_16x16x32_bf16 v[8:11], v[162:165], v[214:217], v[8:11]
	v_mfma_f32_16x16x32_bf16 v[60:63], v[158:161], v[194:197], v[60:63]
	v_mfma_f32_16x16x32_bf16 v[56:59], v[166:169], v[194:197], v[56:59]
	v_mfma_f32_16x16x32_bf16 v[44:47], v[158:161], v[202:205], v[44:47]
	v_mfma_f32_16x16x32_bf16 v[40:43], v[166:169], v[202:205], v[40:43]
	v_mfma_f32_16x16x32_bf16 v[28:31], v[158:161], v[210:213], v[28:31]
	v_mfma_f32_16x16x32_bf16 v[24:27], v[166:169], v[210:213], v[24:27]
	v_mfma_f32_16x16x32_bf16 v[12:15], v[158:161], v[218:221], v[12:15]
	v_mfma_f32_16x16x32_bf16 v[8:11], v[166:169], v[218:221], v[8:11]
	v_mfma_f32_16x16x32_bf16 v[52:55], v[170:173], v[190:193], v[52:55]
	v_mfma_f32_16x16x32_bf16 v[48:51], v[178:181], v[190:193], v[48:51]
	v_mfma_f32_16x16x32_bf16 v[36:39], v[170:173], v[198:201], v[36:39]
	v_mfma_f32_16x16x32_bf16 v[32:35], v[178:181], v[198:201], v[32:35]
	v_mfma_f32_16x16x32_bf16 v[20:23], v[170:173], v[206:209], v[20:23]
	v_mfma_f32_16x16x32_bf16 v[16:19], v[178:181], v[206:209], v[16:19]
	v_mfma_f32_16x16x32_bf16 v[4:7], v[170:173], v[214:217], v[4:7]
	v_mfma_f32_16x16x32_bf16 v[0:3], v[178:181], v[214:217], v[0:3]
	v_mfma_f32_16x16x32_bf16 v[52:55], v[174:177], v[194:197], v[52:55]
	v_mfma_f32_16x16x32_bf16 v[48:51], v[186:189], v[194:197], v[48:51]
	v_mfma_f32_16x16x32_bf16 v[36:39], v[174:177], v[202:205], v[36:39]
	v_mfma_f32_16x16x32_bf16 v[32:35], v[186:189], v[202:205], v[32:35]
	v_mfma_f32_16x16x32_bf16 v[20:23], v[174:177], v[210:213], v[20:23]
	v_mfma_f32_16x16x32_bf16 v[16:19], v[186:189], v[210:213], v[16:19]
	v_mfma_f32_16x16x32_bf16 v[4:7], v[174:177], v[218:221], v[4:7]
	v_mfma_f32_16x16x32_bf16 v[0:3], v[186:189], v[218:221], v[0:3]
	s_barrier
	s_add_i32 s91, s91, 2
	s_add_u32 s36, s36, 0x100
	s_addc_u32 s37, s37, 0
	s_add_u32 s89, s89, 0x100
	s_addc_u32 s90, s90, 0
	s_cmp_gt_u32 s91, 13
	s_cbranch_scc0 .LBB0_188
	s_setprio 0
	s_and_b64 vcc, exec, s[22:23]
	s_cbranch_vccz .LBB0_191
	s_barrier

; #define PG8_STAGE(bufoff, gbase, voff) do { _Pragma("unroll") for (int _i = 0; _i < 2; ++_i) \
;         __builtin_amdgcn_global_load_lds((const unsigned*)((const char*)(gbase) + (voff)[_i]), (PG8_LAS unsigned*)(lds + (bufoff) + ldsw + _i * 8192), 16, 0, 0); } while (0)
; #define PG8_LDA(dst, b, h) do { _Pragma("unroll") for (int m = 0; m < 4; ++m) _Pragma("unroll") for (int k = 0; k < 2; ++k) dst[m][k] = *(const PG8_LAS bf16x8*)(lds + PG8_SA(b, h) + aoff + m * 2048 + k * 1024); } while (0)
; #define PG8_LDB(dst, b, h) do { _Pragma("unroll") for (int n = 0; n < 2; ++n) _Pragma("unroll") for (int k = 0; k < 2; ++k) dst[n][k] = *(const PG8_LAS bf16x8*)(lds + PG8_SB(b, h) + boff + n * 2048 + k * 1024); } while (0)
; #define PG8_MMA(ai, bj, At, Bt) do { __builtin_amdgcn_s_setprio(1); _Pragma("unroll") for (int m = 0; m < 4; ++m) _Pragma("unroll") for (int n = 0; n < 2; ++n) _Pragma("unroll") for (int k = 0; k < 2; ++k) \
;         acc[ai][bj][m][n] = __builtin_amdgcn_mfma_f32_16x16x32_bf16(Bt[n][k], At[m][k], acc[ai][bj][m][n], 0, 0, 0); __builtin_amdgcn_s_setprio(0); } while (0)
; #define PG8_WAIT_V(n) asm volatile("s_waitcnt vmcnt(" #n ")" ::: "memory")
; #define PG8_WAIT_L(n) asm volatile("s_waitcnt lgkmcnt(" #n ")" ::: "memory")
; #define PG8_BAR __builtin_amdgcn_s_barrier()
; #define PG8_SCHED __builtin_amdgcn_sched_barrier(0)
; template <class Epi, class Sched, bool ALIGN_EPI = false, bool SP2 = false>
; __device__ __forceinline__ void gemm_phase(PG8_LAS unsigned char* lds, const Gemm g, const Sched& S, const Epi& E) {
;     ...
;             PG8_LDB(B0, 0, 0); PG8_LDB(B1, 0, 1); PG8_SCHED; PG8_LDA(At, 0, 0); PG8_STAGE(PG8_SA(1, 1), a1 + hstep, voffA);
;             PG8_WAIT_V(8); PG8_WAIT_L(0); PG8_BAR; PG8_MMA(0, 0, At, B0); PG8_MMA(0, 1, At, B1); PG8_BAR; PG8_SCHED;
;     ...
; #pragma unroll
;         for (int a = 0; a < 2; ++a)
; #pragma unroll
;             for (int b = 0; b < 2; ++b)
; #pragma unroll
;                 for (int m = 0; m < 4; ++m)
; #pragma unroll
;                     for (int n = 0; n < 2; ++n) acc[a][b][m][n] = (f32x4){0.f, 0.f, 0.f, 0.f};
.LBB0_403:
	s_add_u32 s18, s18, 0x50080
	s_addc_u32 s19, s19, 0
	s_add_u32 s50, s20, 0x100
	v_mov_b32_e32 v0, 0
	s_addc_u32 s51, s21, 0
	s_mov_b32 s58, -2
	s_waitcnt lgkmcnt(0)
	v_mov_b32_e32 v1, v0
	v_mov_b32_e32 v2, v0
	v_mov_b32_e32 v3, v0
	v_mov_b32_e32 v4, v0
	v_mov_b32_e32 v5, v0
	v_mov_b32_e32 v6, v0
	v_mov_b32_e32 v7, v0
	v_mov_b32_e32 v16, v0
	v_mov_b32_e32 v17, v0
	v_mov_b32_e32 v18, v0
	v_mov_b32_e32 v19, v0
	v_mov_b32_e32 v20, v0
	v_mov_b32_e32 v21, v0
	v_mov_b32_e32 v22, v0
	v_mov_b32_e32 v23, v0
	v_mov_b32_e32 v32, v0
	v_mov_b32_e32 v33, v0
	v_mov_b32_e32 v34, v0
	v_mov_b32_e32 v35, v0
	v_mov_b32_e32 v36, v0
	v_mov_b32_e32 v37, v0
	v_mov_b32_e32 v38, v0
	v_mov_b32_e32 v39, v0
	v_mov_b32_e32 v48, v0
	v_mov_b32_e32 v49, v0
	v_mov_b32_e32 v50, v0
	v_mov_b32_e32 v51, v0
	v_mov_b32_e32 v52, v0
	v_mov_b32_e32 v53, v0
	v_mov_b32_e32 v54, v0
	v_mov_b32_e32 v55, v0
	v_mov_b32_e32 v8, v0
	v_mov_b32_e32 v9, v0
	v_mov_b32_e32 v10, v0
	v_mov_b32_e32 v11, v0
	v_mov_b32_e32 v12, v0
	v_mov_b32_e32 v13, v0
	v_mov_b32_e32 v14, v0
	v_mov_b32_e32 v15, v0
	v_mov_b32_e32 v24, v0
	v_mov_b32_e32 v25, v0
	v_mov_b32_e32 v26, v0
	v_mov_b32_e32 v27, v0
	v_mov_b32_e32 v28, v0
	v_mov_b32_e32 v29, v0
	v_mov_b32_e32 v30, v0
	v_mov_b32_e32 v31, v0
	v_mov_b32_e32 v40, v0
	v_mov_b32_e32 v41, v0
	v_mov_b32_e32 v42, v0
	v_mov_b32_e32 v43, v0
	v_mov_b32_e32 v44, v0
	v_mov_b32_e32 v45, v0
	v_mov_b32_e32 v46, v0
	v_mov_b32_e32 v47, v0
	v_mov_b32_e32 v56, v0
	v_mov_b32_e32 v57, v0
	v_mov_b32_e32 v58, v0
	v_mov_b32_e32 v59, v0
	v_mov_b32_e32 v60, v0
	v_mov_b32_e32 v61, v0
	v_mov_b32_e32 v62, v0
	v_mov_b32_e32 v63, v0
	v_mov_b32_e32 v64, v0
	v_mov_b32_e32 v65, v0
	v_mov_b32_e32 v66, v0
	v_mov_b32_e32 v67, v0
	v_mov_b32_e32 v68, v0
	v_mov_b32_e32 v69, v0
	v_mov_b32_e32 v70, v0
	v_mov_b32_e32 v71, v0
	v_mov_b32_e32 v80, v0
	v_mov_b32_e32 v81, v0
	v_mov_b32_e32 v82, v0
	v_mov_b32_e32 v83, v0
	v_mov_b32_e32 v84, v0
	v_mov_b32_e32 v85, v0
	v_mov_b32_e32 v86, v0
	v_mov_b32_e32 v87, v0
	v_mov_b32_e32 v96, v0
	v_mov_b32_e32 v97, v0
	v_mov_b32_e32 v98, v0
	v_mov_b32_e32 v99, v0
	v_mov_b32_e32 v104, v0
	v_mov_b32_e32 v105, v0
	v_mov_b32_e32 v106, v0
	v_mov_b32_e32 v107, v0
	v_mov_b32_e32 v124, v0
	v_mov_b32_e32 v125, v0
	v_mov_b32_e32 v126, v0
	v_mov_b32_e32 v127, v0
	v_mov_b32_e32 v128, v0
	v_mov_b32_e32 v129, v0
	v_mov_b32_e32 v130, v0
	v_mov_b32_e32 v131, v0
	v_mov_b32_e32 v72, v0
	v_mov_b32_e32 v73, v0
	v_mov_b32_e32 v74, v0
	v_mov_b32_e32 v75, v0
	v_mov_b32_e32 v76, v0
	v_mov_b32_e32 v77, v0
	v_mov_b32_e32 v78, v0
	v_mov_b32_e32 v79, v0
	v_mov_b32_e32 v88, v0
	v_mov_b32_e32 v89, v0
	v_mov_b32_e32 v90, v0
	v_mov_b32_e32 v91, v0
	v_mov_b32_e32 v92, v0
	v_mov_b32_e32 v93, v0
	v_mov_b32_e32 v94, v0
	v_mov_b32_e32 v95, v0
	v_mov_b32_e32 v112, v0
	v_mov_b32_e32 v113, v0
	v_mov_b32_e32 v114, v0
	v_mov_b32_e32 v115, v0
	v_mov_b32_e32 v116, v0
	v_mov_b32_e32 v117, v0
	v_mov_b32_e32 v118, v0
	v_mov_b32_e32 v119, v0
	v_mov_b32_e32 v136, v0
	v_mov_b32_e32 v137, v0
	v_mov_b32_e32 v138, v0
	v_mov_b32_e32 v139, v0
	v_mov_b32_e32 v140, v0
	v_mov_b32_e32 v141, v0
	v_mov_b32_e32 v142, v0
	v_mov_b32_e32 v143, v0
	s_bitcmp1_b32 s60, 2
	s_cbranch_scc0 .Lgprio_1
	s_setprio 1
.Lgprio_1:
.LBB0_404:
	ds_read_b128 v[100:103], v223
	ds_read_b128 v[108:111], v223 offset:1024
	ds_read_b128 v[120:123], v223 offset:2048
	ds_read_b128 v[132:135], v223 offset:3072
	ds_read_b128 v[144:147], v224
	ds_read_b128 v[148:151], v224 offset:1024
	ds_read_b128 v[152:155], v224 offset:2048
	ds_read_b128 v[156:159], v224 offset:3072
	s_add_u32 s20, s18, 0xfffb0080
	s_addc_u32 s21, s19, -1
	s_cmp_eq_u32 s58, 16
	s_cselect_b32 s23, s7, s21
	s_cselect_b32 s22, s6, s20
	s_cselect_b32 s21, s9, s51
	s_cselect_b32 s20, s8, s50
	v_lshl_add_u64 v[212:213], s[18:19], 0, v[196:197]
	s_add_i32 m0, s30, 0xc000
	ds_read_b128 v[160:163], v225
	ds_read_b128 v[164:167], v225 offset:1024
	ds_read_b128 v[168:171], v225 offset:2048
	ds_read_b128 v[172:175], v225 offset:3072
	ds_read_b128 v[176:179], v225 offset:4096
	ds_read_b128 v[180:183], v225 offset:5120
	ds_read_b128 v[204:207], v225 offset:6144
	ds_read_b128 v[208:211], v225 offset:7168
	global_load_lds_dwordx4 v[212:213], off
	v_lshl_add_u64 v[212:213], s[18:19], 0, v[198:199]
	s_add_i32 m0, s30, 0xe000
	s_nop 0
	global_load_lds_dwordx4 v[212:213], off
	s_waitcnt vmcnt(8)
	s_waitcnt lgkmcnt(0)
	s_barrier
	s_waitcnt lgkmcnt(0)
	v_mfma_f32_16x16x32_bf16 v[140:143], v[100:103], v[160:163], v[140:143]
	v_mfma_f32_16x16x32_bf16 v[136:139], v[120:123], v[160:163], v[136:139]
	v_mfma_f32_16x16x32_bf16 v[116:119], v[100:103], v[168:171], v[116:119]
	v_mfma_f32_16x16x32_bf16 v[112:115], v[120:123], v[168:171], v[112:115]
	v_mfma_f32_16x16x32_bf16 v[92:95], v[100:103], v[176:179], v[92:95]
	v_mfma_f32_16x16x32_bf16 v[88:91], v[120:123], v[176:179], v[88:91]
	v_mfma_f32_16x16x32_bf16 v[76:79], v[100:103], v[204:207], v[76:79]
	v_mfma_f32_16x16x32_bf16 v[72:75], v[120:123], v[204:207], v[72:75]
	v_mfma_f32_16x16x32_bf16 v[140:143], v[108:111], v[164:167], v[140:143]
	v_mfma_f32_16x16x32_bf16 v[136:139], v[132:135], v[164:167], v[136:139]
	v_mfma_f32_16x16x32_bf16 v[116:119], v[108:111], v[172:175], v[116:119]
	v_mfma_f32_16x16x32_bf16 v[112:115], v[132:135], v[172:175], v[112:115]
	v_mfma_f32_16x16x32_bf16 v[92:95], v[108:111], v[180:183], v[92:95]
	v_mfma_f32_16x16x32_bf16 v[88:91], v[132:135], v[180:183], v[88:91]
	v_mfma_f32_16x16x32_bf16 v[76:79], v[108:111], v[208:211], v[76:79]
	v_mfma_f32_16x16x32_bf16 v[72:75], v[132:135], v[208:211], v[72:75]
	v_mfma_f32_16x16x32_bf16 v[128:131], v[144:147], v[160:163], v[128:131]
	v_mfma_f32_16x16x32_bf16 v[124:127], v[152:155], v[160:163], v[124:127]
	v_mfma_f32_16x16x32_bf16 v[104:107], v[144:147], v[168:171], v[104:107]
	v_mfma_f32_16x16x32_bf16 v[96:99], v[152:155], v[168:171], v[96:99]
	v_mfma_f32_16x16x32_bf16 v[84:87], v[144:147], v[176:179], v[84:87]
	v_mfma_f32_16x16x32_bf16 v[80:83], v[152:155], v[176:179], v[80:83]
	v_mfma_f32_16x16x32_bf16 v[68:71], v[144:147], v[204:207], v[68:71]
	v_mfma_f32_16x16x32_bf16 v[64:67], v[152:155], v[204:207], v[64:67]
	v_mfma_f32_16x16x32_bf16 v[128:131], v[148:151], v[164:167], v[128:131]
	v_mfma_f32_16x16x32_bf16 v[124:127], v[156:159], v[164:167], v[124:127]
	v_mfma_f32_16x16x32_bf16 v[104:107], v[148:151], v[172:175], v[104:107]
	v_mfma_f32_16x16x32_bf16 v[96:99], v[156:159], v[172:175], v[96:99]
	v_mfma_f32_16x16x32_bf16 v[84:87], v[148:151], v[180:183], v[84:87]
	v_mfma_f32_16x16x32_bf16 v[80:83], v[156:159], v[180:183], v[80:83]
	v_mfma_f32_16x16x32_bf16 v[68:71], v[148:151], v[208:211], v[68:71]
	v_mfma_f32_16x16x32_bf16 v[64:67], v[156:159], v[208:211], v[64:67]
	s_barrier
; #define PG8_STAGE(bufoff, gbase, voff) do { _Pragma("unroll") for (int _i = 0; _i < 2; ++_i) \
;         __builtin_amdgcn_global_load_lds((const unsigned*)((const char*)(gbase) + (voff)[_i]), (PG8_LAS unsigned*)(lds + (bufoff) + ldsw + _i * 8192), 16, 0, 0); } while (0)
; #define PG8_LDA(dst, b, h) do { _Pragma("unroll") for (int m = 0; m < 4; ++m) _Pragma("unroll") for (int k = 0; k < 2; ++k) dst[m][k] = *(const PG8_LAS bf16x8*)(lds + PG8_SA(b, h) + aoff + m * 2048 + k * 1024); } while (0)
; #define PG8_LDB(dst, b, h) do { _Pragma("unroll") for (int n = 0; n < 2; ++n) _Pragma("unroll") for (int k = 0; k < 2; ++k) dst[n][k] = *(const PG8_LAS bf16x8*)(lds + PG8_SB(b, h) + boff + n * 2048 + k * 1024); } while (0)
; #define PG8_MMA(ai, bj, At, Bt) do { __builtin_amdgcn_s_setprio(1); _Pragma("unroll") for (int m = 0; m < 4; ++m) _Pragma("unroll") for (int n = 0; n < 2; ++n) _Pragma("unroll") for (int k = 0; k < 2; ++k) \
;         acc[ai][bj][m][n] = __builtin_amdgcn_mfma_f32_16x16x32_bf16(Bt[n][k], At[m][k], acc[ai][bj][m][n], 0, 0, 0); __builtin_amdgcn_s_setprio(0); } while (0)
; #define PG8_WAIT_V(n) asm volatile("s_waitcnt vmcnt(" #n ")" ::: "memory")
; #define PG8_WAIT_L(n) asm volatile("s_waitcnt lgkmcnt(" #n ")" ::: "memory")
; #define PG8_BAR __builtin_amdgcn_s_barrier()
; #define PG8_SCHED __builtin_amdgcn_sched_barrier(0)
; template <class Epi, class Sched, bool ALIGN_EPI = false, bool SP2 = false>
; __device__ __forceinline__ void gemm_phase(PG8_LAS unsigned char* lds, const Gemm g, const Sched& S, const Epi& E) {
;     ...
;             PG8_LDA(At, 0, 1); PG8_STAGE(PG8_SB(0, 0), b2, voffB); PG8_STAGE(PG8_SB(0, 1), b2 + hstep, voffB); PG8_STAGE(PG8_SA(0, 0), a2, voffA);
;             PG8_WAIT_V(8); PG8_WAIT_L(0); PG8_BAR; PG8_MMA(1, 0, At, B0); PG8_MMA(1, 1, At, B1); PG8_BAR; PG8_SCHED;
;             PG8_LDB(B0, 1, 0); PG8_LDB(B1, 1, 1); PG8_SCHED; PG8_LDA(At, 1, 0); PG8_STAGE(PG8_SA(0, 1), a2 + hstep, voffA);
	s_add_i32 s69, s44, s29
	v_lshl_add_u64 v[212:213], s[20:21], 0, v[190:191]
	s_mov_b32 m0, s69
	ds_read_b128 v[160:163], v225 offset:16384
	ds_read_b128 v[164:167], v225 offset:17408
	ds_read_b128 v[168:171], v225 offset:18432
	ds_read_b128 v[172:175], v225 offset:19456
	ds_read_b128 v[176:179], v225 offset:20480
	ds_read_b128 v[180:183], v225 offset:21504
	ds_read_b128 v[204:207], v225 offset:22528
	ds_read_b128 v[208:211], v225 offset:23552
	global_load_lds_dwordx4 v[212:213], off
	s_add_i32 m0, s69, 0x2000
	s_add_u32 s70, s20, 0x50000
	v_lshl_add_u64 v[214:215], s[20:21], 0, v[194:195]
	s_addc_u32 s71, s21, 0
	s_add_i32 s69, s45, s29
	global_load_lds_dwordx4 v[214:215], off
	v_lshl_add_u64 v[216:217], s[70:71], 0, v[190:191]
	s_mov_b32 m0, s69
	v_lshl_add_u64 v[218:219], s[22:23], 0, v[192:193]
	global_load_lds_dwordx4 v[216:217], off
	v_lshl_add_u64 v[216:217], s[70:71], 0, v[194:195]
	s_add_i32 m0, s69, 0x2000
	s_nop 0
	global_load_lds_dwordx4 v[216:217], off
	v_lshl_add_u64 v[216:217], s[22:23], 0, v[188:189]
	s_mov_b32 m0, s30
	s_nop 0
	global_load_lds_dwordx4 v[216:217], off
	s_mov_b32 m0, s31
	s_nop 0
	global_load_lds_dwordx4 v[218:219], off
	s_waitcnt vmcnt(8)
	s_waitcnt lgkmcnt(0)
	s_barrier
	s_waitcnt lgkmcnt(0)
	v_mfma_f32_16x16x32_bf16 v[60:63], v[100:103], v[160:163], v[60:63]
	v_mfma_f32_16x16x32_bf16 v[56:59], v[120:123], v[160:163], v[56:59]
	v_mfma_f32_16x16x32_bf16 v[44:47], v[100:103], v[168:171], v[44:47]
	v_mfma_f32_16x16x32_bf16 v[40:43], v[120:123], v[168:171], v[40:43]
	v_mfma_f32_16x16x32_bf16 v[28:31], v[100:103], v[176:179], v[28:31]
	v_mfma_f32_16x16x32_bf16 v[24:27], v[120:123], v[176:179], v[24:27]
	v_mfma_f32_16x16x32_bf16 v[12:15], v[100:103], v[204:207], v[12:15]
	v_mfma_f32_16x16x32_bf16 v[8:11], v[120:123], v[204:207], v[8:11]
	v_mfma_f32_16x16x32_bf16 v[60:63], v[108:111], v[164:167], v[60:63]
	v_mfma_f32_16x16x32_bf16 v[56:59], v[132:135], v[164:167], v[56:59]
	v_mfma_f32_16x16x32_bf16 v[44:47], v[108:111], v[172:175], v[44:47]
	v_mfma_f32_16x16x32_bf16 v[40:43], v[132:135], v[172:175], v[40:43]
	v_mfma_f32_16x16x32_bf16 v[28:31], v[108:111], v[180:183], v[28:31]
	v_mfma_f32_16x16x32_bf16 v[24:27], v[132:135], v[180:183], v[24:27]
	v_mfma_f32_16x16x32_bf16 v[12:15], v[108:111], v[208:211], v[12:15]
	v_mfma_f32_16x16x32_bf16 v[8:11], v[132:135], v[208:211], v[8:11]
	v_mfma_f32_16x16x32_bf16 v[52:55], v[144:147], v[160:163], v[52:55]
	v_mfma_f32_16x16x32_bf16 v[48:51], v[152:155], v[160:163], v[48:51]
	v_mfma_f32_16x16x32_bf16 v[36:39], v[144:147], v[168:171], v[36:39]
	v_mfma_f32_16x16x32_bf16 v[32:35], v[152:155], v[168:171], v[32:35]
	v_mfma_f32_16x16x32_bf16 v[20:23], v[144:147], v[176:179], v[20:23]
	v_mfma_f32_16x16x32_bf16 v[16:19], v[152:155], v[176:179], v[16:19]
	v_mfma_f32_16x16x32_bf16 v[4:7], v[144:147], v[204:207], v[4:7]
	v_mfma_f32_16x16x32_bf16 v[0:3], v[152:155], v[204:207], v[0:3]
	v_mfma_f32_16x16x32_bf16 v[52:55], v[148:151], v[164:167], v[52:55]
	v_mfma_f32_16x16x32_bf16 v[48:51], v[156:159], v[164:167], v[48:51]
	v_mfma_f32_16x16x32_bf16 v[36:39], v[148:151], v[172:175], v[36:39]
	v_mfma_f32_16x16x32_bf16 v[32:35], v[156:159], v[172:175], v[32:35]
	v_mfma_f32_16x16x32_bf16 v[20:23], v[148:151], v[180:183], v[20:23]
	v_mfma_f32_16x16x32_bf16 v[16:19], v[156:159], v[180:183], v[16:19]
	v_mfma_f32_16x16x32_bf16 v[4:7], v[148:151], v[208:211], v[4:7]
	v_mfma_f32_16x16x32_bf16 v[0:3], v[156:159], v[208:211], v[0:3]
	s_barrier
	s_add_i32 s69, 0, 0x18000
	s_add_i32 s70, 0, 0x1c000
	v_add_u32_e32 v132, s69, v187
	v_add_u32_e32 v156, s70, v187
	ds_read_b128 v[100:103], v132
	ds_read_b128 v[108:111], v132 offset:1024
	ds_read_b128 v[120:123], v132 offset:2048
	ds_read_b128 v[132:135], v132 offset:3072
	ds_read_b128 v[144:147], v156
	ds_read_b128 v[148:151], v156 offset:1024
	ds_read_b128 v[152:155], v156 offset:2048
	ds_read_b128 v[156:159], v156 offset:3072
	s_add_u32 s22, s22, 0x50000
	s_addc_u32 s23, s23, 0
	s_mov_b32 m0, s34
	v_lshl_add_u64 v[220:221], s[22:23], 0, v[188:189]
	ds_read_b128 v[160:163], v225 offset:32768
	ds_read_b128 v[164:167], v225 offset:33792
	ds_read_b128 v[168:171], v225 offset:34816
	ds_read_b128 v[172:175], v225 offset:35840
	ds_read_b128 v[176:179], v225 offset:36864
	ds_read_b128 v[180:183], v225 offset:37888
	ds_read_b128 v[204:207], v225 offset:38912
	ds_read_b128 v[208:211], v225 offset:39936
	global_load_lds_dwordx4 v[220:221], off
	v_lshl_add_u64 v[220:221], s[22:23], 0, v[192:193]
	s_mov_b32 m0, s35
	s_nop 0
	global_load_lds_dwordx4 v[220:221], off
	s_waitcnt vmcnt(8)
	s_waitcnt lgkmcnt(0)
	s_barrier
; #define PG8_STAGE(bufoff, gbase, voff) do { _Pragma("unroll") for (int _i = 0; _i < 2; ++_i) \
;         __builtin_amdgcn_global_load_lds((const unsigned*)((const char*)(gbase) + (voff)[_i]), (PG8_LAS unsigned*)(lds + (bufoff) + ldsw + _i * 8192), 16, 0, 0); } while (0)
; #define PG8_LDA(dst, b, h) do { _Pragma("unroll") for (int m = 0; m < 4; ++m) _Pragma("unroll") for (int k = 0; k < 2; ++k) dst[m][k] = *(const PG8_LAS bf16x8*)(lds + PG8_SA(b, h) + aoff + m * 2048 + k * 1024); } while (0)
; #define PG8_MMA(ai, bj, At, Bt) do { __builtin_amdgcn_s_setprio(1); _Pragma("unroll") for (int m = 0; m < 4; ++m) _Pragma("unroll") for (int n = 0; n < 2; ++n) _Pragma("unroll") for (int k = 0; k < 2; ++k) \
;         acc[ai][bj][m][n] = __builtin_amdgcn_mfma_f32_16x16x32_bf16(Bt[n][k], At[m][k], acc[ai][bj][m][n], 0, 0, 0); __builtin_amdgcn_s_setprio(0); } while (0)
; #define PG8_WAIT_V(n) asm volatile("s_waitcnt vmcnt(" #n ")" ::: "memory")
; #define PG8_WAIT_L(n) asm volatile("s_waitcnt lgkmcnt(" #n ")" ::: "memory")
; #define PG8_BAR __builtin_amdgcn_s_barrier()
; #define PG8_SCHED __builtin_amdgcn_sched_barrier(0)
; template <class Epi, class Sched, bool ALIGN_EPI = false, bool SP2 = false>
; __device__ __forceinline__ void gemm_phase(PG8_LAS unsigned char* lds, const Gemm g, const Sched& S, const Epi& E) {
;     ...
;             PG8_WAIT_V(8); PG8_WAIT_L(0); PG8_BAR; PG8_MMA(0, 0, At, B0); PG8_MMA(0, 1, At, B1); PG8_BAR; PG8_SCHED;
;             PG8_LDA(At, 1, 1); PG8_STAGE(PG8_SB(1, 0), b3, voffB); PG8_STAGE(PG8_SB(1, 1), b3 + hstep, voffB); PG8_STAGE(PG8_SA(1, 0), a3, voffA);
;             PG8_WAIT_V(8); PG8_WAIT_L(0); PG8_BAR; PG8_MMA(1, 0, At, B0); PG8_MMA(1, 1, At, B1); PG8_BAR; PG8_SCHED;
	s_waitcnt lgkmcnt(0)
	v_mfma_f32_16x16x32_bf16 v[140:143], v[100:103], v[160:163], v[140:143]
	v_mfma_f32_16x16x32_bf16 v[136:139], v[120:123], v[160:163], v[136:139]
	v_mfma_f32_16x16x32_bf16 v[116:119], v[100:103], v[168:171], v[116:119]
	v_mfma_f32_16x16x32_bf16 v[112:115], v[120:123], v[168:171], v[112:115]
	v_mfma_f32_16x16x32_bf16 v[92:95], v[100:103], v[176:179], v[92:95]
	v_mfma_f32_16x16x32_bf16 v[88:91], v[120:123], v[176:179], v[88:91]
	v_mfma_f32_16x16x32_bf16 v[76:79], v[100:103], v[204:207], v[76:79]
	v_mfma_f32_16x16x32_bf16 v[72:75], v[120:123], v[204:207], v[72:75]
	v_mfma_f32_16x16x32_bf16 v[140:143], v[108:111], v[164:167], v[140:143]
	v_mfma_f32_16x16x32_bf16 v[136:139], v[132:135], v[164:167], v[136:139]
	v_mfma_f32_16x16x32_bf16 v[116:119], v[108:111], v[172:175], v[116:119]
	v_mfma_f32_16x16x32_bf16 v[112:115], v[132:135], v[172:175], v[112:115]
	v_mfma_f32_16x16x32_bf16 v[92:95], v[108:111], v[180:183], v[92:95]
	v_mfma_f32_16x16x32_bf16 v[88:91], v[132:135], v[180:183], v[88:91]
	v_mfma_f32_16x16x32_bf16 v[76:79], v[108:111], v[208:211], v[76:79]
	v_mfma_f32_16x16x32_bf16 v[72:75], v[132:135], v[208:211], v[72:75]
	v_mfma_f32_16x16x32_bf16 v[128:131], v[144:147], v[160:163], v[128:131]
	v_mfma_f32_16x16x32_bf16 v[124:127], v[152:155], v[160:163], v[124:127]
	v_mfma_f32_16x16x32_bf16 v[104:107], v[144:147], v[168:171], v[104:107]
	v_mfma_f32_16x16x32_bf16 v[96:99], v[152:155], v[168:171], v[96:99]
	v_mfma_f32_16x16x32_bf16 v[84:87], v[144:147], v[176:179], v[84:87]
	v_mfma_f32_16x16x32_bf16 v[80:83], v[152:155], v[176:179], v[80:83]
	v_mfma_f32_16x16x32_bf16 v[68:71], v[144:147], v[204:207], v[68:71]
	v_mfma_f32_16x16x32_bf16 v[64:67], v[152:155], v[204:207], v[64:67]
	v_mfma_f32_16x16x32_bf16 v[128:131], v[148:151], v[164:167], v[128:131]
	v_mfma_f32_16x16x32_bf16 v[124:127], v[156:159], v[164:167], v[124:127]
	v_mfma_f32_16x16x32_bf16 v[104:107], v[148:151], v[172:175], v[104:107]
	v_mfma_f32_16x16x32_bf16 v[96:99], v[156:159], v[172:175], v[96:99]
	v_mfma_f32_16x16x32_bf16 v[84:87], v[148:151], v[180:183], v[84:87]
	v_mfma_f32_16x16x32_bf16 v[80:83], v[156:159], v[180:183], v[80:83]
	v_mfma_f32_16x16x32_bf16 v[68:71], v[148:151], v[208:211], v[68:71]
	v_mfma_f32_16x16x32_bf16 v[64:67], v[156:159], v[208:211], v[64:67]
	s_barrier
	s_add_i32 s22, s69, s29
	v_lshl_add_u64 v[212:213], v[212:213], 0, s[16:17]
	s_mov_b32 m0, s22
	ds_read_b128 v[160:163], v225 offset:49152
	ds_read_b128 v[164:167], v225 offset:50176
	ds_read_b128 v[168:171], v225 offset:51200
	ds_read_b128 v[172:175], v225 offset:52224
	ds_read_b128 v[176:179], v225 offset:53248
	ds_read_b128 v[180:183], v225 offset:54272
	ds_read_b128 v[204:207], v225 offset:55296
	ds_read_b128 v[208:211], v225 offset:56320
	global_load_lds_dwordx4 v[212:213], off
	s_add_i32 m0, s22, 0x2000
	s_add_u32 s20, s20, 0x50080
	v_lshl_add_u64 v[212:213], v[214:215], 0, s[16:17]
	s_addc_u32 s21, s21, 0
	s_add_i32 s22, s70, s29
	global_load_lds_dwordx4 v[212:213], off
	v_lshl_add_u64 v[212:213], s[20:21], 0, v[190:191]
	s_mov_b32 m0, s22
	s_nop 0
	global_load_lds_dwordx4 v[212:213], off
	v_lshl_add_u64 v[212:213], s[20:21], 0, v[194:195]
	s_add_i32 m0, s22, 0x2000
	s_nop 0
	global_load_lds_dwordx4 v[212:213], off
	v_lshl_add_u64 v[212:213], v[216:217], 0, s[16:17]
	s_mov_b32 m0, s37
	s_nop 0
	global_load_lds_dwordx4 v[212:213], off
	v_lshl_add_u64 v[212:213], v[218:219], 0, s[16:17]
	s_mov_b32 m0, s38
	s_nop 0
	global_load_lds_dwordx4 v[212:213], off
	s_waitcnt vmcnt(8)
	s_waitcnt lgkmcnt(0)
	s_barrier
	s_waitcnt lgkmcnt(0)
	v_mfma_f32_16x16x32_bf16 v[60:63], v[100:103], v[160:163], v[60:63]
	v_mfma_f32_16x16x32_bf16 v[56:59], v[120:123], v[160:163], v[56:59]
	v_mfma_f32_16x16x32_bf16 v[44:47], v[100:103], v[168:171], v[44:47]
	v_mfma_f32_16x16x32_bf16 v[40:43], v[120:123], v[168:171], v[40:43]
	v_mfma_f32_16x16x32_bf16 v[28:31], v[100:103], v[176:179], v[28:31]
	v_mfma_f32_16x16x32_bf16 v[24:27], v[120:123], v[176:179], v[24:27]
	v_mfma_f32_16x16x32_bf16 v[12:15], v[100:103], v[204:207], v[12:15]
	v_mfma_f32_16x16x32_bf16 v[8:11], v[120:123], v[204:207], v[8:11]
	v_mfma_f32_16x16x32_bf16 v[60:63], v[108:111], v[164:167], v[60:63]
	v_mfma_f32_16x16x32_bf16 v[56:59], v[132:135], v[164:167], v[56:59]
	v_mfma_f32_16x16x32_bf16 v[44:47], v[108:111], v[172:175], v[44:47]
	v_mfma_f32_16x16x32_bf16 v[40:43], v[132:135], v[172:175], v[40:43]
	v_mfma_f32_16x16x32_bf16 v[28:31], v[108:111], v[180:183], v[28:31]
	v_mfma_f32_16x16x32_bf16 v[24:27], v[132:135], v[180:183], v[24:27]
	v_mfma_f32_16x16x32_bf16 v[12:15], v[108:111], v[208:211], v[12:15]
	v_mfma_f32_16x16x32_bf16 v[8:11], v[132:135], v[208:211], v[8:11]
	v_mfma_f32_16x16x32_bf16 v[52:55], v[144:147], v[160:163], v[52:55]
	v_mfma_f32_16x16x32_bf16 v[48:51], v[152:155], v[160:163], v[48:51]
	v_mfma_f32_16x16x32_bf16 v[36:39], v[144:147], v[168:171], v[36:39]
	v_mfma_f32_16x16x32_bf16 v[32:35], v[152:155], v[168:171], v[32:35]
	v_mfma_f32_16x16x32_bf16 v[20:23], v[144:147], v[176:179], v[20:23]
	v_mfma_f32_16x16x32_bf16 v[16:19], v[152:155], v[176:179], v[16:19]
	v_mfma_f32_16x16x32_bf16 v[4:7], v[144:147], v[204:207], v[4:7]
	v_mfma_f32_16x16x32_bf16 v[0:3], v[152:155], v[204:207], v[0:3]
	v_mfma_f32_16x16x32_bf16 v[52:55], v[148:151], v[164:167], v[52:55]
	v_mfma_f32_16x16x32_bf16 v[48:51], v[156:159], v[164:167], v[48:51]
	v_mfma_f32_16x16x32_bf16 v[36:39], v[148:151], v[172:175], v[36:39]
	v_mfma_f32_16x16x32_bf16 v[32:35], v[156:159], v[172:175], v[32:35]
	v_mfma_f32_16x16x32_bf16 v[20:23], v[148:151], v[180:183], v[20:23]
	v_mfma_f32_16x16x32_bf16 v[16:19], v[156:159], v[180:183], v[16:19]
	v_mfma_f32_16x16x32_bf16 v[4:7], v[148:151], v[208:211], v[4:7]
	v_mfma_f32_16x16x32_bf16 v[0:3], v[156:159], v[208:211], v[0:3]
	s_barrier
; __device__ __forceinline__ unsigned cvt_pk_bf16(float lo, float hi) { unsigned r; asm volatile("v_cvt_pk_bf16_f32 %0, %1, %2" : "=v"(r) : "v"(lo), "v"(hi)); return r; }
;     __device__ __forceinline__ void operator()(const f32x4 (&acc)[2][2][4][2], const Unit& u, int wr, int wc, int fr, int fq) const {
;         const int row0 = u.pm * BM + wr * 64 + fr, col0 = u.pn * BM + wc * 32 + 8 * fq;
;         u32x4 rb[2][4][2];
; #pragma unroll
;         for (int ai = 0; ai < 2; ++ai)
; #pragma unroll
;             for (int m = 0; m < 4; ++m)
; #pragma unroll
;                 for (int bj = 0; bj < 2; ++bj) rb[ai][m][bj] = *(const u32x4*)(base + (size_t)(row0 + ai * HALF + m * 16) * ldc + col0 + bj * HALF);
;         asm volatile("" ::: "memory");
; #pragma unroll
;         for (int ai = 0; ai < 2; ++ai)
; #pragma unroll
;             for (int m = 0; m < 4; ++m) { const int row = row0 + ai * HALF + m * 16; float s = 0.f;
; #pragma unroll
;                 for (int bj = 0; bj < 2; ++bj) { const u32x4 w = rb[ai][m][bj];
;                     const f32x4 v0 = acc[ai][bj][m][0] + (f32x4){__uint_as_float(w.x << 16), __uint_as_float(w.x & 0xffff0000u), __uint_as_float(w.y << 16), __uint_as_float(w.y & 0xffff0000u)};
;                     const f32x4 v1 = acc[ai][bj][m][1] + (f32x4){__uint_as_float(w.z << 16), __uint_as_float(w.z & 0xffff0000u), __uint_as_float(w.w << 16), __uint_as_float(w.w & 0xffff0000u)};
;                     s += ((v0[0] * v0[0] + v0[1] * v0[1]) + (v0[2] * v0[2] + v0[3] * v0[3])) + ((v1[0] * v1[0] + v1[1] * v1[1]) + (v1[2] * v1[2] + v1[3] * v1[3]));
;                     u32x4 o; o.x = cvt_pk_bf16(v0[0], v0[1]); o.y = cvt_pk_bf16(v0[2], v0[3]); o.z = cvt_pk_bf16(v1[0], v1[1]); o.w = cvt_pk_bf16(v1[2], v1[3]);
;                     *(u32x4*)(outb + (size_t)row * ldc + col0 + bj * HALF) = o; }
;                 s += __shfl_xor(s, 16); s += __shfl_xor(s, 32);
;                 if (fq == 0) atomicAdd(ssq + row, s); }
	s_add_i32 s58, s58, 2
	s_add_u32 s18, s18, 0x100
	s_addc_u32 s19, s19, 0
	s_add_u32 s50, s50, 0x100
	s_addc_u32 s51, s51, 0
	s_cmp_gt_u32 s58, 17
	s_cbranch_scc0 .LBB0_404
	s_setprio 0
	v_lshl_or_b32 v204, s48, 8, v222
	v_lshl_add_u32 v220, s49, 8, v185
	v_ashrrev_i32_e32 v205, 31, v204
	v_lshlrev_b64 v[238:239], 1, v[204:205]
	v_ashrrev_i32_e32 v221, 31, v220
	v_lshl_add_u64 v[100:101], s[12:13], 0, v[238:239]
	v_lshlrev_b64 v[240:241], 11, v[220:221]
	v_lshl_add_u64 v[102:103], v[100:101], 0, v[240:241]
	global_load_dwordx4 v[228:231], v[102:103], off
	global_load_dwordx4 v[234:237], v[102:103], off offset:256
	v_or_b32_e32 v218, 16, v220
	v_or_b32_e32 v216, 32, v220
	v_or_b32_e32 v214, 48, v220
	v_add_u32_e32 v212, 0x80, v220
	v_add_u32_e32 v210, 0x90, v220
	v_add_u32_e32 v208, 0xa0, v220
	v_add_u32_e32 v206, 0xb0, v220
	v_ashrrev_i32_e32 v219, 31, v218
	v_ashrrev_i32_e32 v217, 31, v216
	v_ashrrev_i32_e32 v215, 31, v214
	v_ashrrev_i32_e32 v213, 31, v212
	v_ashrrev_i32_e32 v211, 31, v210
	v_ashrrev_i32_e32 v209, 31, v208
	v_ashrrev_i32_e32 v207, 31, v206
	v_lshlrev_b64 v[102:103], 11, v[218:219]
	v_lshlrev_b64 v[108:109], 11, v[216:217]
	v_lshlrev_b64 v[110:111], 11, v[214:215]
	v_lshlrev_b64 v[120:121], 11, v[212:213]
	v_lshlrev_b64 v[122:123], 11, v[210:211]
	v_lshlrev_b64 v[132:133], 11, v[208:209]
	v_lshlrev_b64 v[134:135], 11, v[206:207]
	v_lshl_add_u64 v[102:103], v[100:101], 0, v[102:103]
	v_lshl_add_u64 v[108:109], v[100:101], 0, v[108:109]
	v_lshl_add_u64 v[110:111], v[100:101], 0, v[110:111]
	v_lshl_add_u64 v[120:121], v[100:101], 0, v[120:121]
	v_lshl_add_u64 v[122:123], v[100:101], 0, v[122:123]
	v_lshl_add_u64 v[242:243], v[100:101], 0, v[132:133]
	v_lshl_add_u64 v[100:101], v[100:101], 0, v[134:135]
	global_load_dwordx4 v[180:183], v[102:103], off
	global_load_dwordx4 v[176:179], v[102:103], off offset:256
	global_load_dwordx4 v[172:175], v[108:109], off
	global_load_dwordx4 v[168:171], v[108:109], off offset:256
	global_load_dwordx4 v[164:167], v[110:111], off
	global_load_dwordx4 v[160:163], v[110:111], off offset:256
	global_load_dwordx4 v[156:159], v[120:121], off
	global_load_dwordx4 v[152:155], v[120:121], off offset:256
	global_load_dwordx4 v[148:151], v[122:123], off
	global_load_dwordx4 v[144:147], v[122:123], off offset:256
	global_load_dwordx4 v[132:135], v[242:243], off
	s_nop 0
	global_load_dwordx4 v[120:123], v[242:243], off offset:256
	global_load_dwordx4 v[108:111], v[100:101], off
	s_nop 0
	global_load_dwordx4 v[100:103], v[100:101], off offset:256
	s_waitcnt vmcnt(0)
	v_lshlrev_b32_e32 v242, 16, v228
	v_and_b32_e32 v243, 0xffff0000, v228
	v_lshlrev_b32_e32 v228, 16, v229
	v_and_b32_e32 v229, 0xffff0000, v229
	v_lshlrev_b32_e32 v244, 16, v230
	v_and_b32_e32 v245, 0xffff0000, v230
	v_lshlrev_b32_e32 v230, 16, v231
	v_and_b32_e32 v231, 0xffff0000, v231
	v_lshlrev_b32_e32 v246, 16, v234
	v_and_b32_e32 v247, 0xffff0000, v234
	v_lshlrev_b32_e32 v234, 16, v235
	v_and_b32_e32 v235, 0xffff0000, v235
	v_pk_add_f32 v[142:143], v[142:143], v[228:229]
	v_pk_add_f32 v[140:141], v[140:141], v[242:243]
	v_pk_add_f32 v[138:139], v[138:139], v[230:231]
	v_pk_add_f32 v[136:137], v[136:137], v[244:245]
	v_pk_add_f32 v[130:131], v[130:131], v[234:235]
	v_mul_f32_e32 v227, v141, v141
	v_mul_f32_e32 v233, v143, v143
	v_mul_f32_e32 v234, v137, v137
	v_mul_f32_e32 v235, v139, v139
	v_lshlrev_b32_e32 v248, 16, v236
	v_and_b32_e32 v249, 0xffff0000, v236
	v_lshlrev_b32_e32 v236, 16, v237
	v_and_b32_e32 v237, 0xffff0000, v237
	v_fmac_f32_e32 v227, v140, v140
	v_fmac_f32_e32 v233, v142, v142
	v_fmac_f32_e32 v234, v136, v136
	v_fmac_f32_e32 v235, v138, v138
	v_pk_add_f32 v[228:229], v[128:129], v[246:247]
	v_pk_add_f32 v[230:231], v[126:127], v[236:237]
	v_cvt_pk_bf16_f32 v126, v140, v141
	v_cvt_pk_bf16_f32 v127, v142, v143
	v_cvt_pk_bf16_f32 v128, v136, v137
	v_add_f32_e32 v136, v227, v233
	v_add_f32_e32 v137, v234, v235
	v_cvt_pk_bf16_f32 v129, v138, v139
	v_add_f32_e32 v138, v136, v137
	v_pk_add_f32 v[136:137], v[124:125], v[248:249]
	v_mul_f32_e32 v124, v229, v229
	v_mul_f32_e32 v125, v131, v131
	v_fmac_f32_e32 v124, v228, v228
	v_fmac_f32_e32 v125, v130, v130
	v_add_f32_e32 v124, v124, v125
	v_mul_f32_e32 v125, v137, v137
	v_mul_f32_e32 v139, v231, v231
	v_fmac_f32_e32 v125, v136, v136
	v_fmac_f32_e32 v139, v230, v230
	v_add_f32_e32 v125, v125, v139
	v_add_f32_e32 v124, v124, v125
	v_add_f32_e32 v125, v138, v124
	v_and_b32_e32 v138, 64, v226
	v_xor_b32_e32 v124, 16, v226
	v_add_u32_e32 v140, 64, v138
	v_cmp_lt_i32_e32 vcc, v124, v140
	v_lshl_add_u64 v[138:139], s[12:13], 0, v[240:241]
	v_lshl_add_u64 v[138:139], v[138:139], 0, v[238:239]
	v_cndmask_b32_e32 v124, v226, v124, vcc
	v_lshlrev_b32_e32 v124, 2, v124
	ds_bpermute_b32 v141, v124, v125
	global_store_dwordx4 v[138:139], v[126:129], off
	s_nop 1
	v_cvt_pk_bf16_f32 v128, v228, v229
	s_waitcnt lgkmcnt(0)
	v_add_f32_e32 v126, v125, v141
	v_xor_b32_e32 v125, 32, v226
	v_cmp_lt_i32_e32 vcc, v125, v140
	v_cvt_pk_bf16_f32 v129, v130, v131
	v_cvt_pk_bf16_f32 v130, v136, v137
	v_cvt_pk_bf16_f32 v131, v230, v231
	global_store_dwordx4 v[138:139], v[128:131], off offset:256
	s_nop 0
	v_cndmask_b32_e32 v125, v226, v125, vcc
	v_lshlrev_b32_e32 v125, 2, v125
	ds_bpermute_b32 v127, v125, v126
	s_and_saveexec_b64 s[18:19], s[2:3]
	s_cbranch_execz .LBB0_407
	v_lshl_add_u64 v[128:129], v[220:221], 2, s[14:15]
	s_waitcnt lgkmcnt(0)
	v_add_f32_e32 v126, v126, v127
	global_atomic_add_f32 v[128:129], v126, off

; #define PG8_STAGE(bufoff, gbase, voff) do { _Pragma("unroll") for (int _i = 0; _i < 2; ++_i) \
;         __builtin_amdgcn_global_load_lds((const unsigned*)((const char*)(gbase) + (voff)[_i]), (PG8_LAS unsigned*)(lds + (bufoff) + ldsw + _i * 8192), 16, 0, 0); } while (0)
; #define PG8_LDA(dst, b, h) do { _Pragma("unroll") for (int m = 0; m < 4; ++m) _Pragma("unroll") for (int k = 0; k < 2; ++k) dst[m][k] = *(const PG8_LAS bf16x8*)(lds + PG8_SA(b, h) + aoff + m * 2048 + k * 1024); } while (0)
; #define PG8_LDB(dst, b, h) do { _Pragma("unroll") for (int n = 0; n < 2; ++n) _Pragma("unroll") for (int k = 0; k < 2; ++k) dst[n][k] = *(const PG8_LAS bf16x8*)(lds + PG8_SB(b, h) + boff + n * 2048 + k * 1024); } while (0)
; #define PG8_MMA(ai, bj, At, Bt) do { __builtin_amdgcn_s_setprio(1); _Pragma("unroll") for (int m = 0; m < 4; ++m) _Pragma("unroll") for (int n = 0; n < 2; ++n) _Pragma("unroll") for (int k = 0; k < 2; ++k) \
;         acc[ai][bj][m][n] = __builtin_amdgcn_mfma_f32_16x16x32_bf16(Bt[n][k], At[m][k], acc[ai][bj][m][n], 0, 0, 0); __builtin_amdgcn_s_setprio(0); } while (0)
; #define PG8_WAIT_V(n) asm volatile("s_waitcnt vmcnt(" #n ")" ::: "memory")
; #define PG8_WAIT_L(n) asm volatile("s_waitcnt lgkmcnt(" #n ")" ::: "memory")
; #define PG8_BAR __builtin_amdgcn_s_barrier()
; #define PG8_SCHED __builtin_amdgcn_sched_barrier(0)
; template <class Epi, class Sched, bool ALIGN_EPI = false, bool SP2 = false>
; __device__ __forceinline__ void gemm_phase(PG8_LAS unsigned char* lds, const Gemm g, const Sched& S, const Epi& E) {
;     ...
;             PG8_LDB(B0, 0, 0); PG8_LDB(B1, 0, 1); PG8_SCHED; PG8_LDA(At, 0, 0); PG8_STAGE(PG8_SA(1, 1), a1 + hstep, voffA);
;             PG8_WAIT_V(8); PG8_WAIT_L(0); PG8_BAR; PG8_MMA(0, 0, At, B0); PG8_MMA(0, 1, At, B1); PG8_BAR; PG8_SCHED;
;     ...
; #pragma unroll
;         for (int a = 0; a < 2; ++a)
; #pragma unroll
;             for (int b = 0; b < 2; ++b)
; #pragma unroll
;                 for (int m = 0; m < 4; ++m)
; #pragma unroll
;                     for (int n = 0; n < 2; ++n) acc[a][b][m][n] = (f32x4){0.f, 0.f, 0.f, 0.f};
.LBB0_489:
	s_ashr_i32 s19, s18, 31
	s_lshl_b64 s[20:21], s[18:19], 19
	s_add_u32 s20, s34, s20
	s_addc_u32 s21, s35, s21
	s_and_b64 s[22:23], s[2:3], exec
	s_cselect_b32 s5, s21, s27
	s_cselect_b32 s19, s20, s26
	s_ashr_i32 s17, s16, 31
	s_lshl_b64 s[22:23], s[16:17], 19
	s_add_u32 s22, s36, s22
	s_addc_u32 s23, s37, s23
	s_and_b64 s[30:31], s[2:3], exec
	s_cselect_b32 s17, s23, s29
	s_cselect_b32 s25, s22, s28
	s_add_u32 s26, s26, 0x40080
	s_addc_u32 s27, s27, 0
	s_add_u32 s76, s28, 0x100
	v_mov_b32_e32 v0, 0
	s_addc_u32 s77, s29, 0
	s_mov_b32 s78, -2
	v_mov_b32_e32 v1, v0
	v_mov_b32_e32 v2, v0
	v_mov_b32_e32 v3, v0
	v_mov_b32_e32 v4, v0
	v_mov_b32_e32 v5, v0
	v_mov_b32_e32 v6, v0
	v_mov_b32_e32 v7, v0
	v_mov_b32_e32 v16, v0
	v_mov_b32_e32 v17, v0
	v_mov_b32_e32 v18, v0
	v_mov_b32_e32 v19, v0
	v_mov_b32_e32 v20, v0
	v_mov_b32_e32 v21, v0
	v_mov_b32_e32 v22, v0
	v_mov_b32_e32 v23, v0
	v_mov_b32_e32 v32, v0
	v_mov_b32_e32 v33, v0
	v_mov_b32_e32 v34, v0
	v_mov_b32_e32 v35, v0
	v_mov_b32_e32 v36, v0
	v_mov_b32_e32 v37, v0
	v_mov_b32_e32 v38, v0
	v_mov_b32_e32 v39, v0
	v_mov_b32_e32 v48, v0
	v_mov_b32_e32 v49, v0
	v_mov_b32_e32 v50, v0
	v_mov_b32_e32 v51, v0
	v_mov_b32_e32 v52, v0
	v_mov_b32_e32 v53, v0
	v_mov_b32_e32 v54, v0
	v_mov_b32_e32 v55, v0
	v_mov_b32_e32 v8, v0
	v_mov_b32_e32 v9, v0
	v_mov_b32_e32 v10, v0
	v_mov_b32_e32 v11, v0
	v_mov_b32_e32 v12, v0
	v_mov_b32_e32 v13, v0
	v_mov_b32_e32 v14, v0
	v_mov_b32_e32 v15, v0
	v_mov_b32_e32 v24, v0
	v_mov_b32_e32 v25, v0
	v_mov_b32_e32 v26, v0
	v_mov_b32_e32 v27, v0
	v_mov_b32_e32 v28, v0
	v_mov_b32_e32 v29, v0
	v_mov_b32_e32 v30, v0
	v_mov_b32_e32 v31, v0
	v_mov_b32_e32 v40, v0
	v_mov_b32_e32 v41, v0
	v_mov_b32_e32 v42, v0
	v_mov_b32_e32 v43, v0
	v_mov_b32_e32 v44, v0
	v_mov_b32_e32 v45, v0
	v_mov_b32_e32 v46, v0
	v_mov_b32_e32 v47, v0
	v_mov_b32_e32 v56, v0
	v_mov_b32_e32 v57, v0
	v_mov_b32_e32 v58, v0
	v_mov_b32_e32 v59, v0
	v_mov_b32_e32 v60, v0
	v_mov_b32_e32 v61, v0
	v_mov_b32_e32 v62, v0
	v_mov_b32_e32 v63, v0
	v_mov_b32_e32 v64, v0
	v_mov_b32_e32 v65, v0
	v_mov_b32_e32 v66, v0
	v_mov_b32_e32 v67, v0
	v_mov_b32_e32 v68, v0
	v_mov_b32_e32 v69, v0
	v_mov_b32_e32 v70, v0
	v_mov_b32_e32 v71, v0
	v_mov_b32_e32 v80, v0
	v_mov_b32_e32 v81, v0
	v_mov_b32_e32 v82, v0
	v_mov_b32_e32 v83, v0
	v_mov_b32_e32 v84, v0
	v_mov_b32_e32 v85, v0
	v_mov_b32_e32 v86, v0
	v_mov_b32_e32 v87, v0
	v_mov_b32_e32 v96, v0
	v_mov_b32_e32 v97, v0
	v_mov_b32_e32 v98, v0
	v_mov_b32_e32 v99, v0
	v_mov_b32_e32 v100, v0
	v_mov_b32_e32 v101, v0
	v_mov_b32_e32 v102, v0
	v_mov_b32_e32 v103, v0
	v_mov_b32_e32 v112, v0
	v_mov_b32_e32 v113, v0
	v_mov_b32_e32 v114, v0
	v_mov_b32_e32 v115, v0
	v_mov_b32_e32 v116, v0
	v_mov_b32_e32 v117, v0
	v_mov_b32_e32 v118, v0
	v_mov_b32_e32 v119, v0
	v_mov_b32_e32 v72, v0
	v_mov_b32_e32 v73, v0
	v_mov_b32_e32 v74, v0
	v_mov_b32_e32 v75, v0
	v_mov_b32_e32 v76, v0
	v_mov_b32_e32 v77, v0
	v_mov_b32_e32 v78, v0
	v_mov_b32_e32 v79, v0
	v_mov_b32_e32 v88, v0
	v_mov_b32_e32 v89, v0
	v_mov_b32_e32 v90, v0
	v_mov_b32_e32 v91, v0
	v_mov_b32_e32 v92, v0
	v_mov_b32_e32 v93, v0
	v_mov_b32_e32 v94, v0
	v_mov_b32_e32 v95, v0
	v_mov_b32_e32 v104, v0
	v_mov_b32_e32 v105, v0
	v_mov_b32_e32 v106, v0
	v_mov_b32_e32 v107, v0
	v_mov_b32_e32 v108, v0
	v_mov_b32_e32 v109, v0
	v_mov_b32_e32 v110, v0
	v_mov_b32_e32 v111, v0
	v_mov_b32_e32 v120, v0
	v_mov_b32_e32 v121, v0
	v_mov_b32_e32 v122, v0
	v_mov_b32_e32 v123, v0
	v_mov_b32_e32 v124, v0
	v_mov_b32_e32 v125, v0
	v_mov_b32_e32 v126, v0
	v_mov_b32_e32 v127, v0
	s_bitcmp1_b32 s60, 2
	s_cbranch_scc0 .Lgprio_2
	s_setprio 1
.Lgprio_2:
.LBB0_490:
	ds_read_b128 v[144:147], v161
	ds_read_b128 v[168:171], v161 offset:1024
	ds_read_b128 v[172:175], v161 offset:2048
	ds_read_b128 v[176:179], v161 offset:3072
	ds_read_b128 v[180:183], v163
	ds_read_b128 v[188:191], v163 offset:1024
	ds_read_b128 v[192:195], v163 offset:2048
	ds_read_b128 v[196:199], v163 offset:3072
	s_add_u32 s28, s26, 0xfffc0080
	s_addc_u32 s29, s27, -1
	s_cmp_eq_u32 s78, 12
	s_cselect_b32 s31, s5, s29
	s_cselect_b32 s30, s19, s28
	s_cselect_b32 s29, s17, s77
	s_cselect_b32 s28, s25, s76
	v_lshl_add_u64 v[148:149], s[26:27], 0, v[136:137]
	s_add_i32 m0, s39, 0xc000
	ds_read_b128 v[200:203], v164
	ds_read_b128 v[204:207], v164 offset:1024
	ds_read_b128 v[208:211], v164 offset:2048
	ds_read_b128 v[212:215], v164 offset:3072
	ds_read_b128 v[216:219], v164 offset:4096
	ds_read_b128 v[220:223], v164 offset:5120
	ds_read_b128 v[224:227], v164 offset:6144
	ds_read_b128 v[228:231], v164 offset:7168
	global_load_lds_dwordx4 v[148:149], off
	v_lshl_add_u64 v[148:149], s[26:27], 0, v[138:139]
	s_add_i32 m0, s39, 0xe000
	s_nop 0
	global_load_lds_dwordx4 v[148:149], off
	s_waitcnt vmcnt(8)
	s_waitcnt lgkmcnt(0)
	s_barrier
; #define PG8_STAGE(bufoff, gbase, voff) do { _Pragma("unroll") for (int _i = 0; _i < 2; ++_i) \
;         __builtin_amdgcn_global_load_lds((const unsigned*)((const char*)(gbase) + (voff)[_i]), (PG8_LAS unsigned*)(lds + (bufoff) + ldsw + _i * 8192), 16, 0, 0); } while (0)
; #define PG8_LDA(dst, b, h) do { _Pragma("unroll") for (int m = 0; m < 4; ++m) _Pragma("unroll") for (int k = 0; k < 2; ++k) dst[m][k] = *(const PG8_LAS bf16x8*)(lds + PG8_SA(b, h) + aoff + m * 2048 + k * 1024); } while (0)
; #define PG8_MMA(ai, bj, At, Bt) do { __builtin_amdgcn_s_setprio(1); _Pragma("unroll") for (int m = 0; m < 4; ++m) _Pragma("unroll") for (int n = 0; n < 2; ++n) _Pragma("unroll") for (int k = 0; k < 2; ++k) \
;         acc[ai][bj][m][n] = __builtin_amdgcn_mfma_f32_16x16x32_bf16(Bt[n][k], At[m][k], acc[ai][bj][m][n], 0, 0, 0); __builtin_amdgcn_s_setprio(0); } while (0)
; #define PG8_WAIT_V(n) asm volatile("s_waitcnt vmcnt(" #n ")" ::: "memory")
; #define PG8_WAIT_L(n) asm volatile("s_waitcnt lgkmcnt(" #n ")" ::: "memory")
; #define PG8_BAR __builtin_amdgcn_s_barrier()
; #define PG8_SCHED __builtin_amdgcn_sched_barrier(0)
; template <class Epi, class Sched, bool ALIGN_EPI = false, bool SP2 = false>
; __device__ __forceinline__ void gemm_phase(PG8_LAS unsigned char* lds, const Gemm g, const Sched& S, const Epi& E) {
;     ...
;             PG8_WAIT_V(8); PG8_WAIT_L(0); PG8_BAR; PG8_MMA(0, 0, At, B0); PG8_MMA(0, 1, At, B1); PG8_BAR; PG8_SCHED;
;             PG8_LDA(At, 0, 1); PG8_STAGE(PG8_SB(0, 0), b2, voffB); PG8_STAGE(PG8_SB(0, 1), b2 + hstep, voffB); PG8_STAGE(PG8_SA(0, 0), a2, voffA);
;             PG8_WAIT_V(8); PG8_WAIT_L(0); PG8_BAR; PG8_MMA(1, 0, At, B0); PG8_MMA(1, 1, At, B1); PG8_BAR; PG8_SCHED;
	s_waitcnt lgkmcnt(0)
	v_mfma_f32_16x16x32_bf16 v[124:127], v[144:147], v[200:203], v[124:127]
	v_mfma_f32_16x16x32_bf16 v[120:123], v[172:175], v[200:203], v[120:123]
	v_mfma_f32_16x16x32_bf16 v[108:111], v[144:147], v[208:211], v[108:111]
	v_mfma_f32_16x16x32_bf16 v[104:107], v[172:175], v[208:211], v[104:107]
	v_mfma_f32_16x16x32_bf16 v[92:95], v[144:147], v[216:219], v[92:95]
	v_mfma_f32_16x16x32_bf16 v[88:91], v[172:175], v[216:219], v[88:91]
	v_mfma_f32_16x16x32_bf16 v[76:79], v[144:147], v[224:227], v[76:79]
	v_mfma_f32_16x16x32_bf16 v[72:75], v[172:175], v[224:227], v[72:75]
	v_mfma_f32_16x16x32_bf16 v[124:127], v[168:171], v[204:207], v[124:127]
	v_mfma_f32_16x16x32_bf16 v[120:123], v[176:179], v[204:207], v[120:123]
	v_mfma_f32_16x16x32_bf16 v[108:111], v[168:171], v[212:215], v[108:111]
	v_mfma_f32_16x16x32_bf16 v[104:107], v[176:179], v[212:215], v[104:107]
	v_mfma_f32_16x16x32_bf16 v[92:95], v[168:171], v[220:223], v[92:95]
	v_mfma_f32_16x16x32_bf16 v[88:91], v[176:179], v[220:223], v[88:91]
	v_mfma_f32_16x16x32_bf16 v[76:79], v[168:171], v[228:231], v[76:79]
	v_mfma_f32_16x16x32_bf16 v[72:75], v[176:179], v[228:231], v[72:75]
	v_mfma_f32_16x16x32_bf16 v[116:119], v[180:183], v[200:203], v[116:119]
	v_mfma_f32_16x16x32_bf16 v[112:115], v[192:195], v[200:203], v[112:115]
	v_mfma_f32_16x16x32_bf16 v[100:103], v[180:183], v[208:211], v[100:103]
	v_mfma_f32_16x16x32_bf16 v[96:99], v[192:195], v[208:211], v[96:99]
	v_mfma_f32_16x16x32_bf16 v[84:87], v[180:183], v[216:219], v[84:87]
	v_mfma_f32_16x16x32_bf16 v[80:83], v[192:195], v[216:219], v[80:83]
	v_mfma_f32_16x16x32_bf16 v[68:71], v[180:183], v[224:227], v[68:71]
	v_mfma_f32_16x16x32_bf16 v[64:67], v[192:195], v[224:227], v[64:67]
	v_mfma_f32_16x16x32_bf16 v[116:119], v[188:191], v[204:207], v[116:119]
	v_mfma_f32_16x16x32_bf16 v[112:115], v[196:199], v[204:207], v[112:115]
	v_mfma_f32_16x16x32_bf16 v[100:103], v[188:191], v[212:215], v[100:103]
	v_mfma_f32_16x16x32_bf16 v[96:99], v[196:199], v[212:215], v[96:99]
	v_mfma_f32_16x16x32_bf16 v[84:87], v[188:191], v[220:223], v[84:87]
	v_mfma_f32_16x16x32_bf16 v[80:83], v[196:199], v[220:223], v[80:83]
	v_mfma_f32_16x16x32_bf16 v[68:71], v[188:191], v[228:231], v[68:71]
	v_mfma_f32_16x16x32_bf16 v[64:67], v[196:199], v[228:231], v[64:67]
	s_barrier
	s_add_i32 s79, s74, s38
	v_lshl_add_u64 v[148:149], s[28:29], 0, v[130:131]
	s_mov_b32 m0, s79
	ds_read_b128 v[200:203], v164 offset:16384
	ds_read_b128 v[204:207], v164 offset:17408
	ds_read_b128 v[208:211], v164 offset:18432
	ds_read_b128 v[212:215], v164 offset:19456
	ds_read_b128 v[216:219], v164 offset:20480
	ds_read_b128 v[220:223], v164 offset:21504
	ds_read_b128 v[224:227], v164 offset:22528
	ds_read_b128 v[228:231], v164 offset:23552
	global_load_lds_dwordx4 v[148:149], off
	s_add_i32 m0, s79, 0x2000
	s_add_u32 s80, s28, 0x40000
	v_lshl_add_u64 v[234:235], s[28:29], 0, v[134:135]
	s_addc_u32 s81, s29, 0
	s_add_i32 s79, s75, s38
	global_load_lds_dwordx4 v[234:235], off
	v_lshl_add_u64 v[236:237], s[80:81], 0, v[130:131]
	s_mov_b32 m0, s79
	v_lshl_add_u64 v[238:239], s[30:31], 0, v[132:133]
	global_load_lds_dwordx4 v[236:237], off
	v_lshl_add_u64 v[236:237], s[80:81], 0, v[134:135]
	s_add_i32 m0, s79, 0x2000
	s_nop 0
	global_load_lds_dwordx4 v[236:237], off
	v_lshl_add_u64 v[236:237], s[30:31], 0, v[128:129]
	s_mov_b32 m0, s39
	s_nop 0
	global_load_lds_dwordx4 v[236:237], off
	s_mov_b32 m0, s42
	s_nop 0
	global_load_lds_dwordx4 v[238:239], off
	s_waitcnt vmcnt(8)
	s_waitcnt lgkmcnt(0)
	s_barrier
	s_waitcnt lgkmcnt(0)
	v_mfma_f32_16x16x32_bf16 v[60:63], v[144:147], v[200:203], v[60:63]
	v_mfma_f32_16x16x32_bf16 v[56:59], v[172:175], v[200:203], v[56:59]
	v_mfma_f32_16x16x32_bf16 v[44:47], v[144:147], v[208:211], v[44:47]
	v_mfma_f32_16x16x32_bf16 v[40:43], v[172:175], v[208:211], v[40:43]
	v_mfma_f32_16x16x32_bf16 v[28:31], v[144:147], v[216:219], v[28:31]
	v_mfma_f32_16x16x32_bf16 v[24:27], v[172:175], v[216:219], v[24:27]
	v_mfma_f32_16x16x32_bf16 v[12:15], v[144:147], v[224:227], v[12:15]
	v_mfma_f32_16x16x32_bf16 v[8:11], v[172:175], v[224:227], v[8:11]
	v_mfma_f32_16x16x32_bf16 v[60:63], v[168:171], v[204:207], v[60:63]
	v_mfma_f32_16x16x32_bf16 v[56:59], v[176:179], v[204:207], v[56:59]
	v_mfma_f32_16x16x32_bf16 v[44:47], v[168:171], v[212:215], v[44:47]
	v_mfma_f32_16x16x32_bf16 v[40:43], v[176:179], v[212:215], v[40:43]
	v_mfma_f32_16x16x32_bf16 v[28:31], v[168:171], v[220:223], v[28:31]
	v_mfma_f32_16x16x32_bf16 v[24:27], v[176:179], v[220:223], v[24:27]
	v_mfma_f32_16x16x32_bf16 v[12:15], v[168:171], v[228:231], v[12:15]
	v_mfma_f32_16x16x32_bf16 v[8:11], v[176:179], v[228:231], v[8:11]
	v_mfma_f32_16x16x32_bf16 v[52:55], v[180:183], v[200:203], v[52:55]
	v_mfma_f32_16x16x32_bf16 v[48:51], v[192:195], v[200:203], v[48:51]
	v_mfma_f32_16x16x32_bf16 v[36:39], v[180:183], v[208:211], v[36:39]
	v_mfma_f32_16x16x32_bf16 v[32:35], v[192:195], v[208:211], v[32:35]
	v_mfma_f32_16x16x32_bf16 v[20:23], v[180:183], v[216:219], v[20:23]
	v_mfma_f32_16x16x32_bf16 v[16:19], v[192:195], v[216:219], v[16:19]
	v_mfma_f32_16x16x32_bf16 v[4:7], v[180:183], v[224:227], v[4:7]
	v_mfma_f32_16x16x32_bf16 v[0:3], v[192:195], v[224:227], v[0:3]
	v_mfma_f32_16x16x32_bf16 v[52:55], v[188:191], v[204:207], v[52:55]
	v_mfma_f32_16x16x32_bf16 v[48:51], v[196:199], v[204:207], v[48:51]
	v_mfma_f32_16x16x32_bf16 v[36:39], v[188:191], v[212:215], v[36:39]
	v_mfma_f32_16x16x32_bf16 v[32:35], v[196:199], v[212:215], v[32:35]
	v_mfma_f32_16x16x32_bf16 v[20:23], v[188:191], v[220:223], v[20:23]
	v_mfma_f32_16x16x32_bf16 v[16:19], v[196:199], v[220:223], v[16:19]
	v_mfma_f32_16x16x32_bf16 v[4:7], v[188:191], v[228:231], v[4:7]
	v_mfma_f32_16x16x32_bf16 v[0:3], v[196:199], v[228:231], v[0:3]
	s_barrier
; #define PG8_STAGE(bufoff, gbase, voff) do { _Pragma("unroll") for (int _i = 0; _i < 2; ++_i) \
;         __builtin_amdgcn_global_load_lds((const unsigned*)((const char*)(gbase) + (voff)[_i]), (PG8_LAS unsigned*)(lds + (bufoff) + ldsw + _i * 8192), 16, 0, 0); } while (0)
; #define PG8_LDA(dst, b, h) do { _Pragma("unroll") for (int m = 0; m < 4; ++m) _Pragma("unroll") for (int k = 0; k < 2; ++k) dst[m][k] = *(const PG8_LAS bf16x8*)(lds + PG8_SA(b, h) + aoff + m * 2048 + k * 1024); } while (0)
; #define PG8_LDB(dst, b, h) do { _Pragma("unroll") for (int n = 0; n < 2; ++n) _Pragma("unroll") for (int k = 0; k < 2; ++k) dst[n][k] = *(const PG8_LAS bf16x8*)(lds + PG8_SB(b, h) + boff + n * 2048 + k * 1024); } while (0)
; #define PG8_MMA(ai, bj, At, Bt) do { __builtin_amdgcn_s_setprio(1); _Pragma("unroll") for (int m = 0; m < 4; ++m) _Pragma("unroll") for (int n = 0; n < 2; ++n) _Pragma("unroll") for (int k = 0; k < 2; ++k) \
;         acc[ai][bj][m][n] = __builtin_amdgcn_mfma_f32_16x16x32_bf16(Bt[n][k], At[m][k], acc[ai][bj][m][n], 0, 0, 0); __builtin_amdgcn_s_setprio(0); } while (0)
; #define PG8_WAIT_V(n) asm volatile("s_waitcnt vmcnt(" #n ")" ::: "memory")
; #define PG8_WAIT_L(n) asm volatile("s_waitcnt lgkmcnt(" #n ")" ::: "memory")
; #define PG8_BAR __builtin_amdgcn_s_barrier()
; #define PG8_SCHED __builtin_amdgcn_sched_barrier(0)
; template <class Epi, class Sched, bool ALIGN_EPI = false, bool SP2 = false>
; __device__ __forceinline__ void gemm_phase(PG8_LAS unsigned char* lds, const Gemm g, const Sched& S, const Epi& E) {
;     ...
;             PG8_LDB(B0, 1, 0); PG8_LDB(B1, 1, 1); PG8_SCHED; PG8_LDA(At, 1, 0); PG8_STAGE(PG8_SA(0, 1), a2 + hstep, voffA);
;             PG8_WAIT_V(8); PG8_WAIT_L(0); PG8_BAR; PG8_MMA(0, 0, At, B0); PG8_MMA(0, 1, At, B1); PG8_BAR; PG8_SCHED;
	s_add_i32 s79, 0, 0x18000
	v_add_u32_e32 v167, s79, v157
	s_add_i32 s80, 0, 0x1c000
	ds_read_b128 v[144:147], v167
	ds_read_b128 v[168:171], v167 offset:1024
	ds_read_b128 v[172:175], v167 offset:2048
	ds_read_b128 v[176:179], v167 offset:3072
	v_add_u32_e32 v167, s80, v157
	ds_read_b128 v[180:183], v167
	ds_read_b128 v[188:191], v167 offset:1024
	ds_read_b128 v[192:195], v167 offset:2048
	ds_read_b128 v[196:199], v167 offset:3072
	s_add_u32 s30, s30, 0x40000
	s_addc_u32 s31, s31, 0
	s_mov_b32 m0, s43
	v_lshl_add_u64 v[240:241], s[30:31], 0, v[128:129]
	ds_read_b128 v[200:203], v164 offset:32768
	ds_read_b128 v[204:207], v164 offset:33792
	ds_read_b128 v[208:211], v164 offset:34816
	ds_read_b128 v[212:215], v164 offset:35840
	ds_read_b128 v[216:219], v164 offset:36864
	ds_read_b128 v[220:223], v164 offset:37888
	ds_read_b128 v[224:227], v164 offset:38912
	ds_read_b128 v[228:231], v164 offset:39936
	global_load_lds_dwordx4 v[240:241], off
	v_lshl_add_u64 v[240:241], s[30:31], 0, v[132:133]
	s_mov_b32 m0, s44
	s_nop 0
	global_load_lds_dwordx4 v[240:241], off
	s_waitcnt vmcnt(8)
	s_waitcnt lgkmcnt(0)
	s_barrier
	s_waitcnt lgkmcnt(0)
	v_mfma_f32_16x16x32_bf16 v[124:127], v[144:147], v[200:203], v[124:127]
	v_mfma_f32_16x16x32_bf16 v[120:123], v[172:175], v[200:203], v[120:123]
	v_mfma_f32_16x16x32_bf16 v[108:111], v[144:147], v[208:211], v[108:111]
	v_mfma_f32_16x16x32_bf16 v[104:107], v[172:175], v[208:211], v[104:107]
	v_mfma_f32_16x16x32_bf16 v[92:95], v[144:147], v[216:219], v[92:95]
	v_mfma_f32_16x16x32_bf16 v[88:91], v[172:175], v[216:219], v[88:91]
	v_mfma_f32_16x16x32_bf16 v[76:79], v[144:147], v[224:227], v[76:79]
	v_mfma_f32_16x16x32_bf16 v[72:75], v[172:175], v[224:227], v[72:75]
	v_mfma_f32_16x16x32_bf16 v[124:127], v[168:171], v[204:207], v[124:127]
	v_mfma_f32_16x16x32_bf16 v[120:123], v[176:179], v[204:207], v[120:123]
	v_mfma_f32_16x16x32_bf16 v[108:111], v[168:171], v[212:215], v[108:111]
	v_mfma_f32_16x16x32_bf16 v[104:107], v[176:179], v[212:215], v[104:107]
	v_mfma_f32_16x16x32_bf16 v[92:95], v[168:171], v[220:223], v[92:95]
	v_mfma_f32_16x16x32_bf16 v[88:91], v[176:179], v[220:223], v[88:91]
	v_mfma_f32_16x16x32_bf16 v[76:79], v[168:171], v[228:231], v[76:79]
	v_mfma_f32_16x16x32_bf16 v[72:75], v[176:179], v[228:231], v[72:75]
	v_mfma_f32_16x16x32_bf16 v[116:119], v[180:183], v[200:203], v[116:119]
	v_mfma_f32_16x16x32_bf16 v[112:115], v[192:195], v[200:203], v[112:115]
	v_mfma_f32_16x16x32_bf16 v[100:103], v[180:183], v[208:211], v[100:103]
	v_mfma_f32_16x16x32_bf16 v[96:99], v[192:195], v[208:211], v[96:99]
	v_mfma_f32_16x16x32_bf16 v[84:87], v[180:183], v[216:219], v[84:87]
	v_mfma_f32_16x16x32_bf16 v[80:83], v[192:195], v[216:219], v[80:83]
	v_mfma_f32_16x16x32_bf16 v[68:71], v[180:183], v[224:227], v[68:71]
	v_mfma_f32_16x16x32_bf16 v[64:67], v[192:195], v[224:227], v[64:67]
	v_mfma_f32_16x16x32_bf16 v[116:119], v[188:191], v[204:207], v[116:119]
	v_mfma_f32_16x16x32_bf16 v[112:115], v[196:199], v[204:207], v[112:115]
	v_mfma_f32_16x16x32_bf16 v[100:103], v[188:191], v[212:215], v[100:103]
	v_mfma_f32_16x16x32_bf16 v[96:99], v[196:199], v[212:215], v[96:99]
	v_mfma_f32_16x16x32_bf16 v[84:87], v[188:191], v[220:223], v[84:87]
	v_mfma_f32_16x16x32_bf16 v[80:83], v[196:199], v[220:223], v[80:83]
	v_mfma_f32_16x16x32_bf16 v[68:71], v[188:191], v[228:231], v[68:71]
	v_mfma_f32_16x16x32_bf16 v[64:67], v[196:199], v[228:231], v[64:67]
	s_barrier
; #define PG8_STAGE(bufoff, gbase, voff) do { _Pragma("unroll") for (int _i = 0; _i < 2; ++_i) \
;         __builtin_amdgcn_global_load_lds((const unsigned*)((const char*)(gbase) + (voff)[_i]), (PG8_LAS unsigned*)(lds + (bufoff) + ldsw + _i * 8192), 16, 0, 0); } while (0)
; #define PG8_LDA(dst, b, h) do { _Pragma("unroll") for (int m = 0; m < 4; ++m) _Pragma("unroll") for (int k = 0; k < 2; ++k) dst[m][k] = *(const PG8_LAS bf16x8*)(lds + PG8_SA(b, h) + aoff + m * 2048 + k * 1024); } while (0)
; #define PG8_MMA(ai, bj, At, Bt) do { __builtin_amdgcn_s_setprio(1); _Pragma("unroll") for (int m = 0; m < 4; ++m) _Pragma("unroll") for (int n = 0; n < 2; ++n) _Pragma("unroll") for (int k = 0; k < 2; ++k) \
;         acc[ai][bj][m][n] = __builtin_amdgcn_mfma_f32_16x16x32_bf16(Bt[n][k], At[m][k], acc[ai][bj][m][n], 0, 0, 0); __builtin_amdgcn_s_setprio(0); } while (0)
; #define PG8_WAIT_V(n) asm volatile("s_waitcnt vmcnt(" #n ")" ::: "memory")
; #define PG8_WAIT_L(n) asm volatile("s_waitcnt lgkmcnt(" #n ")" ::: "memory")
; #define PG8_BAR __builtin_amdgcn_s_barrier()
; #define PG8_SCHED __builtin_amdgcn_sched_barrier(0)
; template <class Epi, class Sched, bool ALIGN_EPI = false, bool SP2 = false>
; __device__ __forceinline__ void gemm_phase(PG8_LAS unsigned char* lds, const Gemm g, const Sched& S, const Epi& E) {
;     ...
;             PG8_LDA(At, 1, 1); PG8_STAGE(PG8_SB(1, 0), b3, voffB); PG8_STAGE(PG8_SB(1, 1), b3 + hstep, voffB); PG8_STAGE(PG8_SA(1, 0), a3, voffA);
;             PG8_WAIT_V(8); PG8_WAIT_L(0); PG8_BAR; PG8_MMA(1, 0, At, B0); PG8_MMA(1, 1, At, B1); PG8_BAR; PG8_SCHED;
;     ...
;         if constexpr (ALIGN_EPI) { if (wr == 0) PG8_BAR; }
	s_add_i32 s30, s79, s38
	v_lshl_add_u64 v[148:149], v[148:149], 0, s[12:13]
	s_mov_b32 m0, s30
	ds_read_b128 v[200:203], v164 offset:49152
	ds_read_b128 v[204:207], v164 offset:50176
	ds_read_b128 v[208:211], v164 offset:51200
	ds_read_b128 v[212:215], v164 offset:52224
	ds_read_b128 v[216:219], v164 offset:53248
	ds_read_b128 v[220:223], v164 offset:54272
	ds_read_b128 v[224:227], v164 offset:55296
	ds_read_b128 v[228:231], v164 offset:56320
	global_load_lds_dwordx4 v[148:149], off
	s_add_i32 m0, s30, 0x2000
	s_add_u32 s28, s28, 0x40080
	v_lshl_add_u64 v[148:149], v[234:235], 0, s[12:13]
	s_addc_u32 s29, s29, 0
	s_add_i32 s30, s80, s38
	global_load_lds_dwordx4 v[148:149], off
	v_lshl_add_u64 v[148:149], s[28:29], 0, v[130:131]
	s_mov_b32 m0, s30
	s_nop 0
	global_load_lds_dwordx4 v[148:149], off
	v_lshl_add_u64 v[148:149], s[28:29], 0, v[134:135]
	s_add_i32 m0, s30, 0x2000
	s_nop 0
	global_load_lds_dwordx4 v[148:149], off
	v_lshl_add_u64 v[148:149], v[236:237], 0, s[12:13]
	s_mov_b32 m0, s50
	s_nop 0
	global_load_lds_dwordx4 v[148:149], off
	v_lshl_add_u64 v[148:149], v[238:239], 0, s[12:13]
	s_mov_b32 m0, s51
	s_nop 0
	global_load_lds_dwordx4 v[148:149], off
	s_waitcnt vmcnt(8)
	s_waitcnt lgkmcnt(0)
	s_barrier
	s_waitcnt lgkmcnt(0)
	v_mfma_f32_16x16x32_bf16 v[60:63], v[144:147], v[200:203], v[60:63]
	v_mfma_f32_16x16x32_bf16 v[56:59], v[172:175], v[200:203], v[56:59]
	v_mfma_f32_16x16x32_bf16 v[44:47], v[144:147], v[208:211], v[44:47]
	v_mfma_f32_16x16x32_bf16 v[40:43], v[172:175], v[208:211], v[40:43]
	v_mfma_f32_16x16x32_bf16 v[28:31], v[144:147], v[216:219], v[28:31]
	v_mfma_f32_16x16x32_bf16 v[24:27], v[172:175], v[216:219], v[24:27]
	v_mfma_f32_16x16x32_bf16 v[12:15], v[144:147], v[224:227], v[12:15]
	v_mfma_f32_16x16x32_bf16 v[8:11], v[172:175], v[224:227], v[8:11]
	v_mfma_f32_16x16x32_bf16 v[60:63], v[168:171], v[204:207], v[60:63]
	v_mfma_f32_16x16x32_bf16 v[56:59], v[176:179], v[204:207], v[56:59]
	v_mfma_f32_16x16x32_bf16 v[44:47], v[168:171], v[212:215], v[44:47]
	v_mfma_f32_16x16x32_bf16 v[40:43], v[176:179], v[212:215], v[40:43]
	v_mfma_f32_16x16x32_bf16 v[28:31], v[168:171], v[220:223], v[28:31]
	v_mfma_f32_16x16x32_bf16 v[24:27], v[176:179], v[220:223], v[24:27]
	v_mfma_f32_16x16x32_bf16 v[12:15], v[168:171], v[228:231], v[12:15]
	v_mfma_f32_16x16x32_bf16 v[8:11], v[176:179], v[228:231], v[8:11]
	v_mfma_f32_16x16x32_bf16 v[52:55], v[180:183], v[200:203], v[52:55]
	v_mfma_f32_16x16x32_bf16 v[48:51], v[192:195], v[200:203], v[48:51]
	v_mfma_f32_16x16x32_bf16 v[36:39], v[180:183], v[208:211], v[36:39]
	v_mfma_f32_16x16x32_bf16 v[32:35], v[192:195], v[208:211], v[32:35]
	v_mfma_f32_16x16x32_bf16 v[20:23], v[180:183], v[216:219], v[20:23]
	v_mfma_f32_16x16x32_bf16 v[16:19], v[192:195], v[216:219], v[16:19]
	v_mfma_f32_16x16x32_bf16 v[4:7], v[180:183], v[224:227], v[4:7]
	v_mfma_f32_16x16x32_bf16 v[0:3], v[192:195], v[224:227], v[0:3]
	v_mfma_f32_16x16x32_bf16 v[52:55], v[188:191], v[204:207], v[52:55]
	v_mfma_f32_16x16x32_bf16 v[48:51], v[196:199], v[204:207], v[48:51]
	v_mfma_f32_16x16x32_bf16 v[36:39], v[188:191], v[212:215], v[36:39]
	v_mfma_f32_16x16x32_bf16 v[32:35], v[196:199], v[212:215], v[32:35]
	v_mfma_f32_16x16x32_bf16 v[20:23], v[188:191], v[220:223], v[20:23]
	v_mfma_f32_16x16x32_bf16 v[16:19], v[196:199], v[220:223], v[16:19]
	v_mfma_f32_16x16x32_bf16 v[4:7], v[188:191], v[228:231], v[4:7]
	v_mfma_f32_16x16x32_bf16 v[0:3], v[196:199], v[228:231], v[0:3]
	s_barrier
	s_add_i32 s78, s78, 2
	s_add_u32 s26, s26, 0x100
	s_addc_u32 s27, s27, 0
	s_add_u32 s76, s76, 0x100
	s_addc_u32 s77, s77, 0
	s_cmp_gt_u32 s78, 13
	s_cbranch_scc0 .LBB0_490
	s_setprio 0
	s_and_b64 vcc, exec, s[14:15]
	s_cbranch_vccz .LBB0_493
	s_barrier

; #define PG8_STAGE(bufoff, gbase, voff) do { _Pragma("unroll") for (int _i = 0; _i < 2; ++_i) \
;         __builtin_amdgcn_global_load_lds((const unsigned*)((const char*)(gbase) + (voff)[_i]), (PG8_LAS unsigned*)(lds + (bufoff) + ldsw + _i * 8192), 16, 0, 0); } while (0)
; #define PG8_LDA(dst, b, h) do { _Pragma("unroll") for (int m = 0; m < 4; ++m) _Pragma("unroll") for (int k = 0; k < 2; ++k) dst[m][k] = *(const PG8_LAS bf16x8*)(lds + PG8_SA(b, h) + aoff + m * 2048 + k * 1024); } while (0)
; #define PG8_LDB(dst, b, h) do { _Pragma("unroll") for (int n = 0; n < 2; ++n) _Pragma("unroll") for (int k = 0; k < 2; ++k) dst[n][k] = *(const PG8_LAS bf16x8*)(lds + PG8_SB(b, h) + boff + n * 2048 + k * 1024); } while (0)
; #define PG8_MMA(ai, bj, At, Bt) do { __builtin_amdgcn_s_setprio(1); _Pragma("unroll") for (int m = 0; m < 4; ++m) _Pragma("unroll") for (int n = 0; n < 2; ++n) _Pragma("unroll") for (int k = 0; k < 2; ++k) \
;         acc[ai][bj][m][n] = __builtin_amdgcn_mfma_f32_16x16x32_bf16(Bt[n][k], At[m][k], acc[ai][bj][m][n], 0, 0, 0); __builtin_amdgcn_s_setprio(0); } while (0)
; #define PG8_WAIT_V(n) asm volatile("s_waitcnt vmcnt(" #n ")" ::: "memory")
; #define PG8_WAIT_L(n) asm volatile("s_waitcnt lgkmcnt(" #n ")" ::: "memory")
; #define PG8_BAR __builtin_amdgcn_s_barrier()
; #define PG8_SCHED __builtin_amdgcn_sched_barrier(0)
; template <class Epi, class Sched, bool ALIGN_EPI = false, bool SP2 = false>
; __device__ __forceinline__ void gemm_phase(PG8_LAS unsigned char* lds, const Gemm g, const Sched& S, const Epi& E) {
;     ...
;             PG8_LDB(B0, 0, 0); PG8_LDB(B1, 0, 1); PG8_SCHED; PG8_LDA(At, 0, 0); PG8_STAGE(PG8_SA(1, 1), a1 + hstep, voffA);
;             PG8_WAIT_V(8); PG8_WAIT_L(0); PG8_BAR; PG8_MMA(0, 0, At, B0); PG8_MMA(0, 1, At, B1); PG8_BAR; PG8_SCHED;
;     ...
; #pragma unroll
;         for (int a = 0; a < 2; ++a)
; #pragma unroll
;             for (int b = 0; b < 2; ++b)
; #pragma unroll
;                 for (int m = 0; m < 4; ++m)
; #pragma unroll
;                     for (int n = 0; n < 2; ++n) acc[a][b][m][n] = (f32x4){0.f, 0.f, 0.f, 0.f};
.LBB0_575:
	s_ashr_i32 s13, s12, 31
	v_cmp_lt_i64_e32 vcc, s[14:15], v[142:143]
	s_lshl_b64 s[14:15], s[12:13], 19
	s_add_u32 s14, s28, s14
	s_addc_u32 s15, s29, s15
	s_and_b64 s[16:17], vcc, exec
	s_cselect_b32 s13, s15, s21
	s_cselect_b32 s50, s14, s20
	s_ashr_i32 s11, s10, 31
	s_lshl_b64 s[16:17], s[10:11], 19
	s_add_u32 s16, s34, s16
	s_addc_u32 s17, s35, s17
	s_and_b64 s[24:25], vcc, exec
	s_cselect_b32 s11, s17, s23
	s_cselect_b32 s51, s16, s22
	s_add_u32 s20, s20, 0x40080
	s_addc_u32 s21, s21, 0
	s_add_u32 s58, s22, 0x100
	v_mov_b32_e32 v0, 0
	s_addc_u32 s69, s23, 0
	s_mov_b32 s70, -2
	v_mov_b32_e32 v1, v0
	v_mov_b32_e32 v2, v0
	v_mov_b32_e32 v3, v0
	v_mov_b32_e32 v4, v0
	v_mov_b32_e32 v5, v0
	v_mov_b32_e32 v6, v0
	v_mov_b32_e32 v7, v0
	v_mov_b32_e32 v16, v0
	v_mov_b32_e32 v17, v0
	v_mov_b32_e32 v18, v0
	v_mov_b32_e32 v19, v0
	v_mov_b32_e32 v20, v0
	v_mov_b32_e32 v21, v0
	v_mov_b32_e32 v22, v0
	v_mov_b32_e32 v23, v0
	v_mov_b32_e32 v32, v0
	v_mov_b32_e32 v33, v0
	v_mov_b32_e32 v34, v0
	v_mov_b32_e32 v35, v0
	v_mov_b32_e32 v36, v0
	v_mov_b32_e32 v37, v0
	v_mov_b32_e32 v38, v0
	v_mov_b32_e32 v39, v0
	v_mov_b32_e32 v48, v0
	v_mov_b32_e32 v49, v0
	v_mov_b32_e32 v50, v0
	v_mov_b32_e32 v51, v0
	v_mov_b32_e32 v52, v0
	v_mov_b32_e32 v53, v0
	v_mov_b32_e32 v54, v0
	v_mov_b32_e32 v55, v0
	v_mov_b32_e32 v8, v0
	v_mov_b32_e32 v9, v0
	v_mov_b32_e32 v10, v0
	v_mov_b32_e32 v11, v0
	v_mov_b32_e32 v12, v0
	v_mov_b32_e32 v13, v0
	v_mov_b32_e32 v14, v0
	v_mov_b32_e32 v15, v0
	v_mov_b32_e32 v24, v0
	v_mov_b32_e32 v25, v0
	v_mov_b32_e32 v26, v0
	v_mov_b32_e32 v27, v0
	v_mov_b32_e32 v28, v0
	v_mov_b32_e32 v29, v0
	v_mov_b32_e32 v30, v0
	v_mov_b32_e32 v31, v0
	v_mov_b32_e32 v40, v0
	v_mov_b32_e32 v41, v0
	v_mov_b32_e32 v42, v0
	v_mov_b32_e32 v43, v0
	v_mov_b32_e32 v44, v0
	v_mov_b32_e32 v45, v0
	v_mov_b32_e32 v46, v0
	v_mov_b32_e32 v47, v0
	v_mov_b32_e32 v56, v0
	v_mov_b32_e32 v57, v0
	v_mov_b32_e32 v58, v0
	v_mov_b32_e32 v59, v0
	v_mov_b32_e32 v60, v0
	v_mov_b32_e32 v61, v0
	v_mov_b32_e32 v62, v0
	v_mov_b32_e32 v63, v0
	v_mov_b32_e32 v64, v0
	v_mov_b32_e32 v65, v0
	v_mov_b32_e32 v66, v0
	v_mov_b32_e32 v67, v0
	v_mov_b32_e32 v68, v0
	v_mov_b32_e32 v69, v0
	v_mov_b32_e32 v70, v0
	v_mov_b32_e32 v71, v0
	v_mov_b32_e32 v80, v0
	v_mov_b32_e32 v81, v0
	v_mov_b32_e32 v82, v0
	v_mov_b32_e32 v83, v0
	v_mov_b32_e32 v84, v0
	v_mov_b32_e32 v85, v0
	v_mov_b32_e32 v86, v0
	v_mov_b32_e32 v87, v0
	v_mov_b32_e32 v96, v0
	v_mov_b32_e32 v97, v0
	v_mov_b32_e32 v98, v0
	v_mov_b32_e32 v99, v0
	v_mov_b32_e32 v100, v0
	v_mov_b32_e32 v101, v0
	v_mov_b32_e32 v102, v0
	v_mov_b32_e32 v103, v0
	v_mov_b32_e32 v104, v0
	v_mov_b32_e32 v105, v0
	v_mov_b32_e32 v106, v0
	v_mov_b32_e32 v107, v0
	v_mov_b32_e32 v108, v0
	v_mov_b32_e32 v109, v0
	v_mov_b32_e32 v110, v0
	v_mov_b32_e32 v111, v0
	v_mov_b32_e32 v72, v0
	v_mov_b32_e32 v73, v0
	v_mov_b32_e32 v74, v0
	v_mov_b32_e32 v75, v0
	v_mov_b32_e32 v76, v0
	v_mov_b32_e32 v77, v0
	v_mov_b32_e32 v78, v0
	v_mov_b32_e32 v79, v0
	v_mov_b32_e32 v88, v0
	v_mov_b32_e32 v89, v0
	v_mov_b32_e32 v90, v0
	v_mov_b32_e32 v91, v0
	v_mov_b32_e32 v92, v0
	v_mov_b32_e32 v93, v0
	v_mov_b32_e32 v94, v0
	v_mov_b32_e32 v95, v0
	v_mov_b32_e32 v112, v0
	v_mov_b32_e32 v113, v0
	v_mov_b32_e32 v114, v0
	v_mov_b32_e32 v115, v0
	v_mov_b32_e32 v116, v0
	v_mov_b32_e32 v117, v0
	v_mov_b32_e32 v118, v0
	v_mov_b32_e32 v119, v0
	v_mov_b32_e32 v120, v0
	v_mov_b32_e32 v121, v0
	v_mov_b32_e32 v122, v0
	v_mov_b32_e32 v123, v0
	v_mov_b32_e32 v124, v0
	v_mov_b32_e32 v125, v0
	v_mov_b32_e32 v126, v0
	v_mov_b32_e32 v127, v0
	s_bitcmp1_b32 s60, 2
	s_cbranch_scc0 .Lgprio_3
	s_setprio 1
.Lgprio_3:
.LBB0_576:
	ds_read_b128 v[146:149], v167
	ds_read_b128 v[150:153], v167 offset:1024
	ds_read_b128 v[154:157], v167 offset:2048
	ds_read_b128 v[158:161], v167 offset:3072
	ds_read_b128 v[172:175], v168
	ds_read_b128 v[176:179], v168 offset:1024
	ds_read_b128 v[180:183], v168 offset:2048
	ds_read_b128 v[188:191], v168 offset:3072
	s_add_u32 s22, s20, 0xfffc0080
	s_addc_u32 s23, s21, -1
	s_cmp_eq_u32 s70, 12
	s_cselect_b32 s25, s13, s23
	s_cselect_b32 s24, s50, s22
	s_cselect_b32 s23, s11, s69
	s_cselect_b32 s22, s51, s58
	v_lshl_add_u64 v[224:225], s[20:21], 0, v[138:139]
	s_add_i32 m0, s19, 0xc000
	ds_read_b128 v[192:195], v169
	ds_read_b128 v[196:199], v169 offset:1024
	ds_read_b128 v[200:203], v169 offset:2048
	ds_read_b128 v[204:207], v169 offset:3072
	ds_read_b128 v[208:211], v169 offset:4096
	ds_read_b128 v[212:215], v169 offset:5120
	ds_read_b128 v[216:219], v169 offset:6144
	ds_read_b128 v[220:223], v169 offset:7168
	global_load_lds_dwordx4 v[224:225], off
	v_lshl_add_u64 v[224:225], s[20:21], 0, v[140:141]
	s_add_i32 m0, s19, 0xe000
	s_nop 0
	global_load_lds_dwordx4 v[224:225], off
	s_waitcnt vmcnt(8)
	s_waitcnt lgkmcnt(0)
	s_barrier
; #define PG8_STAGE(bufoff, gbase, voff) do { _Pragma("unroll") for (int _i = 0; _i < 2; ++_i) \
;         __builtin_amdgcn_global_load_lds((const unsigned*)((const char*)(gbase) + (voff)[_i]), (PG8_LAS unsigned*)(lds + (bufoff) + ldsw + _i * 8192), 16, 0, 0); } while (0)
; #define PG8_LDA(dst, b, h) do { _Pragma("unroll") for (int m = 0; m < 4; ++m) _Pragma("unroll") for (int k = 0; k < 2; ++k) dst[m][k] = *(const PG8_LAS bf16x8*)(lds + PG8_SA(b, h) + aoff + m * 2048 + k * 1024); } while (0)
; #define PG8_MMA(ai, bj, At, Bt) do { __builtin_amdgcn_s_setprio(1); _Pragma("unroll") for (int m = 0; m < 4; ++m) _Pragma("unroll") for (int n = 0; n < 2; ++n) _Pragma("unroll") for (int k = 0; k < 2; ++k) \
;         acc[ai][bj][m][n] = __builtin_amdgcn_mfma_f32_16x16x32_bf16(Bt[n][k], At[m][k], acc[ai][bj][m][n], 0, 0, 0); __builtin_amdgcn_s_setprio(0); } while (0)
; #define PG8_WAIT_V(n) asm volatile("s_waitcnt vmcnt(" #n ")" ::: "memory")
; #define PG8_WAIT_L(n) asm volatile("s_waitcnt lgkmcnt(" #n ")" ::: "memory")
; #define PG8_BAR __builtin_amdgcn_s_barrier()
; #define PG8_SCHED __builtin_amdgcn_sched_barrier(0)
; template <class Epi, class Sched, bool ALIGN_EPI = false, bool SP2 = false>
; __device__ __forceinline__ void gemm_phase(PG8_LAS unsigned char* lds, const Gemm g, const Sched& S, const Epi& E) {
;     ...
;             PG8_WAIT_V(8); PG8_WAIT_L(0); PG8_BAR; PG8_MMA(0, 0, At, B0); PG8_MMA(0, 1, At, B1); PG8_BAR; PG8_SCHED;
;             PG8_LDA(At, 0, 1); PG8_STAGE(PG8_SB(0, 0), b2, voffB); PG8_STAGE(PG8_SB(0, 1), b2 + hstep, voffB); PG8_STAGE(PG8_SA(0, 0), a2, voffA);
;             PG8_WAIT_V(8); PG8_WAIT_L(0); PG8_BAR; PG8_MMA(1, 0, At, B0); PG8_MMA(1, 1, At, B1); PG8_BAR; PG8_SCHED;
	s_waitcnt lgkmcnt(0)
	v_mfma_f32_16x16x32_bf16 v[124:127], v[146:149], v[192:195], v[124:127]
	v_mfma_f32_16x16x32_bf16 v[120:123], v[154:157], v[192:195], v[120:123]
	v_mfma_f32_16x16x32_bf16 v[116:119], v[146:149], v[200:203], v[116:119]
	v_mfma_f32_16x16x32_bf16 v[112:115], v[154:157], v[200:203], v[112:115]
	v_mfma_f32_16x16x32_bf16 v[92:95], v[146:149], v[208:211], v[92:95]
	v_mfma_f32_16x16x32_bf16 v[88:91], v[154:157], v[208:211], v[88:91]
	v_mfma_f32_16x16x32_bf16 v[76:79], v[146:149], v[216:219], v[76:79]
	v_mfma_f32_16x16x32_bf16 v[72:75], v[154:157], v[216:219], v[72:75]
	v_mfma_f32_16x16x32_bf16 v[124:127], v[150:153], v[196:199], v[124:127]
	v_mfma_f32_16x16x32_bf16 v[120:123], v[158:161], v[196:199], v[120:123]
	v_mfma_f32_16x16x32_bf16 v[116:119], v[150:153], v[204:207], v[116:119]
	v_mfma_f32_16x16x32_bf16 v[112:115], v[158:161], v[204:207], v[112:115]
	v_mfma_f32_16x16x32_bf16 v[92:95], v[150:153], v[212:215], v[92:95]
	v_mfma_f32_16x16x32_bf16 v[88:91], v[158:161], v[212:215], v[88:91]
	v_mfma_f32_16x16x32_bf16 v[76:79], v[150:153], v[220:223], v[76:79]
	v_mfma_f32_16x16x32_bf16 v[72:75], v[158:161], v[220:223], v[72:75]
	v_mfma_f32_16x16x32_bf16 v[108:111], v[172:175], v[192:195], v[108:111]
	v_mfma_f32_16x16x32_bf16 v[104:107], v[180:183], v[192:195], v[104:107]
	v_mfma_f32_16x16x32_bf16 v[100:103], v[172:175], v[200:203], v[100:103]
	v_mfma_f32_16x16x32_bf16 v[96:99], v[180:183], v[200:203], v[96:99]
	v_mfma_f32_16x16x32_bf16 v[84:87], v[172:175], v[208:211], v[84:87]
	v_mfma_f32_16x16x32_bf16 v[80:83], v[180:183], v[208:211], v[80:83]
	v_mfma_f32_16x16x32_bf16 v[68:71], v[172:175], v[216:219], v[68:71]
	v_mfma_f32_16x16x32_bf16 v[64:67], v[180:183], v[216:219], v[64:67]
	v_mfma_f32_16x16x32_bf16 v[108:111], v[176:179], v[196:199], v[108:111]
	v_mfma_f32_16x16x32_bf16 v[104:107], v[188:191], v[196:199], v[104:107]
	v_mfma_f32_16x16x32_bf16 v[100:103], v[176:179], v[204:207], v[100:103]
	v_mfma_f32_16x16x32_bf16 v[96:99], v[188:191], v[204:207], v[96:99]
	v_mfma_f32_16x16x32_bf16 v[84:87], v[176:179], v[212:215], v[84:87]
	v_mfma_f32_16x16x32_bf16 v[80:83], v[188:191], v[212:215], v[80:83]
	v_mfma_f32_16x16x32_bf16 v[68:71], v[176:179], v[220:223], v[68:71]
	v_mfma_f32_16x16x32_bf16 v[64:67], v[188:191], v[220:223], v[64:67]
	s_barrier
	s_add_i32 s71, s47, s30
	v_lshl_add_u64 v[224:225], s[22:23], 0, v[130:131]
	s_mov_b32 m0, s71
	ds_read_b128 v[192:195], v169 offset:16384
	ds_read_b128 v[196:199], v169 offset:17408
	ds_read_b128 v[200:203], v169 offset:18432
	ds_read_b128 v[204:207], v169 offset:19456
	ds_read_b128 v[208:211], v169 offset:20480
	ds_read_b128 v[212:215], v169 offset:21504
	ds_read_b128 v[216:219], v169 offset:22528
	ds_read_b128 v[220:223], v169 offset:23552
	global_load_lds_dwordx4 v[224:225], off
	s_add_i32 m0, s71, 0x2000
	s_add_u32 s72, s22, 0x40000
	v_lshl_add_u64 v[226:227], s[22:23], 0, v[134:135]
	s_addc_u32 s73, s23, 0
	s_add_i32 s71, s48, s30
	global_load_lds_dwordx4 v[226:227], off
	v_lshl_add_u64 v[228:229], s[72:73], 0, v[130:131]
	s_mov_b32 m0, s71
	v_lshl_add_u64 v[230:231], s[24:25], 0, v[132:133]
	global_load_lds_dwordx4 v[228:229], off
	v_lshl_add_u64 v[228:229], s[72:73], 0, v[134:135]
	s_add_i32 m0, s71, 0x2000
	s_nop 0
	global_load_lds_dwordx4 v[228:229], off
	v_lshl_add_u64 v[228:229], s[24:25], 0, v[128:129]
	s_mov_b32 m0, s19
	s_nop 0
	global_load_lds_dwordx4 v[228:229], off
	s_mov_b32 m0, s31
	s_nop 0
	global_load_lds_dwordx4 v[230:231], off
	s_waitcnt vmcnt(8)
	s_waitcnt lgkmcnt(0)
	s_barrier
	s_waitcnt lgkmcnt(0)
	v_mfma_f32_16x16x32_bf16 v[60:63], v[146:149], v[192:195], v[60:63]
	v_mfma_f32_16x16x32_bf16 v[56:59], v[154:157], v[192:195], v[56:59]
	v_mfma_f32_16x16x32_bf16 v[44:47], v[146:149], v[200:203], v[44:47]
	v_mfma_f32_16x16x32_bf16 v[40:43], v[154:157], v[200:203], v[40:43]
	v_mfma_f32_16x16x32_bf16 v[28:31], v[146:149], v[208:211], v[28:31]
	v_mfma_f32_16x16x32_bf16 v[24:27], v[154:157], v[208:211], v[24:27]
	v_mfma_f32_16x16x32_bf16 v[12:15], v[146:149], v[216:219], v[12:15]
	v_mfma_f32_16x16x32_bf16 v[8:11], v[154:157], v[216:219], v[8:11]
	v_mfma_f32_16x16x32_bf16 v[60:63], v[150:153], v[196:199], v[60:63]
	v_mfma_f32_16x16x32_bf16 v[56:59], v[158:161], v[196:199], v[56:59]
	v_mfma_f32_16x16x32_bf16 v[44:47], v[150:153], v[204:207], v[44:47]
	v_mfma_f32_16x16x32_bf16 v[40:43], v[158:161], v[204:207], v[40:43]
	v_mfma_f32_16x16x32_bf16 v[28:31], v[150:153], v[212:215], v[28:31]
	v_mfma_f32_16x16x32_bf16 v[24:27], v[158:161], v[212:215], v[24:27]
	v_mfma_f32_16x16x32_bf16 v[12:15], v[150:153], v[220:223], v[12:15]
	v_mfma_f32_16x16x32_bf16 v[8:11], v[158:161], v[220:223], v[8:11]
	v_mfma_f32_16x16x32_bf16 v[52:55], v[172:175], v[192:195], v[52:55]
	v_mfma_f32_16x16x32_bf16 v[48:51], v[180:183], v[192:195], v[48:51]
	v_mfma_f32_16x16x32_bf16 v[36:39], v[172:175], v[200:203], v[36:39]
	v_mfma_f32_16x16x32_bf16 v[32:35], v[180:183], v[200:203], v[32:35]
	v_mfma_f32_16x16x32_bf16 v[20:23], v[172:175], v[208:211], v[20:23]
	v_mfma_f32_16x16x32_bf16 v[16:19], v[180:183], v[208:211], v[16:19]
	v_mfma_f32_16x16x32_bf16 v[4:7], v[172:175], v[216:219], v[4:7]
	v_mfma_f32_16x16x32_bf16 v[0:3], v[180:183], v[216:219], v[0:3]
	v_mfma_f32_16x16x32_bf16 v[52:55], v[176:179], v[196:199], v[52:55]
	v_mfma_f32_16x16x32_bf16 v[48:51], v[188:191], v[196:199], v[48:51]
	v_mfma_f32_16x16x32_bf16 v[36:39], v[176:179], v[204:207], v[36:39]
	v_mfma_f32_16x16x32_bf16 v[32:35], v[188:191], v[204:207], v[32:35]
	v_mfma_f32_16x16x32_bf16 v[20:23], v[176:179], v[212:215], v[20:23]
	v_mfma_f32_16x16x32_bf16 v[16:19], v[188:191], v[212:215], v[16:19]
	v_mfma_f32_16x16x32_bf16 v[4:7], v[176:179], v[220:223], v[4:7]
	v_mfma_f32_16x16x32_bf16 v[0:3], v[188:191], v[220:223], v[0:3]
	s_barrier
; #define PG8_STAGE(bufoff, gbase, voff) do { _Pragma("unroll") for (int _i = 0; _i < 2; ++_i) \
;         __builtin_amdgcn_global_load_lds((const unsigned*)((const char*)(gbase) + (voff)[_i]), (PG8_LAS unsigned*)(lds + (bufoff) + ldsw + _i * 8192), 16, 0, 0); } while (0)
; #define PG8_LDA(dst, b, h) do { _Pragma("unroll") for (int m = 0; m < 4; ++m) _Pragma("unroll") for (int k = 0; k < 2; ++k) dst[m][k] = *(const PG8_LAS bf16x8*)(lds + PG8_SA(b, h) + aoff + m * 2048 + k * 1024); } while (0)
; #define PG8_LDB(dst, b, h) do { _Pragma("unroll") for (int n = 0; n < 2; ++n) _Pragma("unroll") for (int k = 0; k < 2; ++k) dst[n][k] = *(const PG8_LAS bf16x8*)(lds + PG8_SB(b, h) + boff + n * 2048 + k * 1024); } while (0)
; #define PG8_MMA(ai, bj, At, Bt) do { __builtin_amdgcn_s_setprio(1); _Pragma("unroll") for (int m = 0; m < 4; ++m) _Pragma("unroll") for (int n = 0; n < 2; ++n) _Pragma("unroll") for (int k = 0; k < 2; ++k) \
;         acc[ai][bj][m][n] = __builtin_amdgcn_mfma_f32_16x16x32_bf16(Bt[n][k], At[m][k], acc[ai][bj][m][n], 0, 0, 0); __builtin_amdgcn_s_setprio(0); } while (0)
; #define PG8_WAIT_V(n) asm volatile("s_waitcnt vmcnt(" #n ")" ::: "memory")
; #define PG8_WAIT_L(n) asm volatile("s_waitcnt lgkmcnt(" #n ")" ::: "memory")
; #define PG8_BAR __builtin_amdgcn_s_barrier()
; #define PG8_SCHED __builtin_amdgcn_sched_barrier(0)
; template <class Epi, class Sched, bool ALIGN_EPI = false, bool SP2 = false>
; __device__ __forceinline__ void gemm_phase(PG8_LAS unsigned char* lds, const Gemm g, const Sched& S, const Epi& E) {
;     ...
;             PG8_LDB(B0, 1, 0); PG8_LDB(B1, 1, 1); PG8_SCHED; PG8_LDA(At, 1, 0); PG8_STAGE(PG8_SA(0, 1), a2 + hstep, voffA);
;             PG8_WAIT_V(8); PG8_WAIT_L(0); PG8_BAR; PG8_MMA(0, 0, At, B0); PG8_MMA(0, 1, At, B1); PG8_BAR; PG8_SCHED;
;             PG8_LDA(At, 1, 1); PG8_STAGE(PG8_SB(1, 0), b3, voffB); PG8_STAGE(PG8_SB(1, 1), b3 + hstep, voffB); PG8_STAGE(PG8_SA(1, 0), a3, voffA);
	s_add_i32 s71, 0, 0x18000
	s_add_i32 s72, 0, 0x1c000
	v_add_u32_e32 v158, s71, v164
	v_add_u32_e32 v171, s72, v164
	ds_read_b128 v[146:149], v158
	ds_read_b128 v[150:153], v158 offset:1024
	ds_read_b128 v[154:157], v158 offset:2048
	ds_read_b128 v[158:161], v158 offset:3072
	ds_read_b128 v[172:175], v171
	ds_read_b128 v[176:179], v171 offset:1024
	ds_read_b128 v[180:183], v171 offset:2048
	ds_read_b128 v[188:191], v171 offset:3072
	s_add_u32 s24, s24, 0x40000
	s_addc_u32 s25, s25, 0
	s_mov_b32 m0, s36
	v_lshl_add_u64 v[234:235], s[24:25], 0, v[128:129]
	ds_read_b128 v[192:195], v169 offset:32768
	ds_read_b128 v[196:199], v169 offset:33792
	ds_read_b128 v[200:203], v169 offset:34816
	ds_read_b128 v[204:207], v169 offset:35840
	ds_read_b128 v[208:211], v169 offset:36864
	ds_read_b128 v[212:215], v169 offset:37888
	ds_read_b128 v[216:219], v169 offset:38912
	ds_read_b128 v[220:223], v169 offset:39936
	global_load_lds_dwordx4 v[234:235], off
	v_lshl_add_u64 v[234:235], s[24:25], 0, v[132:133]
	s_mov_b32 m0, s37
	s_nop 0
	global_load_lds_dwordx4 v[234:235], off
	s_waitcnt vmcnt(8)
	s_waitcnt lgkmcnt(0)
	s_barrier
	s_waitcnt lgkmcnt(0)
	v_mfma_f32_16x16x32_bf16 v[124:127], v[146:149], v[192:195], v[124:127]
	v_mfma_f32_16x16x32_bf16 v[120:123], v[154:157], v[192:195], v[120:123]
	v_mfma_f32_16x16x32_bf16 v[116:119], v[146:149], v[200:203], v[116:119]
	v_mfma_f32_16x16x32_bf16 v[112:115], v[154:157], v[200:203], v[112:115]
	v_mfma_f32_16x16x32_bf16 v[92:95], v[146:149], v[208:211], v[92:95]
	v_mfma_f32_16x16x32_bf16 v[88:91], v[154:157], v[208:211], v[88:91]
	v_mfma_f32_16x16x32_bf16 v[76:79], v[146:149], v[216:219], v[76:79]
	v_mfma_f32_16x16x32_bf16 v[72:75], v[154:157], v[216:219], v[72:75]
	v_mfma_f32_16x16x32_bf16 v[124:127], v[150:153], v[196:199], v[124:127]
	v_mfma_f32_16x16x32_bf16 v[120:123], v[158:161], v[196:199], v[120:123]
	v_mfma_f32_16x16x32_bf16 v[116:119], v[150:153], v[204:207], v[116:119]
	v_mfma_f32_16x16x32_bf16 v[112:115], v[158:161], v[204:207], v[112:115]
	v_mfma_f32_16x16x32_bf16 v[92:95], v[150:153], v[212:215], v[92:95]
	v_mfma_f32_16x16x32_bf16 v[88:91], v[158:161], v[212:215], v[88:91]
	v_mfma_f32_16x16x32_bf16 v[76:79], v[150:153], v[220:223], v[76:79]
	v_mfma_f32_16x16x32_bf16 v[72:75], v[158:161], v[220:223], v[72:75]
	v_mfma_f32_16x16x32_bf16 v[108:111], v[172:175], v[192:195], v[108:111]
	v_mfma_f32_16x16x32_bf16 v[104:107], v[180:183], v[192:195], v[104:107]
	v_mfma_f32_16x16x32_bf16 v[100:103], v[172:175], v[200:203], v[100:103]
	v_mfma_f32_16x16x32_bf16 v[96:99], v[180:183], v[200:203], v[96:99]
	v_mfma_f32_16x16x32_bf16 v[84:87], v[172:175], v[208:211], v[84:87]
	v_mfma_f32_16x16x32_bf16 v[80:83], v[180:183], v[208:211], v[80:83]
	v_mfma_f32_16x16x32_bf16 v[68:71], v[172:175], v[216:219], v[68:71]
	v_mfma_f32_16x16x32_bf16 v[64:67], v[180:183], v[216:219], v[64:67]
	v_mfma_f32_16x16x32_bf16 v[108:111], v[176:179], v[196:199], v[108:111]
	v_mfma_f32_16x16x32_bf16 v[104:107], v[188:191], v[196:199], v[104:107]
	v_mfma_f32_16x16x32_bf16 v[100:103], v[176:179], v[204:207], v[100:103]
	v_mfma_f32_16x16x32_bf16 v[96:99], v[188:191], v[204:207], v[96:99]
	v_mfma_f32_16x16x32_bf16 v[84:87], v[176:179], v[212:215], v[84:87]
	v_mfma_f32_16x16x32_bf16 v[80:83], v[188:191], v[212:215], v[80:83]
	v_mfma_f32_16x16x32_bf16 v[68:71], v[176:179], v[220:223], v[68:71]
	v_mfma_f32_16x16x32_bf16 v[64:67], v[188:191], v[220:223], v[64:67]
	s_barrier
	s_add_i32 s24, s71, s30
	v_lshl_add_u64 v[224:225], v[224:225], 0, s[4:5]
	s_mov_b32 m0, s24
	ds_read_b128 v[192:195], v169 offset:49152
	ds_read_b128 v[196:199], v169 offset:50176
	ds_read_b128 v[200:203], v169 offset:51200
	ds_read_b128 v[204:207], v169 offset:52224
	ds_read_b128 v[208:211], v169 offset:53248
	ds_read_b128 v[212:215], v169 offset:54272
	ds_read_b128 v[216:219], v169 offset:55296
	ds_read_b128 v[220:223], v169 offset:56320
	global_load_lds_dwordx4 v[224:225], off
	s_add_i32 m0, s24, 0x2000
	s_add_u32 s22, s22, 0x40080
	v_lshl_add_u64 v[224:225], v[226:227], 0, s[4:5]
	s_addc_u32 s23, s23, 0
	s_add_i32 s24, s72, s30
	global_load_lds_dwordx4 v[224:225], off
	v_lshl_add_u64 v[224:225], s[22:23], 0, v[130:131]
	s_mov_b32 m0, s24
	s_nop 0
	global_load_lds_dwordx4 v[224:225], off
	v_lshl_add_u64 v[224:225], s[22:23], 0, v[134:135]
	s_add_i32 m0, s24, 0x2000
	s_nop 0
	global_load_lds_dwordx4 v[224:225], off
	v_lshl_add_u64 v[224:225], v[228:229], 0, s[4:5]
	s_mov_b32 m0, s43
	s_nop 0
	global_load_lds_dwordx4 v[224:225], off
	v_lshl_add_u64 v[224:225], v[230:231], 0, s[4:5]
	s_mov_b32 m0, s44
	s_nop 0
	global_load_lds_dwordx4 v[224:225], off
	s_waitcnt vmcnt(8)
	s_waitcnt lgkmcnt(0)
	s_barrier
; __device__ __forceinline__ unsigned cvt_pk_bf16(float lo, float hi) { unsigned r; asm volatile("v_cvt_pk_bf16_f32 %0, %1, %2" : "=v"(r) : "v"(lo), "v"(hi)); return r; }
;     __device__ __forceinline__ void operator()(const f32x4 (&acc)[2][2][4][2], const Unit& u, int wr, int wc, int fr, int fq) const {
;         const int row0 = u.pm * BM + wr * 64 + fr, col0 = u.pn * BM + wc * 32 + 8 * fq;
;         f32x4 cs[2][2];
; #pragma unroll
;         for (int bj = 0; bj < 2; ++bj)
; #pragma unroll
;             for (int n = 0; n < 2; ++n) { const f32x4 q = *(const f32x4*)(ssq + col0 + bj * HALF + 4 * n);
; #pragma unroll
;                 for (int e = 0; e < 4; ++e) cs[bj][n][e] = __builtin_amdgcn_rsqf(q[e] * (1.0f / 1024.0f) + 1e-6f); }
; #pragma unroll
;         for (int ai = 0; ai < 2; ++ai)
; #pragma unroll
;             for (int m = 0; m < 4; ++m) { const int row = row0 + ai * HALF + m * 16, h = row >> 6, d = row & 63, dt = d >> 5, r = d & 31;
; #pragma unroll
;                 for (int bj = 0; bj < 2; ++bj) { const int col = col0 + bj * HALF, b = col >> 12, tl = col & 4095, kt = tl >> 5, k0 = tl & 31, s = k0 >> 4, half = (k0 >> 3) & 1, bh = b * 16 + h;
;                     const f32x4 v0 = acc[ai][bj][m][0] * cs[bj][0], v1 = acc[ai][bj][m][1] * cs[bj][1];
;                     bf16_t* p = VF + (((size_t)((((bh * 128 + kt) * 2 + dt) * 2 + s) * 64 + r)) << 3) + 4 * half;
;                     *(unsigned long long*)p = (unsigned long long)cvt_pk_bf16(v0[0], v0[1]) | ((unsigned long long)cvt_pk_bf16(v0[2], v0[3]) << 32);
;                     *(unsigned long long*)(p + 256) = (unsigned long long)cvt_pk_bf16(v1[0], v1[1]) | ((unsigned long long)cvt_pk_bf16(v1[2], v1[3]) << 32); }
	s_waitcnt lgkmcnt(0)
	v_mfma_f32_16x16x32_bf16 v[60:63], v[146:149], v[192:195], v[60:63]
	v_mfma_f32_16x16x32_bf16 v[56:59], v[154:157], v[192:195], v[56:59]
	v_mfma_f32_16x16x32_bf16 v[44:47], v[146:149], v[200:203], v[44:47]
	v_mfma_f32_16x16x32_bf16 v[40:43], v[154:157], v[200:203], v[40:43]
	v_mfma_f32_16x16x32_bf16 v[28:31], v[146:149], v[208:211], v[28:31]
	v_mfma_f32_16x16x32_bf16 v[24:27], v[154:157], v[208:211], v[24:27]
	v_mfma_f32_16x16x32_bf16 v[12:15], v[146:149], v[216:219], v[12:15]
	v_mfma_f32_16x16x32_bf16 v[8:11], v[154:157], v[216:219], v[8:11]
	v_mfma_f32_16x16x32_bf16 v[60:63], v[150:153], v[196:199], v[60:63]
	v_mfma_f32_16x16x32_bf16 v[56:59], v[158:161], v[196:199], v[56:59]
	v_mfma_f32_16x16x32_bf16 v[44:47], v[150:153], v[204:207], v[44:47]
	v_mfma_f32_16x16x32_bf16 v[40:43], v[158:161], v[204:207], v[40:43]
	v_mfma_f32_16x16x32_bf16 v[28:31], v[150:153], v[212:215], v[28:31]
	v_mfma_f32_16x16x32_bf16 v[24:27], v[158:161], v[212:215], v[24:27]
	v_mfma_f32_16x16x32_bf16 v[12:15], v[150:153], v[220:223], v[12:15]
	v_mfma_f32_16x16x32_bf16 v[8:11], v[158:161], v[220:223], v[8:11]
	v_mfma_f32_16x16x32_bf16 v[52:55], v[172:175], v[192:195], v[52:55]
	v_mfma_f32_16x16x32_bf16 v[48:51], v[180:183], v[192:195], v[48:51]
	v_mfma_f32_16x16x32_bf16 v[36:39], v[172:175], v[200:203], v[36:39]
	v_mfma_f32_16x16x32_bf16 v[32:35], v[180:183], v[200:203], v[32:35]
	v_mfma_f32_16x16x32_bf16 v[20:23], v[172:175], v[208:211], v[20:23]
	v_mfma_f32_16x16x32_bf16 v[16:19], v[180:183], v[208:211], v[16:19]
	v_mfma_f32_16x16x32_bf16 v[4:7], v[172:175], v[216:219], v[4:7]
	v_mfma_f32_16x16x32_bf16 v[0:3], v[180:183], v[216:219], v[0:3]
	v_mfma_f32_16x16x32_bf16 v[52:55], v[176:179], v[196:199], v[52:55]
	v_mfma_f32_16x16x32_bf16 v[48:51], v[188:191], v[196:199], v[48:51]
	v_mfma_f32_16x16x32_bf16 v[36:39], v[176:179], v[204:207], v[36:39]
	v_mfma_f32_16x16x32_bf16 v[32:35], v[188:191], v[204:207], v[32:35]
	v_mfma_f32_16x16x32_bf16 v[20:23], v[176:179], v[212:215], v[20:23]
	v_mfma_f32_16x16x32_bf16 v[16:19], v[188:191], v[212:215], v[16:19]
	v_mfma_f32_16x16x32_bf16 v[4:7], v[176:179], v[220:223], v[4:7]
	v_mfma_f32_16x16x32_bf16 v[0:3], v[188:191], v[220:223], v[0:3]
	s_barrier
	s_add_i32 s70, s70, 2
	s_add_u32 s20, s20, 0x100
	s_addc_u32 s21, s21, 0
	s_add_u32 s58, s58, 0x100
	s_addc_u32 s69, s69, 0
	s_cmp_gt_u32 s70, 13
	s_cbranch_scc0 .LBB0_576
	s_setprio 0
	s_lshl_b32 s11, s49, 8
	s_or_b32 s11, s11, s42
	v_or_b32_e32 v146, s11, v163
	v_ashrrev_i32_e32 v147, 31, v146
	v_lshl_add_u64 v[158:159], v[146:147], 2, s[8:9]
	global_load_dwordx4 v[146:149], v[158:159], off
	global_load_dwordx4 v[150:153], v[158:159], off offset:16
	global_load_dwordx4 v[154:157], v[158:159], off offset:512
	s_nop 0
	global_load_dwordx4 v[158:161], v[158:159], off offset:528
	s_lshl_b32 s20, s18, 8
	s_add_i32 s20, s20, s39
	s_and_b32 s18, s49, 0x7ffff0
	s_lshr_b32 s13, s20, 6
	s_lshr_b32 s11, s11, 3
	s_add_i32 s13, s13, s18
	s_and_b32 s11, s11, 0x1ec
	v_lshl_or_b32 v171, s13, 9, v165
	s_or_b32 s13, s11, 16
	v_or_b32_e32 v172, s11, v171
	v_or_b32_e32 v173, s13, v171
	v_lshlrev_b32_e32 v175, 6, v172
	v_lshlrev_b32_e32 v173, 6, v173
	v_or_b32_e32 v172, v175, v162
	v_or_b32_e32 v174, v173, v162
	v_or_b32_e32 v176, v175, v166
	v_or_b32_e32 v178, v173, v166
	v_ashrrev_i32_e32 v173, 31, v172
	v_ashrrev_i32_e32 v175, 31, v174
	v_lshl_add_u64 v[172:173], v[172:173], 4, v[136:137]
	v_lshl_add_u64 v[174:175], v[174:175], 4, v[136:137]
	v_ashrrev_i32_e32 v177, 31, v176
	v_lshl_add_u64 v[176:177], v[176:177], 4, v[136:137]
	s_addk_i32 s20, 0x80
	s_lshr_b32 s20, s20, 6
	s_add_i32 s20, s20, s18
	s_and_b64 vcc, exec, s[2:3]
	s_mov_b32 s49, s10
	s_mov_b32 s18, s12
	s_mov_b64 s[22:23], s[16:17]
	s_waitcnt vmcnt(0)
	v_fmamk_f32 v146, v146, 0x3a800000, v170
	v_fmamk_f32 v147, v147, 0x3a800000, v170
	v_fmamk_f32 v148, v148, 0x3a800000, v170
	v_fmamk_f32 v149, v149, 0x3a800000, v170
	v_fmamk_f32 v150, v150, 0x3a800000, v170
	v_fmamk_f32 v151, v151, 0x3a800000, v170
	v_fmamk_f32 v179, v154, 0x3a800000, v170
	v_fmamk_f32 v180, v155, 0x3a800000, v170
	v_fmamk_f32 v183, v158, 0x3a800000, v170
	v_fmamk_f32 v185, v159, 0x3a800000, v170
	v_fmamk_f32 v152, v152, 0x3a800000, v170
	v_fmamk_f32 v153, v153, 0x3a800000, v170
	v_fmamk_f32 v181, v156, 0x3a800000, v170
	v_fmamk_f32 v182, v157, 0x3a800000, v170
	v_fmamk_f32 v187, v160, 0x3a800000, v170
	v_fmamk_f32 v188, v161, 0x3a800000, v170
	v_rsq_f32_e32 v156, v146
	v_rsq_f32_e32 v157, v147
	v_rsq_f32_e32 v160, v148
	v_rsq_f32_e32 v161, v149
	v_rsq_f32_e32 v154, v150
	v_rsq_f32_e32 v155, v151
	v_rsq_f32_e32 v148, v179
	v_rsq_f32_e32 v149, v180
	v_rsq_f32_e32 v146, v183
	v_rsq_f32_e32 v147, v185
	v_rsq_f32_e32 v158, v152
	v_rsq_f32_e32 v159, v153
	v_rsq_f32_e32 v152, v181
	v_rsq_f32_e32 v153, v182
	v_rsq_f32_e32 v150, v187
	v_rsq_f32_e32 v151, v188
	v_pk_mul_f32 v[124:125], v[124:125], v[156:157]
	v_pk_mul_f32 v[120:121], v[120:121], v[154:155]
	v_pk_mul_f32 v[108:109], v[108:109], v[148:149]
	v_pk_mul_f32 v[104:105], v[104:105], v[146:147]
	v_pk_mul_f32 v[126:127], v[126:127], v[160:161]
	v_pk_mul_f32 v[122:123], v[122:123], v[158:159]
	v_pk_mul_f32 v[110:111], v[110:111], v[152:153]
	v_pk_mul_f32 v[106:107], v[106:107], v[150:151]
	v_cvt_pk_bf16_f32 v124, v124, v125
	v_cvt_pk_bf16_f32 v125, v126, v127
	global_store_dwordx2 v[172:173], v[124:125], off
	v_cvt_pk_bf16_f32 v120, v120, v121
	v_cvt_pk_bf16_f32 v121, v122, v123
	global_store_dwordx2 v[172:173], v[120:121], off offset:512
	v_cvt_pk_bf16_f32 v108, v108, v109
	v_cvt_pk_bf16_f32 v109, v110, v111
	global_store_dwordx2 v[174:175], v[108:109], off
	v_cvt_pk_bf16_f32 v104, v104, v105
; __device__ __forceinline__ unsigned cvt_pk_bf16(float lo, float hi) { unsigned r; asm volatile("v_cvt_pk_bf16_f32 %0, %1, %2" : "=v"(r) : "v"(lo), "v"(hi)); return r; }
;     __device__ __forceinline__ void operator()(const f32x4 (&acc)[2][2][4][2], const Unit& u, int wr, int wc, int fr, int fq) const {
;     ...
;             for (int m = 0; m < 4; ++m) { const int row = row0 + ai * HALF + m * 16, h = row >> 6, d = row & 63, dt = d >> 5, r = d & 31;
; #pragma unroll
;                 for (int bj = 0; bj < 2; ++bj) { const int col = col0 + bj * HALF, b = col >> 12, tl = col & 4095, kt = tl >> 5, k0 = tl & 31, s = k0 >> 4, half = (k0 >> 3) & 1, bh = b * 16 + h;
;                     const f32x4 v0 = acc[ai][bj][m][0] * cs[bj][0], v1 = acc[ai][bj][m][1] * cs[bj][1];
;                     bf16_t* p = VF + (((size_t)((((bh * 128 + kt) * 2 + dt) * 2 + s) * 64 + r)) << 3) + 4 * half;
;                     *(unsigned long long*)p = (unsigned long long)cvt_pk_bf16(v0[0], v0[1]) | ((unsigned long long)cvt_pk_bf16(v0[2], v0[3]) << 32);
;                     *(unsigned long long*)(p + 256) = (unsigned long long)cvt_pk_bf16(v1[0], v1[1]) | ((unsigned long long)cvt_pk_bf16(v1[2], v1[3]) << 32); }
	v_cvt_pk_bf16_f32 v105, v106, v107
	global_store_dwordx2 v[174:175], v[104:105], off offset:512
	v_pk_mul_f32 v[118:119], v[118:119], v[160:161]
	v_pk_mul_f32 v[116:117], v[116:117], v[156:157]
	v_pk_mul_f32 v[114:115], v[114:115], v[158:159]
	v_cvt_pk_bf16_f32 v104, v116, v117
	v_cvt_pk_bf16_f32 v105, v118, v119
	v_pk_mul_f32 v[112:113], v[112:113], v[154:155]
	global_store_dwordx2 v[176:177], v[104:105], off
	v_cvt_pk_bf16_f32 v104, v112, v113
	v_cvt_pk_bf16_f32 v105, v114, v115
	v_ashrrev_i32_e32 v179, 31, v178
	v_pk_mul_f32 v[100:101], v[100:101], v[148:149]
	v_pk_mul_f32 v[98:99], v[98:99], v[150:151]
	v_pk_mul_f32 v[96:97], v[96:97], v[146:147]
	global_store_dwordx2 v[176:177], v[104:105], off offset:512
	v_lshl_add_u64 v[104:105], v[178:179], 4, v[136:137]
	v_pk_mul_f32 v[102:103], v[102:103], v[152:153]
	v_cvt_pk_bf16_f32 v100, v100, v101
	v_pk_mul_f32 v[92:93], v[92:93], v[156:157]
	v_cvt_pk_bf16_f32 v101, v102, v103
	global_store_dwordx2 v[104:105], v[100:101], off
	v_cvt_pk_bf16_f32 v96, v96, v97
	v_cvt_pk_bf16_f32 v97, v98, v99
	v_or_b32_e32 v98, 2, v171
	global_store_dwordx2 v[104:105], v[96:97], off offset:512
	v_or_b32_e32 v96, s11, v98
	v_lshlrev_b32_e32 v99, 6, v96
	v_or_b32_e32 v96, v99, v162
	v_ashrrev_i32_e32 v97, 31, v96
	v_pk_mul_f32 v[88:89], v[88:89], v[154:155]
	v_lshl_add_u64 v[96:97], v[96:97], 4, v[136:137]
	v_pk_mul_f32 v[94:95], v[94:95], v[160:161]
	v_cvt_pk_bf16_f32 v92, v92, v93
	v_pk_mul_f32 v[90:91], v[90:91], v[158:159]
	v_cvt_pk_bf16_f32 v93, v94, v95
	global_store_dwordx2 v[96:97], v[92:93], off
	v_cvt_pk_bf16_f32 v88, v88, v89
	v_cvt_pk_bf16_f32 v89, v90, v91
	global_store_dwordx2 v[96:97], v[88:89], off offset:512
	v_or_b32_e32 v88, s13, v98
	v_lshlrev_b32_e32 v90, 6, v88
	v_or_b32_e32 v88, v90, v162
	v_ashrrev_i32_e32 v89, 31, v88
	v_pk_mul_f32 v[84:85], v[84:85], v[148:149]
	v_pk_mul_f32 v[80:81], v[80:81], v[146:147]
	v_lshl_add_u64 v[88:89], v[88:89], 4, v[136:137]
	v_pk_mul_f32 v[86:87], v[86:87], v[152:153]
	v_cvt_pk_bf16_f32 v84, v84, v85
	v_pk_mul_f32 v[82:83], v[82:83], v[150:151]
	v_cvt_pk_bf16_f32 v85, v86, v87
	global_store_dwordx2 v[88:89], v[84:85], off
	v_cvt_pk_bf16_f32 v80, v80, v81
	v_cvt_pk_bf16_f32 v81, v82, v83
	global_store_dwordx2 v[88:89], v[80:81], off offset:512
	v_or_b32_e32 v80, v99, v166
	v_ashrrev_i32_e32 v81, 31, v80
	v_pk_mul_f32 v[76:77], v[76:77], v[156:157]
	v_pk_mul_f32 v[72:73], v[72:73], v[154:155]
	v_lshl_add_u64 v[80:81], v[80:81], 4, v[136:137]
	v_pk_mul_f32 v[78:79], v[78:79], v[160:161]
	v_cvt_pk_bf16_f32 v76, v76, v77
	v_pk_mul_f32 v[74:75], v[74:75], v[158:159]
	v_cvt_pk_bf16_f32 v77, v78, v79
	global_store_dwordx2 v[80:81], v[76:77], off
	v_cvt_pk_bf16_f32 v72, v72, v73
	v_cvt_pk_bf16_f32 v73, v74, v75
	global_store_dwordx2 v[80:81], v[72:73], off offset:512
	v_or_b32_e32 v72, v90, v166
	v_ashrrev_i32_e32 v73, 31, v72
	v_pk_mul_f32 v[68:69], v[68:69], v[148:149]
	v_pk_mul_f32 v[66:67], v[66:67], v[150:151]
	v_pk_mul_f32 v[64:65], v[64:65], v[146:147]
	v_lshl_add_u64 v[72:73], v[72:73], 4, v[136:137]
	v_pk_mul_f32 v[70:71], v[70:71], v[152:153]
	v_cvt_pk_bf16_f32 v68, v68, v69
	v_pk_mul_f32 v[60:61], v[60:61], v[156:157]
	v_cvt_pk_bf16_f32 v69, v70, v71
	global_store_dwordx2 v[72:73], v[68:69], off
	v_cvt_pk_bf16_f32 v64, v64, v65
	v_cvt_pk_bf16_f32 v65, v66, v67
	v_lshl_or_b32 v66, s20, 9, v165
	global_store_dwordx2 v[72:73], v[64:65], off offset:512
	v_or_b32_e32 v64, s11, v66
	v_lshlrev_b32_e32 v67, 6, v64
	v_or_b32_e32 v64, v67, v162
	v_ashrrev_i32_e32 v65, 31, v64
	v_pk_mul_f32 v[56:57], v[56:57], v[154:155]
	v_lshl_add_u64 v[64:65], v[64:65], 4, v[136:137]
	v_pk_mul_f32 v[62:63], v[62:63], v[160:161]
	v_cvt_pk_bf16_f32 v60, v60, v61
	v_pk_mul_f32 v[58:59], v[58:59], v[158:159]
	v_cvt_pk_bf16_f32 v61, v62, v63
	global_store_dwordx2 v[64:65], v[60:61], off
	v_cvt_pk_bf16_f32 v56, v56, v57
	v_cvt_pk_bf16_f32 v57, v58, v59
	global_store_dwordx2 v[64:65], v[56:57], off offset:512
	v_or_b32_e32 v56, s13, v66
; __device__ __forceinline__ unsigned cvt_pk_bf16(float lo, float hi) { unsigned r; asm volatile("v_cvt_pk_bf16_f32 %0, %1, %2" : "=v"(r) : "v"(lo), "v"(hi)); return r; }
; #define PG8_WAIT_V(n) asm volatile("s_waitcnt vmcnt(" #n ")" ::: "memory")
; #define PG8_BAR __builtin_amdgcn_s_barrier()
;     __device__ __forceinline__ void operator()(const f32x4 (&acc)[2][2][4][2], const Unit& u, int wr, int wc, int fr, int fq) const {
;     ...
;             for (int m = 0; m < 4; ++m) { const int row = row0 + ai * HALF + m * 16, h = row >> 6, d = row & 63, dt = d >> 5, r = d & 31;
; #pragma unroll
;                 for (int bj = 0; bj < 2; ++bj) { const int col = col0 + bj * HALF, b = col >> 12, tl = col & 4095, kt = tl >> 5, k0 = tl & 31, s = k0 >> 4, half = (k0 >> 3) & 1, bh = b * 16 + h;
;                     const f32x4 v0 = acc[ai][bj][m][0] * cs[bj][0], v1 = acc[ai][bj][m][1] * cs[bj][1];
;                     bf16_t* p = VF + (((size_t)((((bh * 128 + kt) * 2 + dt) * 2 + s) * 64 + r)) << 3) + 4 * half;
;                     *(unsigned long long*)p = (unsigned long long)cvt_pk_bf16(v0[0], v0[1]) | ((unsigned long long)cvt_pk_bf16(v0[2], v0[3]) << 32);
;                     *(unsigned long long*)(p + 256) = (unsigned long long)cvt_pk_bf16(v1[0], v1[1]) | ((unsigned long long)cvt_pk_bf16(v1[2], v1[3]) << 32); }
; template <class Epi, class Sched, bool ALIGN_EPI = false, bool SP2 = false>
; __device__ __forceinline__ void gemm_phase(PG8_LAS unsigned char* lds, const Gemm g, const Sched& S, const Epi& E) {
;     ...
;     PG8_WAIT_V(0);
;     if constexpr (!ALIGN_EPI) { if (wr == 0) PG8_BAR; }
	v_lshlrev_b32_e32 v58, 6, v56
	v_or_b32_e32 v56, v58, v162
	v_ashrrev_i32_e32 v57, 31, v56
	v_pk_mul_f32 v[52:53], v[52:53], v[148:149]
	v_pk_mul_f32 v[48:49], v[48:49], v[146:147]
	v_lshl_add_u64 v[56:57], v[56:57], 4, v[136:137]
	v_pk_mul_f32 v[54:55], v[54:55], v[152:153]
	v_cvt_pk_bf16_f32 v52, v52, v53
	v_pk_mul_f32 v[50:51], v[50:51], v[150:151]
	v_cvt_pk_bf16_f32 v53, v54, v55
	global_store_dwordx2 v[56:57], v[52:53], off
	v_cvt_pk_bf16_f32 v48, v48, v49
	v_cvt_pk_bf16_f32 v49, v50, v51
	global_store_dwordx2 v[56:57], v[48:49], off offset:512
	v_or_b32_e32 v48, v67, v166
	v_ashrrev_i32_e32 v49, 31, v48
	v_pk_mul_f32 v[44:45], v[44:45], v[156:157]
	v_pk_mul_f32 v[40:41], v[40:41], v[154:155]
	v_lshl_add_u64 v[48:49], v[48:49], 4, v[136:137]
	v_pk_mul_f32 v[46:47], v[46:47], v[160:161]
	v_cvt_pk_bf16_f32 v44, v44, v45
	v_pk_mul_f32 v[42:43], v[42:43], v[158:159]
	v_cvt_pk_bf16_f32 v45, v46, v47
	global_store_dwordx2 v[48:49], v[44:45], off
	v_cvt_pk_bf16_f32 v40, v40, v41
	v_cvt_pk_bf16_f32 v41, v42, v43
	global_store_dwordx2 v[48:49], v[40:41], off offset:512
	v_or_b32_e32 v40, v58, v166
	v_ashrrev_i32_e32 v41, 31, v40
	v_pk_mul_f32 v[36:37], v[36:37], v[148:149]
	v_pk_mul_f32 v[34:35], v[34:35], v[150:151]
	v_pk_mul_f32 v[32:33], v[32:33], v[146:147]
	v_lshl_add_u64 v[40:41], v[40:41], 4, v[136:137]
	v_pk_mul_f32 v[38:39], v[38:39], v[152:153]
	v_cvt_pk_bf16_f32 v36, v36, v37
	v_pk_mul_f32 v[28:29], v[28:29], v[156:157]
	v_cvt_pk_bf16_f32 v37, v38, v39
	global_store_dwordx2 v[40:41], v[36:37], off
	v_cvt_pk_bf16_f32 v32, v32, v33
	v_cvt_pk_bf16_f32 v33, v34, v35
	v_or_b32_e32 v34, 2, v66
	global_store_dwordx2 v[40:41], v[32:33], off offset:512
	v_or_b32_e32 v32, s11, v34
	v_lshlrev_b32_e32 v35, 6, v32
	v_or_b32_e32 v32, v35, v162
	v_ashrrev_i32_e32 v33, 31, v32
	v_pk_mul_f32 v[24:25], v[24:25], v[154:155]
	v_lshl_add_u64 v[32:33], v[32:33], 4, v[136:137]
	v_pk_mul_f32 v[30:31], v[30:31], v[160:161]
	v_cvt_pk_bf16_f32 v28, v28, v29
	v_pk_mul_f32 v[26:27], v[26:27], v[158:159]
	v_cvt_pk_bf16_f32 v29, v30, v31
	global_store_dwordx2 v[32:33], v[28:29], off
	v_cvt_pk_bf16_f32 v24, v24, v25
	v_cvt_pk_bf16_f32 v25, v26, v27
	global_store_dwordx2 v[32:33], v[24:25], off offset:512
	v_or_b32_e32 v24, s13, v34
	v_lshlrev_b32_e32 v26, 6, v24
	v_or_b32_e32 v24, v26, v162
	v_ashrrev_i32_e32 v25, 31, v24
	v_pk_mul_f32 v[20:21], v[20:21], v[148:149]
	v_pk_mul_f32 v[16:17], v[16:17], v[146:147]
	v_lshl_add_u64 v[24:25], v[24:25], 4, v[136:137]
	v_pk_mul_f32 v[22:23], v[22:23], v[152:153]
	v_cvt_pk_bf16_f32 v20, v20, v21
	v_pk_mul_f32 v[18:19], v[18:19], v[150:151]
	v_cvt_pk_bf16_f32 v21, v22, v23
	global_store_dwordx2 v[24:25], v[20:21], off
	v_cvt_pk_bf16_f32 v16, v16, v17
	v_cvt_pk_bf16_f32 v17, v18, v19
	global_store_dwordx2 v[24:25], v[16:17], off offset:512
	v_or_b32_e32 v16, v35, v166
	v_ashrrev_i32_e32 v17, 31, v16
	v_pk_mul_f32 v[12:13], v[12:13], v[156:157]
	v_pk_mul_f32 v[8:9], v[8:9], v[154:155]
	v_lshl_add_u64 v[16:17], v[16:17], 4, v[136:137]
	v_pk_mul_f32 v[14:15], v[14:15], v[160:161]
	v_cvt_pk_bf16_f32 v12, v12, v13
	v_pk_mul_f32 v[10:11], v[10:11], v[158:159]
	v_cvt_pk_bf16_f32 v13, v14, v15
	global_store_dwordx2 v[16:17], v[12:13], off
	v_cvt_pk_bf16_f32 v8, v8, v9
	v_cvt_pk_bf16_f32 v9, v10, v11
	global_store_dwordx2 v[16:17], v[8:9], off offset:512
	v_or_b32_e32 v8, v26, v166
	v_ashrrev_i32_e32 v9, 31, v8
	v_pk_mul_f32 v[4:5], v[4:5], v[148:149]
	v_pk_mul_f32 v[0:1], v[0:1], v[146:147]
	v_lshl_add_u64 v[8:9], v[8:9], 4, v[136:137]
	v_pk_mul_f32 v[6:7], v[6:7], v[152:153]
	v_pk_mul_f32 v[2:3], v[2:3], v[150:151]
	v_cvt_pk_bf16_f32 v4, v4, v5
	v_cvt_pk_bf16_f32 v5, v6, v7
	global_store_dwordx2 v[8:9], v[4:5], off
	v_cvt_pk_bf16_f32 v0, v0, v1
	v_cvt_pk_bf16_f32 v1, v2, v3
	global_store_dwordx2 v[8:9], v[0:1], off offset:512
	s_mov_b64 s[20:21], s[14:15]
	s_cbranch_vccz .LBB0_569
	s_waitcnt vmcnt(0)
	s_cmpk_gt_u32 s26, 0xff
	s_cbranch_scc1 .LBB0_580
	s_barrier

; #define PG8_STAGE(bufoff, gbase, voff) do { _Pragma("unroll") for (int _i = 0; _i < 2; ++_i) \
;         __builtin_amdgcn_global_load_lds((const unsigned*)((const char*)(gbase) + (voff)[_i]), (PG8_LAS unsigned*)(lds + (bufoff) + ldsw + _i * 8192), 16, 0, 0); } while (0)
; #define PG8_LDA(dst, b, h) do { _Pragma("unroll") for (int m = 0; m < 4; ++m) _Pragma("unroll") for (int k = 0; k < 2; ++k) dst[m][k] = *(const PG8_LAS bf16x8*)(lds + PG8_SA(b, h) + aoff + m * 2048 + k * 1024); } while (0)
; #define PG8_LDB(dst, b, h) do { _Pragma("unroll") for (int n = 0; n < 2; ++n) _Pragma("unroll") for (int k = 0; k < 2; ++k) dst[n][k] = *(const PG8_LAS bf16x8*)(lds + PG8_SB(b, h) + boff + n * 2048 + k * 1024); } while (0)
; #define PG8_MMA(ai, bj, At, Bt) do { __builtin_amdgcn_s_setprio(1); _Pragma("unroll") for (int m = 0; m < 4; ++m) _Pragma("unroll") for (int n = 0; n < 2; ++n) _Pragma("unroll") for (int k = 0; k < 2; ++k) \
;         acc[ai][bj][m][n] = __builtin_amdgcn_mfma_f32_16x16x32_bf16(Bt[n][k], At[m][k], acc[ai][bj][m][n], 0, 0, 0); __builtin_amdgcn_s_setprio(0); } while (0)
; #define PG8_WAIT_V(n) asm volatile("s_waitcnt vmcnt(" #n ")" ::: "memory")
; #define PG8_WAIT_L(n) asm volatile("s_waitcnt lgkmcnt(" #n ")" ::: "memory")
; #define PG8_BAR __builtin_amdgcn_s_barrier()
; #define PG8_SCHED __builtin_amdgcn_sched_barrier(0)
; template <class Epi, class Sched, bool ALIGN_EPI = false, bool SP2 = false>
; __device__ __forceinline__ void gemm_phase(PG8_LAS unsigned char* lds, const Gemm g, const Sched& S, const Epi& E) {
;     ...
;             PG8_LDB(B0, 0, 0); PG8_LDB(B1, 0, 1); PG8_SCHED; PG8_LDA(At, 0, 0); PG8_STAGE(PG8_SA(1, 1), a1 + hstep, voffA);
;             PG8_WAIT_V(8); PG8_WAIT_L(0); PG8_BAR; PG8_MMA(0, 0, At, B0); PG8_MMA(0, 1, At, B1); PG8_BAR; PG8_SCHED;
;     ...
; #pragma unroll
;         for (int a = 0; a < 2; ++a)
; #pragma unroll
;             for (int b = 0; b < 2; ++b)
; #pragma unroll
;                 for (int m = 0; m < 4; ++m)
; #pragma unroll
;                     for (int n = 0; n < 2; ++n) acc[a][b][m][n] = (f32x4){0.f, 0.f, 0.f, 0.f};
.LBB0_715:
	s_ashr_i32 s15, s14, 31
	v_cmp_lt_i64_e32 vcc, s[16:17], v[136:137]
	s_lshl_b64 s[16:17], s[14:15], 19
	s_add_u32 s16, s30, s16
	s_addc_u32 s17, s31, s17
	s_and_b64 s[18:19], vcc, exec
	s_cselect_b32 s15, s17, s25
	s_cselect_b32 s21, s16, s24
	s_ashr_i32 s13, s12, 31
	s_lshl_b64 s[18:19], s[12:13], 19
	s_add_u32 s18, s34, s18
	s_addc_u32 s19, s35, s19
	s_and_b64 s[28:29], vcc, exec
	s_cselect_b32 s13, s19, s27
	s_cselect_b32 s51, s18, s26
	s_add_u32 s24, s24, 0x40080
	s_addc_u32 s25, s25, 0
	s_add_u32 s56, s26, 0x100
	v_mov_b32_e32 v0, 0
	s_addc_u32 s57, s27, 0
	s_mov_b32 s58, -2
	s_waitcnt lgkmcnt(0)
	v_mov_b32_e32 v1, v0
	v_mov_b32_e32 v2, v0
	v_mov_b32_e32 v3, v0
	v_mov_b32_e32 v4, v0
	v_mov_b32_e32 v5, v0
	v_mov_b32_e32 v6, v0
	v_mov_b32_e32 v7, v0
	v_mov_b32_e32 v16, v0
	v_mov_b32_e32 v17, v0
	v_mov_b32_e32 v18, v0
	v_mov_b32_e32 v19, v0
	v_mov_b32_e32 v20, v0
	v_mov_b32_e32 v21, v0
	v_mov_b32_e32 v22, v0
	v_mov_b32_e32 v23, v0
	v_mov_b32_e32 v32, v0
	v_mov_b32_e32 v33, v0
	v_mov_b32_e32 v34, v0
	v_mov_b32_e32 v35, v0
	v_mov_b32_e32 v36, v0
	v_mov_b32_e32 v37, v0
	v_mov_b32_e32 v38, v0
	v_mov_b32_e32 v39, v0
	v_mov_b32_e32 v48, v0
	v_mov_b32_e32 v49, v0
	v_mov_b32_e32 v50, v0
	v_mov_b32_e32 v51, v0
	v_mov_b32_e32 v52, v0
	v_mov_b32_e32 v53, v0
	v_mov_b32_e32 v54, v0
	v_mov_b32_e32 v55, v0
	v_mov_b32_e32 v8, v0
	v_mov_b32_e32 v9, v0
	v_mov_b32_e32 v10, v0
	v_mov_b32_e32 v11, v0
	v_mov_b32_e32 v12, v0
	v_mov_b32_e32 v13, v0
	v_mov_b32_e32 v14, v0
	v_mov_b32_e32 v15, v0
	v_mov_b32_e32 v24, v0
	v_mov_b32_e32 v25, v0
	v_mov_b32_e32 v26, v0
	v_mov_b32_e32 v27, v0
	v_mov_b32_e32 v28, v0
	v_mov_b32_e32 v29, v0
	v_mov_b32_e32 v30, v0
	v_mov_b32_e32 v31, v0
	v_mov_b32_e32 v40, v0
	v_mov_b32_e32 v41, v0
	v_mov_b32_e32 v42, v0
	v_mov_b32_e32 v43, v0
	v_mov_b32_e32 v44, v0
	v_mov_b32_e32 v45, v0
	v_mov_b32_e32 v46, v0
	v_mov_b32_e32 v47, v0
	v_mov_b32_e32 v56, v0
	v_mov_b32_e32 v57, v0
	v_mov_b32_e32 v58, v0
	v_mov_b32_e32 v59, v0
	v_mov_b32_e32 v60, v0
	v_mov_b32_e32 v61, v0
	v_mov_b32_e32 v62, v0
	v_mov_b32_e32 v63, v0
	v_mov_b32_e32 v64, v0
	v_mov_b32_e32 v65, v0
	v_mov_b32_e32 v66, v0
	v_mov_b32_e32 v67, v0
	v_mov_b32_e32 v68, v0
	v_mov_b32_e32 v69, v0
	v_mov_b32_e32 v70, v0
	v_mov_b32_e32 v71, v0
	v_mov_b32_e32 v80, v0
	v_mov_b32_e32 v81, v0
	v_mov_b32_e32 v82, v0
	v_mov_b32_e32 v83, v0
	v_mov_b32_e32 v84, v0
	v_mov_b32_e32 v85, v0
	v_mov_b32_e32 v86, v0
	v_mov_b32_e32 v87, v0
	v_mov_b32_e32 v96, v0
	v_mov_b32_e32 v97, v0
	v_mov_b32_e32 v98, v0
	v_mov_b32_e32 v99, v0
	v_mov_b32_e32 v100, v0
	v_mov_b32_e32 v101, v0
	v_mov_b32_e32 v102, v0
	v_mov_b32_e32 v103, v0
	v_mov_b32_e32 v112, v0
	v_mov_b32_e32 v113, v0
	v_mov_b32_e32 v114, v0
	v_mov_b32_e32 v115, v0
	v_mov_b32_e32 v116, v0
	v_mov_b32_e32 v117, v0
	v_mov_b32_e32 v118, v0
	v_mov_b32_e32 v119, v0
	v_mov_b32_e32 v72, v0
	v_mov_b32_e32 v73, v0
	v_mov_b32_e32 v74, v0
	v_mov_b32_e32 v75, v0
	v_mov_b32_e32 v76, v0
	v_mov_b32_e32 v77, v0
	v_mov_b32_e32 v78, v0
	v_mov_b32_e32 v79, v0
	v_mov_b32_e32 v88, v0
	v_mov_b32_e32 v89, v0
	v_mov_b32_e32 v90, v0
	v_mov_b32_e32 v91, v0
	v_mov_b32_e32 v92, v0
	v_mov_b32_e32 v93, v0
	v_mov_b32_e32 v94, v0
	v_mov_b32_e32 v95, v0
	v_mov_b32_e32 v104, v0
	v_mov_b32_e32 v105, v0
	v_mov_b32_e32 v106, v0
	v_mov_b32_e32 v107, v0
	v_mov_b32_e32 v108, v0
	v_mov_b32_e32 v109, v0
	v_mov_b32_e32 v110, v0
	v_mov_b32_e32 v111, v0
	v_mov_b32_e32 v120, v0
	v_mov_b32_e32 v121, v0
	v_mov_b32_e32 v122, v0
	v_mov_b32_e32 v123, v0
	v_mov_b32_e32 v124, v0
	v_mov_b32_e32 v125, v0
	v_mov_b32_e32 v126, v0
	v_mov_b32_e32 v127, v0
	s_bitcmp1_b32 s60, 2
	s_cbranch_scc0 .Lgprio_4
	s_setprio 1
.Lgprio_4:
.LBB0_716:
	ds_read_b128 v[140:143], v223
	ds_read_b128 v[144:147], v223 offset:1024
	ds_read_b128 v[148:151], v223 offset:2048
	ds_read_b128 v[152:155], v223 offset:3072
	ds_read_b128 v[156:159], v224
	ds_read_b128 v[160:163], v224 offset:1024
	ds_read_b128 v[164:167], v224 offset:2048
	ds_read_b128 v[168:171], v224 offset:3072
	s_add_u32 s26, s24, 0xfffc0080
	s_addc_u32 s27, s25, -1
	s_cmp_eq_u32 s58, 12
	s_cselect_b32 s29, s15, s27
	s_cselect_b32 s28, s21, s26
	s_cselect_b32 s27, s13, s57
	s_cselect_b32 s26, s51, s56
	v_lshl_add_u64 v[206:207], s[24:25], 0, v[132:133]
	s_add_i32 m0, s23, 0xc000
	ds_read_b128 v[172:175], v225
	ds_read_b128 v[176:179], v225 offset:1024
	ds_read_b128 v[180:183], v225 offset:2048
	ds_read_b128 v[186:189], v225 offset:3072
	ds_read_b128 v[190:193], v225 offset:4096
	ds_read_b128 v[194:197], v225 offset:5120
	ds_read_b128 v[198:201], v225 offset:6144
	ds_read_b128 v[202:205], v225 offset:7168
	global_load_lds_dwordx4 v[206:207], off
	v_lshl_add_u64 v[206:207], s[24:25], 0, v[134:135]
	s_add_i32 m0, s23, 0xe000
	s_nop 0
	global_load_lds_dwordx4 v[206:207], off
	s_waitcnt vmcnt(8)
	s_waitcnt lgkmcnt(0)
	s_barrier
; #define PG8_STAGE(bufoff, gbase, voff) do { _Pragma("unroll") for (int _i = 0; _i < 2; ++_i) \
;         __builtin_amdgcn_global_load_lds((const unsigned*)((const char*)(gbase) + (voff)[_i]), (PG8_LAS unsigned*)(lds + (bufoff) + ldsw + _i * 8192), 16, 0, 0); } while (0)
; #define PG8_LDA(dst, b, h) do { _Pragma("unroll") for (int m = 0; m < 4; ++m) _Pragma("unroll") for (int k = 0; k < 2; ++k) dst[m][k] = *(const PG8_LAS bf16x8*)(lds + PG8_SA(b, h) + aoff + m * 2048 + k * 1024); } while (0)
; #define PG8_MMA(ai, bj, At, Bt) do { __builtin_amdgcn_s_setprio(1); _Pragma("unroll") for (int m = 0; m < 4; ++m) _Pragma("unroll") for (int n = 0; n < 2; ++n) _Pragma("unroll") for (int k = 0; k < 2; ++k) \
;         acc[ai][bj][m][n] = __builtin_amdgcn_mfma_f32_16x16x32_bf16(Bt[n][k], At[m][k], acc[ai][bj][m][n], 0, 0, 0); __builtin_amdgcn_s_setprio(0); } while (0)
; #define PG8_WAIT_V(n) asm volatile("s_waitcnt vmcnt(" #n ")" ::: "memory")
; #define PG8_WAIT_L(n) asm volatile("s_waitcnt lgkmcnt(" #n ")" ::: "memory")
; #define PG8_BAR __builtin_amdgcn_s_barrier()
; #define PG8_SCHED __builtin_amdgcn_sched_barrier(0)
; template <class Epi, class Sched, bool ALIGN_EPI = false, bool SP2 = false>
; __device__ __forceinline__ void gemm_phase(PG8_LAS unsigned char* lds, const Gemm g, const Sched& S, const Epi& E) {
;     ...
;             PG8_WAIT_V(8); PG8_WAIT_L(0); PG8_BAR; PG8_MMA(0, 0, At, B0); PG8_MMA(0, 1, At, B1); PG8_BAR; PG8_SCHED;
;             PG8_LDA(At, 0, 1); PG8_STAGE(PG8_SB(0, 0), b2, voffB); PG8_STAGE(PG8_SB(0, 1), b2 + hstep, voffB); PG8_STAGE(PG8_SA(0, 0), a2, voffA);
;             PG8_WAIT_V(8); PG8_WAIT_L(0); PG8_BAR; PG8_MMA(1, 0, At, B0); PG8_MMA(1, 1, At, B1); PG8_BAR; PG8_SCHED;
	s_waitcnt lgkmcnt(0)
	v_mfma_f32_16x16x32_bf16 v[124:127], v[140:143], v[172:175], v[124:127]
	v_mfma_f32_16x16x32_bf16 v[120:123], v[148:151], v[172:175], v[120:123]
	v_mfma_f32_16x16x32_bf16 v[108:111], v[140:143], v[180:183], v[108:111]
	v_mfma_f32_16x16x32_bf16 v[104:107], v[148:151], v[180:183], v[104:107]
	v_mfma_f32_16x16x32_bf16 v[92:95], v[140:143], v[190:193], v[92:95]
	v_mfma_f32_16x16x32_bf16 v[88:91], v[148:151], v[190:193], v[88:91]
	v_mfma_f32_16x16x32_bf16 v[76:79], v[140:143], v[198:201], v[76:79]
	v_mfma_f32_16x16x32_bf16 v[72:75], v[148:151], v[198:201], v[72:75]
	v_mfma_f32_16x16x32_bf16 v[124:127], v[144:147], v[176:179], v[124:127]
	v_mfma_f32_16x16x32_bf16 v[120:123], v[152:155], v[176:179], v[120:123]
	v_mfma_f32_16x16x32_bf16 v[108:111], v[144:147], v[186:189], v[108:111]
	v_mfma_f32_16x16x32_bf16 v[104:107], v[152:155], v[186:189], v[104:107]
	v_mfma_f32_16x16x32_bf16 v[92:95], v[144:147], v[194:197], v[92:95]
	v_mfma_f32_16x16x32_bf16 v[88:91], v[152:155], v[194:197], v[88:91]
	v_mfma_f32_16x16x32_bf16 v[76:79], v[144:147], v[202:205], v[76:79]
	v_mfma_f32_16x16x32_bf16 v[72:75], v[152:155], v[202:205], v[72:75]
	v_mfma_f32_16x16x32_bf16 v[116:119], v[156:159], v[172:175], v[116:119]
	v_mfma_f32_16x16x32_bf16 v[112:115], v[164:167], v[172:175], v[112:115]
	v_mfma_f32_16x16x32_bf16 v[100:103], v[156:159], v[180:183], v[100:103]
	v_mfma_f32_16x16x32_bf16 v[96:99], v[164:167], v[180:183], v[96:99]
	v_mfma_f32_16x16x32_bf16 v[84:87], v[156:159], v[190:193], v[84:87]
	v_mfma_f32_16x16x32_bf16 v[80:83], v[164:167], v[190:193], v[80:83]
	v_mfma_f32_16x16x32_bf16 v[68:71], v[156:159], v[198:201], v[68:71]
	v_mfma_f32_16x16x32_bf16 v[64:67], v[164:167], v[198:201], v[64:67]
	v_mfma_f32_16x16x32_bf16 v[116:119], v[160:163], v[176:179], v[116:119]
	v_mfma_f32_16x16x32_bf16 v[112:115], v[168:171], v[176:179], v[112:115]
	v_mfma_f32_16x16x32_bf16 v[100:103], v[160:163], v[186:189], v[100:103]
	v_mfma_f32_16x16x32_bf16 v[96:99], v[168:171], v[186:189], v[96:99]
	v_mfma_f32_16x16x32_bf16 v[84:87], v[160:163], v[194:197], v[84:87]
	v_mfma_f32_16x16x32_bf16 v[80:83], v[168:171], v[194:197], v[80:83]
	v_mfma_f32_16x16x32_bf16 v[68:71], v[160:163], v[202:205], v[68:71]
	v_mfma_f32_16x16x32_bf16 v[64:67], v[168:171], v[202:205], v[64:67]
	s_barrier
	s_add_i32 s63, s49, s37
	v_lshl_add_u64 v[206:207], s[26:27], 0, v[128:129]
	s_mov_b32 m0, s63
	ds_read_b128 v[172:175], v225 offset:16384
	ds_read_b128 v[176:179], v225 offset:17408
	ds_read_b128 v[180:183], v225 offset:18432
	ds_read_b128 v[186:189], v225 offset:19456
	ds_read_b128 v[190:193], v225 offset:20480
	ds_read_b128 v[194:197], v225 offset:21504
	ds_read_b128 v[198:201], v225 offset:22528
	ds_read_b128 v[202:205], v225 offset:23552
	global_load_lds_dwordx4 v[206:207], off
	s_add_i32 m0, s63, 0x2000
	s_add_u32 s66, s26, 0x40000
	v_lshl_add_u64 v[208:209], s[26:27], 0, v[130:131]
	s_addc_u32 s67, s27, 0
	s_add_i32 s63, s50, s37
	global_load_lds_dwordx4 v[208:209], off
	v_lshl_add_u64 v[210:211], s[66:67], 0, v[128:129]
	s_mov_b32 m0, s63
	v_lshl_add_u64 v[212:213], s[28:29], 0, v[130:131]
	global_load_lds_dwordx4 v[210:211], off
	v_lshl_add_u64 v[210:211], s[66:67], 0, v[130:131]
	s_add_i32 m0, s63, 0x2000
	s_nop 0
	global_load_lds_dwordx4 v[210:211], off
	v_lshl_add_u64 v[210:211], s[28:29], 0, v[128:129]
	s_mov_b32 m0, s23
	s_nop 0
	global_load_lds_dwordx4 v[210:211], off
	s_mov_b32 m0, s38
	s_nop 0
	global_load_lds_dwordx4 v[212:213], off
	s_waitcnt vmcnt(8)
	s_waitcnt lgkmcnt(0)
	s_barrier
	s_waitcnt lgkmcnt(0)
	v_mfma_f32_16x16x32_bf16 v[60:63], v[140:143], v[172:175], v[60:63]
	v_mfma_f32_16x16x32_bf16 v[56:59], v[148:151], v[172:175], v[56:59]
	v_mfma_f32_16x16x32_bf16 v[44:47], v[140:143], v[180:183], v[44:47]
	v_mfma_f32_16x16x32_bf16 v[40:43], v[148:151], v[180:183], v[40:43]
	v_mfma_f32_16x16x32_bf16 v[28:31], v[140:143], v[190:193], v[28:31]
	v_mfma_f32_16x16x32_bf16 v[24:27], v[148:151], v[190:193], v[24:27]
	v_mfma_f32_16x16x32_bf16 v[12:15], v[140:143], v[198:201], v[12:15]
	v_mfma_f32_16x16x32_bf16 v[8:11], v[148:151], v[198:201], v[8:11]
	v_mfma_f32_16x16x32_bf16 v[60:63], v[144:147], v[176:179], v[60:63]
	v_mfma_f32_16x16x32_bf16 v[56:59], v[152:155], v[176:179], v[56:59]
	v_mfma_f32_16x16x32_bf16 v[44:47], v[144:147], v[186:189], v[44:47]
	v_mfma_f32_16x16x32_bf16 v[40:43], v[152:155], v[186:189], v[40:43]
	v_mfma_f32_16x16x32_bf16 v[28:31], v[144:147], v[194:197], v[28:31]
	v_mfma_f32_16x16x32_bf16 v[24:27], v[152:155], v[194:197], v[24:27]
	v_mfma_f32_16x16x32_bf16 v[12:15], v[144:147], v[202:205], v[12:15]
	v_mfma_f32_16x16x32_bf16 v[8:11], v[152:155], v[202:205], v[8:11]
	v_mfma_f32_16x16x32_bf16 v[52:55], v[156:159], v[172:175], v[52:55]
	v_mfma_f32_16x16x32_bf16 v[48:51], v[164:167], v[172:175], v[48:51]
	v_mfma_f32_16x16x32_bf16 v[36:39], v[156:159], v[180:183], v[36:39]
	v_mfma_f32_16x16x32_bf16 v[32:35], v[164:167], v[180:183], v[32:35]
	v_mfma_f32_16x16x32_bf16 v[20:23], v[156:159], v[190:193], v[20:23]
	v_mfma_f32_16x16x32_bf16 v[16:19], v[164:167], v[190:193], v[16:19]
	v_mfma_f32_16x16x32_bf16 v[4:7], v[156:159], v[198:201], v[4:7]
	v_mfma_f32_16x16x32_bf16 v[0:3], v[164:167], v[198:201], v[0:3]
	v_mfma_f32_16x16x32_bf16 v[52:55], v[160:163], v[176:179], v[52:55]
	v_mfma_f32_16x16x32_bf16 v[48:51], v[168:171], v[176:179], v[48:51]
	v_mfma_f32_16x16x32_bf16 v[36:39], v[160:163], v[186:189], v[36:39]
	v_mfma_f32_16x16x32_bf16 v[32:35], v[168:171], v[186:189], v[32:35]
	v_mfma_f32_16x16x32_bf16 v[20:23], v[160:163], v[194:197], v[20:23]
	v_mfma_f32_16x16x32_bf16 v[16:19], v[168:171], v[194:197], v[16:19]
	v_mfma_f32_16x16x32_bf16 v[4:7], v[160:163], v[202:205], v[4:7]
	v_mfma_f32_16x16x32_bf16 v[0:3], v[168:171], v[202:205], v[0:3]
	s_barrier
; #define PG8_STAGE(bufoff, gbase, voff) do { _Pragma("unroll") for (int _i = 0; _i < 2; ++_i) \
;         __builtin_amdgcn_global_load_lds((const unsigned*)((const char*)(gbase) + (voff)[_i]), (PG8_LAS unsigned*)(lds + (bufoff) + ldsw + _i * 8192), 16, 0, 0); } while (0)
; #define PG8_LDA(dst, b, h) do { _Pragma("unroll") for (int m = 0; m < 4; ++m) _Pragma("unroll") for (int k = 0; k < 2; ++k) dst[m][k] = *(const PG8_LAS bf16x8*)(lds + PG8_SA(b, h) + aoff + m * 2048 + k * 1024); } while (0)
; #define PG8_LDB(dst, b, h) do { _Pragma("unroll") for (int n = 0; n < 2; ++n) _Pragma("unroll") for (int k = 0; k < 2; ++k) dst[n][k] = *(const PG8_LAS bf16x8*)(lds + PG8_SB(b, h) + boff + n * 2048 + k * 1024); } while (0)
; #define PG8_MMA(ai, bj, At, Bt) do { __builtin_amdgcn_s_setprio(1); _Pragma("unroll") for (int m = 0; m < 4; ++m) _Pragma("unroll") for (int n = 0; n < 2; ++n) _Pragma("unroll") for (int k = 0; k < 2; ++k) \
;         acc[ai][bj][m][n] = __builtin_amdgcn_mfma_f32_16x16x32_bf16(Bt[n][k], At[m][k], acc[ai][bj][m][n], 0, 0, 0); __builtin_amdgcn_s_setprio(0); } while (0)
; #define PG8_WAIT_V(n) asm volatile("s_waitcnt vmcnt(" #n ")" ::: "memory")
; #define PG8_WAIT_L(n) asm volatile("s_waitcnt lgkmcnt(" #n ")" ::: "memory")
; #define PG8_BAR __builtin_amdgcn_s_barrier()
; #define PG8_SCHED __builtin_amdgcn_sched_barrier(0)
; template <class Epi, class Sched, bool ALIGN_EPI = false, bool SP2 = false>
; __device__ __forceinline__ void gemm_phase(PG8_LAS unsigned char* lds, const Gemm g, const Sched& S, const Epi& E) {
;     ...
;             PG8_LDB(B0, 1, 0); PG8_LDB(B1, 1, 1); PG8_SCHED; PG8_LDA(At, 1, 0); PG8_STAGE(PG8_SA(0, 1), a2 + hstep, voffA);
;             PG8_WAIT_V(8); PG8_WAIT_L(0); PG8_BAR; PG8_MMA(0, 0, At, B0); PG8_MMA(0, 1, At, B1); PG8_BAR; PG8_SCHED;
;             PG8_LDA(At, 1, 1); PG8_STAGE(PG8_SB(1, 0), b3, voffB); PG8_STAGE(PG8_SB(1, 1), b3 + hstep, voffB); PG8_STAGE(PG8_SA(1, 0), a3, voffA);
;             PG8_WAIT_V(8); PG8_WAIT_L(0); PG8_BAR; PG8_MMA(1, 0, At, B0); PG8_MMA(1, 1, At, B1); PG8_BAR; PG8_SCHED;
	s_add_i32 s63, 0, 0x18000
	s_add_i32 s66, 0, 0x1c000
	v_add_u32_e32 v152, s63, v221
	v_add_u32_e32 v168, s66, v221
	ds_read_b128 v[140:143], v152
	ds_read_b128 v[144:147], v152 offset:1024
	ds_read_b128 v[148:151], v152 offset:2048
	ds_read_b128 v[152:155], v152 offset:3072
	ds_read_b128 v[156:159], v168
	ds_read_b128 v[160:163], v168 offset:1024
	ds_read_b128 v[164:167], v168 offset:2048
	ds_read_b128 v[168:171], v168 offset:3072
	s_add_u32 s28, s28, 0x40000
	s_addc_u32 s29, s29, 0
	s_mov_b32 m0, s39
	v_lshl_add_u64 v[214:215], s[28:29], 0, v[128:129]
	ds_read_b128 v[172:175], v225 offset:32768
	ds_read_b128 v[176:179], v225 offset:33792
	ds_read_b128 v[180:183], v225 offset:34816
	ds_read_b128 v[186:189], v225 offset:35840
	ds_read_b128 v[190:193], v225 offset:36864
	ds_read_b128 v[194:197], v225 offset:37888
	ds_read_b128 v[198:201], v225 offset:38912
	ds_read_b128 v[202:205], v225 offset:39936
	global_load_lds_dwordx4 v[214:215], off
	v_lshl_add_u64 v[214:215], s[28:29], 0, v[130:131]
	s_mov_b32 m0, s42
	s_nop 0
	global_load_lds_dwordx4 v[214:215], off
	s_waitcnt vmcnt(8)
	s_waitcnt lgkmcnt(0)
	s_barrier
	s_waitcnt lgkmcnt(0)
	v_mfma_f32_16x16x32_bf16 v[124:127], v[140:143], v[172:175], v[124:127]
	v_mfma_f32_16x16x32_bf16 v[120:123], v[148:151], v[172:175], v[120:123]
	v_mfma_f32_16x16x32_bf16 v[108:111], v[140:143], v[180:183], v[108:111]
	v_mfma_f32_16x16x32_bf16 v[104:107], v[148:151], v[180:183], v[104:107]
	v_mfma_f32_16x16x32_bf16 v[92:95], v[140:143], v[190:193], v[92:95]
	v_mfma_f32_16x16x32_bf16 v[88:91], v[148:151], v[190:193], v[88:91]
	v_mfma_f32_16x16x32_bf16 v[76:79], v[140:143], v[198:201], v[76:79]
	v_mfma_f32_16x16x32_bf16 v[72:75], v[148:151], v[198:201], v[72:75]
	v_mfma_f32_16x16x32_bf16 v[124:127], v[144:147], v[176:179], v[124:127]
	v_mfma_f32_16x16x32_bf16 v[120:123], v[152:155], v[176:179], v[120:123]
	v_mfma_f32_16x16x32_bf16 v[108:111], v[144:147], v[186:189], v[108:111]
	v_mfma_f32_16x16x32_bf16 v[104:107], v[152:155], v[186:189], v[104:107]
	v_mfma_f32_16x16x32_bf16 v[92:95], v[144:147], v[194:197], v[92:95]
	v_mfma_f32_16x16x32_bf16 v[88:91], v[152:155], v[194:197], v[88:91]
	v_mfma_f32_16x16x32_bf16 v[76:79], v[144:147], v[202:205], v[76:79]
	v_mfma_f32_16x16x32_bf16 v[72:75], v[152:155], v[202:205], v[72:75]
	v_mfma_f32_16x16x32_bf16 v[116:119], v[156:159], v[172:175], v[116:119]
	v_mfma_f32_16x16x32_bf16 v[112:115], v[164:167], v[172:175], v[112:115]
	v_mfma_f32_16x16x32_bf16 v[100:103], v[156:159], v[180:183], v[100:103]
	v_mfma_f32_16x16x32_bf16 v[96:99], v[164:167], v[180:183], v[96:99]
	v_mfma_f32_16x16x32_bf16 v[84:87], v[156:159], v[190:193], v[84:87]
	v_mfma_f32_16x16x32_bf16 v[80:83], v[164:167], v[190:193], v[80:83]
	v_mfma_f32_16x16x32_bf16 v[68:71], v[156:159], v[198:201], v[68:71]
	v_mfma_f32_16x16x32_bf16 v[64:67], v[164:167], v[198:201], v[64:67]
	v_mfma_f32_16x16x32_bf16 v[116:119], v[160:163], v[176:179], v[116:119]
	v_mfma_f32_16x16x32_bf16 v[112:115], v[168:171], v[176:179], v[112:115]
	v_mfma_f32_16x16x32_bf16 v[100:103], v[160:163], v[186:189], v[100:103]
	v_mfma_f32_16x16x32_bf16 v[96:99], v[168:171], v[186:189], v[96:99]
	v_mfma_f32_16x16x32_bf16 v[84:87], v[160:163], v[194:197], v[84:87]
	v_mfma_f32_16x16x32_bf16 v[80:83], v[168:171], v[194:197], v[80:83]
	v_mfma_f32_16x16x32_bf16 v[68:71], v[160:163], v[202:205], v[68:71]
	v_mfma_f32_16x16x32_bf16 v[64:67], v[168:171], v[202:205], v[64:67]
	s_barrier
	s_add_i32 s28, s63, s37
	v_lshl_add_u64 v[206:207], v[206:207], 0, s[10:11]
	s_mov_b32 m0, s28
	ds_read_b128 v[172:175], v225 offset:49152
	ds_read_b128 v[176:179], v225 offset:50176
	ds_read_b128 v[180:183], v225 offset:51200
	ds_read_b128 v[186:189], v225 offset:52224
	ds_read_b128 v[190:193], v225 offset:53248
	ds_read_b128 v[194:197], v225 offset:54272
	ds_read_b128 v[198:201], v225 offset:55296
	ds_read_b128 v[202:205], v225 offset:56320
	global_load_lds_dwordx4 v[206:207], off
	s_add_i32 m0, s28, 0x2000
	s_add_u32 s26, s26, 0x40080
	v_lshl_add_u64 v[206:207], v[208:209], 0, s[10:11]
	s_addc_u32 s27, s27, 0
	s_add_i32 s28, s66, s37
	global_load_lds_dwordx4 v[206:207], off
	v_lshl_add_u64 v[206:207], s[26:27], 0, v[128:129]
	s_mov_b32 m0, s28
	s_nop 0
	global_load_lds_dwordx4 v[206:207], off
	v_lshl_add_u64 v[206:207], s[26:27], 0, v[130:131]
	s_add_i32 m0, s28, 0x2000
	s_nop 0
	global_load_lds_dwordx4 v[206:207], off
	v_lshl_add_u64 v[206:207], v[210:211], 0, s[10:11]
	s_mov_b32 m0, s44
	s_nop 0
	global_load_lds_dwordx4 v[206:207], off
	v_lshl_add_u64 v[206:207], v[212:213], 0, s[10:11]
	s_mov_b32 m0, s45
	s_nop 0
	global_load_lds_dwordx4 v[206:207], off
	s_waitcnt vmcnt(8)
	s_waitcnt lgkmcnt(0)
	s_barrier
; #define PG8_MMA(ai, bj, At, Bt) do { __builtin_amdgcn_s_setprio(1); _Pragma("unroll") for (int m = 0; m < 4; ++m) _Pragma("unroll") for (int n = 0; n < 2; ++n) _Pragma("unroll") for (int k = 0; k < 2; ++k) \
;         acc[ai][bj][m][n] = __builtin_amdgcn_mfma_f32_16x16x32_bf16(Bt[n][k], At[m][k], acc[ai][bj][m][n], 0, 0, 0); __builtin_amdgcn_s_setprio(0); } while (0)
; #define PG8_WAIT_V(n) asm volatile("s_waitcnt vmcnt(" #n ")" ::: "memory")
; #define PG8_WAIT_L(n) asm volatile("s_waitcnt lgkmcnt(" #n ")" ::: "memory")
; #define PG8_BAR __builtin_amdgcn_s_barrier()
; #define PG8_SCHED __builtin_amdgcn_sched_barrier(0)
; template <class Epi, class Sched, bool ALIGN_EPI = false, bool SP2 = false>
; __device__ __forceinline__ void gemm_phase(PG8_LAS unsigned char* lds, const Gemm g, const Sched& S, const Epi& E) {
;     ...
;         for (int t = 0; t < nt; t += 2) {
;     ...
;             PG8_WAIT_V(8); PG8_WAIT_L(0); PG8_BAR; PG8_MMA(1, 0, At, B0); PG8_MMA(1, 1, At, B1); PG8_BAR; PG8_SCHED;
	s_waitcnt lgkmcnt(0)
	v_mfma_f32_16x16x32_bf16 v[60:63], v[140:143], v[172:175], v[60:63]
	v_mfma_f32_16x16x32_bf16 v[56:59], v[148:151], v[172:175], v[56:59]
	v_mfma_f32_16x16x32_bf16 v[44:47], v[140:143], v[180:183], v[44:47]
	v_mfma_f32_16x16x32_bf16 v[40:43], v[148:151], v[180:183], v[40:43]
	v_mfma_f32_16x16x32_bf16 v[28:31], v[140:143], v[190:193], v[28:31]
	v_mfma_f32_16x16x32_bf16 v[24:27], v[148:151], v[190:193], v[24:27]
	v_mfma_f32_16x16x32_bf16 v[12:15], v[140:143], v[198:201], v[12:15]
	v_mfma_f32_16x16x32_bf16 v[8:11], v[148:151], v[198:201], v[8:11]
	v_mfma_f32_16x16x32_bf16 v[60:63], v[144:147], v[176:179], v[60:63]
	v_mfma_f32_16x16x32_bf16 v[56:59], v[152:155], v[176:179], v[56:59]
	v_mfma_f32_16x16x32_bf16 v[44:47], v[144:147], v[186:189], v[44:47]
	v_mfma_f32_16x16x32_bf16 v[40:43], v[152:155], v[186:189], v[40:43]
	v_mfma_f32_16x16x32_bf16 v[28:31], v[144:147], v[194:197], v[28:31]
	v_mfma_f32_16x16x32_bf16 v[24:27], v[152:155], v[194:197], v[24:27]
	v_mfma_f32_16x16x32_bf16 v[12:15], v[144:147], v[202:205], v[12:15]
	v_mfma_f32_16x16x32_bf16 v[8:11], v[152:155], v[202:205], v[8:11]
	v_mfma_f32_16x16x32_bf16 v[52:55], v[156:159], v[172:175], v[52:55]
	v_mfma_f32_16x16x32_bf16 v[48:51], v[164:167], v[172:175], v[48:51]
	v_mfma_f32_16x16x32_bf16 v[36:39], v[156:159], v[180:183], v[36:39]
	v_mfma_f32_16x16x32_bf16 v[32:35], v[164:167], v[180:183], v[32:35]
	v_mfma_f32_16x16x32_bf16 v[20:23], v[156:159], v[190:193], v[20:23]
	v_mfma_f32_16x16x32_bf16 v[16:19], v[164:167], v[190:193], v[16:19]
	v_mfma_f32_16x16x32_bf16 v[4:7], v[156:159], v[198:201], v[4:7]
	v_mfma_f32_16x16x32_bf16 v[0:3], v[164:167], v[198:201], v[0:3]
	v_mfma_f32_16x16x32_bf16 v[52:55], v[160:163], v[176:179], v[52:55]
	v_mfma_f32_16x16x32_bf16 v[48:51], v[168:171], v[176:179], v[48:51]
	v_mfma_f32_16x16x32_bf16 v[36:39], v[160:163], v[186:189], v[36:39]
	v_mfma_f32_16x16x32_bf16 v[32:35], v[168:171], v[186:189], v[32:35]
	v_mfma_f32_16x16x32_bf16 v[20:23], v[160:163], v[194:197], v[20:23]
	v_mfma_f32_16x16x32_bf16 v[16:19], v[168:171], v[194:197], v[16:19]
	v_mfma_f32_16x16x32_bf16 v[4:7], v[160:163], v[202:205], v[4:7]
	v_mfma_f32_16x16x32_bf16 v[0:3], v[168:171], v[202:205], v[0:3]
	s_barrier
	s_add_i32 s58, s58, 2
	s_add_u32 s24, s24, 0x100
	s_addc_u32 s25, s25, 0
	s_add_u32 s56, s56, 0x100
	s_addc_u32 s57, s57, 0
	s_cmp_gt_u32 s58, 13
	s_cbranch_scc0 .LBB0_716
; __device__ __forceinline__ unsigned cvt_pk_bf16(float lo, float hi) { unsigned r; asm volatile("v_cvt_pk_bf16_f32 %0, %1, %2" : "=v"(r) : "v"(lo), "v"(hi)); return r; }
;     __device__ __forceinline__ void operator()(const f32x4 (&acc)[2][2][4][2], const Unit& u, int wr, int wc, int fr, int fq) const {
;         const int row0 = u.pm * BM + wr * 64 + fr, col0 = u.pn * BM + wc * 32 + 4 * fq;
;         unsigned long long rb[2][4][2][2];
;         if (BB) {
; #pragma unroll
;             for (int ai = 0; ai < 2; ++ai)
; #pragma unroll
;                 for (int m = 0; m < 4; ++m)
; #pragma unroll
;                     for (int bj = 0; bj < 2; ++bj)
; #pragma unroll
;                         for (int n = 0; n < 2; ++n) rb[ai][m][bj][n] = *(const unsigned long long*)((const bf16_t*)base + (size_t)(row0 + ai * HALF + m * 16) * ldc + col0 + bj * HALF + n * 16);
;             asm volatile("" ::: "memory"); }
; #pragma unroll
;         for (int ai = 0; ai < 2; ++ai)
; #pragma unroll
;             for (int m = 0; m < 4; ++m) { const int row = row0 + ai * HALF + m * 16; const size_t off = (size_t)row * ldc + col0; float s = 0.f;
; #pragma unroll
;                 for (int bj = 0; bj < 2; ++bj)
; #pragma unroll
;                     for (int n = 0; n < 2; ++n) { f32x4 bs;
;                         if (BB) { const unsigned long long rw = rb[ai][m][bj][n]; const unsigned lo = (unsigned)rw, hi = (unsigned)(rw >> 32);
;                             bs = (f32x4){__uint_as_float(lo << 16), __uint_as_float(lo & 0xffff0000u), __uint_as_float(hi << 16), __uint_as_float(hi & 0xffff0000u)}; }
;                         else bs = *(const f32x4*)((const float*)base + off + bj * HALF + n * 16);
;                         const f32x4 v = bs + acc[ai][bj][m][n];
;                         if (WF) *(f32x4*)(out + off + bj * HALF + n * 16) = v;
;                         s += (v[0] * v[0] + v[1] * v[1]) + (v[2] * v[2] + v[3] * v[3]);
;                         if (WB) { unsigned lo = cvt_pk_bf16(v[0], v[1]), hi = cvt_pk_bf16(v[2], v[3]); *(unsigned long long*)(outb + off + bj * HALF + n * 16) = (unsigned long long)lo | ((unsigned long long)hi << 32); } }
;                 s += __shfl_xor(s, 16); s += __shfl_xor(s, 32);
;                 if (fq == 0) atomicAdd(ssq + row, s);
;                 asm volatile("" ::: "memory"); }
	s_setprio 0
	v_lshl_add_u32 v212, s20, 8, v220
	v_lshl_or_b32 v140, s22, 8, v222
	v_ashrrev_i32_e32 v141, 31, v140
	v_ashrrev_i32_e32 v213, 31, v212
	v_lshl_add_u64 v[144:145], v[140:141], 1, s[6:7]
	v_lshlrev_b64 v[142:143], 11, v[212:213]
	v_lshl_add_u64 v[142:143], v[144:145], 0, v[142:143]
	global_load_dwordx2 v[228:229], v[142:143], off
	global_load_dwordx2 v[230:231], v[142:143], off offset:32
	global_load_dwordx2 v[234:235], v[142:143], off offset:256
	global_load_dwordx2 v[236:237], v[142:143], off offset:288
	v_or_b32_e32 v202, 16, v212
	v_ashrrev_i32_e32 v203, 31, v202
	v_lshlrev_b64 v[142:143], 11, v[202:203]
	v_or_b32_e32 v192, 32, v212
	v_lshl_add_u64 v[142:143], v[144:145], 0, v[142:143]
	v_ashrrev_i32_e32 v193, 31, v192
	global_load_dwordx2 v[214:215], v[142:143], off
	global_load_dwordx2 v[210:211], v[142:143], off offset:32
	global_load_dwordx2 v[208:209], v[142:143], off offset:256
	global_load_dwordx2 v[206:207], v[142:143], off offset:288
	v_lshlrev_b64 v[142:143], 11, v[192:193]
	v_or_b32_e32 v180, 48, v212
	v_lshl_add_u64 v[142:143], v[144:145], 0, v[142:143]
	v_ashrrev_i32_e32 v181, 31, v180
	global_load_dwordx2 v[204:205], v[142:143], off
	global_load_dwordx2 v[200:201], v[142:143], off offset:32
	global_load_dwordx2 v[198:199], v[142:143], off offset:256
	global_load_dwordx2 v[196:197], v[142:143], off offset:288
	v_lshlrev_b64 v[142:143], 11, v[180:181]
	v_add_u32_e32 v170, 0x80, v212
	v_lshl_add_u64 v[142:143], v[144:145], 0, v[142:143]
	v_ashrrev_i32_e32 v171, 31, v170
	global_load_dwordx2 v[194:195], v[142:143], off
	global_load_dwordx2 v[190:191], v[142:143], off offset:32
	global_load_dwordx2 v[188:189], v[142:143], off offset:256
	global_load_dwordx2 v[186:187], v[142:143], off offset:288
	v_lshlrev_b64 v[142:143], 11, v[170:171]
	v_add_u32_e32 v160, 0x90, v212
	v_lshl_add_u64 v[142:143], v[144:145], 0, v[142:143]
	v_ashrrev_i32_e32 v161, 31, v160
	global_load_dwordx2 v[182:183], v[142:143], off
	global_load_dwordx2 v[178:179], v[142:143], off offset:32
	global_load_dwordx2 v[176:177], v[142:143], off offset:256
	global_load_dwordx2 v[174:175], v[142:143], off offset:288
	v_lshlrev_b64 v[142:143], 11, v[160:161]
	v_add_u32_e32 v150, 0xa0, v212
	v_lshl_add_u64 v[142:143], v[144:145], 0, v[142:143]
	v_ashrrev_i32_e32 v151, 31, v150
	global_load_dwordx2 v[172:173], v[142:143], off
	global_load_dwordx2 v[168:169], v[142:143], off offset:32
	global_load_dwordx2 v[166:167], v[142:143], off offset:256
	global_load_dwordx2 v[164:165], v[142:143], off offset:288
	v_lshlrev_b64 v[142:143], 11, v[150:151]
	v_lshl_add_u64 v[142:143], v[144:145], 0, v[142:143]
	global_load_dwordx2 v[162:163], v[142:143], off
	global_load_dwordx2 v[158:159], v[142:143], off offset:32
	global_load_dwordx2 v[156:157], v[142:143], off offset:256
	global_load_dwordx2 v[154:155], v[142:143], off offset:288
	v_add_u32_e32 v142, 0xb0, v212
	v_ashrrev_i32_e32 v143, 31, v142
	v_lshlrev_b64 v[146:147], 11, v[142:143]
	v_lshl_add_u64 v[144:145], v[144:145], 0, v[146:147]
	global_load_dwordx2 v[152:153], v[144:145], off
	global_load_dwordx2 v[148:149], v[144:145], off offset:32
	global_load_dwordx2 v[146:147], v[144:145], off offset:256
	s_nop 0
	global_load_dwordx2 v[144:145], v[144:145], off offset:288
	v_and_b32_e32 v233, 64, v226
	v_xor_b32_e32 v227, 16, v226
	v_add_u32_e32 v233, 64, v233
	v_xor_b32_e32 v238, 32, v226
	v_cmp_lt_i32_e32 vcc, v227, v233
	s_waitcnt vmcnt(0)
	v_and_b32_e32 v239, 0xffff0000, v228
	v_cndmask_b32_e32 v227, v226, v227, vcc
	v_cmp_lt_i32_e32 vcc, v238, v233
	v_lshlrev_b32_e32 v240, 16, v230
	v_and_b32_e32 v241, 0xffff0000, v230
	v_cndmask_b32_e32 v233, v226, v238, vcc
	v_lshlrev_b32_e32 v238, 16, v228
	v_lshlrev_b32_e32 v228, 16, v229
	v_and_b32_e32 v229, 0xffff0000, v229
	v_pk_add_f32 v[126:127], v[126:127], v[228:229]
	v_pk_add_f32 v[124:125], v[124:125], v[238:239]
	v_mul_f32_e32 v229, v127, v127
	v_mul_f32_e32 v228, v125, v125
	v_fmac_f32_e32 v228, v124, v124
	v_fmac_f32_e32 v229, v126, v126
	v_add_f32_e32 v238, v228, v229
	v_lshlrev_b32_e32 v228, 16, v231
	v_and_b32_e32 v229, 0xffff0000, v231
	v_pk_add_f32 v[122:123], v[122:123], v[228:229]
	v_pk_add_f32 v[120:121], v[120:121], v[240:241]
	v_mul_f32_e32 v229, v123, v123
	v_mul_f32_e32 v228, v121, v121
	v_fmac_f32_e32 v228, v120, v120
	v_fmac_f32_e32 v229, v122, v122
	v_add_f32_e32 v228, v228, v229
	v_add_f32_e32 v238, v238, v228
	v_lshlrev_b32_e32 v228, 16, v234
	v_and_b32_e32 v229, 0xffff0000, v234
	v_lshlrev_b32_e32 v230, 16, v235
	v_and_b32_e32 v231, 0xffff0000, v235
	v_pk_add_f32 v[118:119], v[118:119], v[230:231]
	v_pk_add_f32 v[116:117], v[116:117], v[228:229]
	v_mul_f32_e32 v229, v119, v119
	v_mul_f32_e32 v228, v117, v117
	v_fmac_f32_e32 v228, v116, v116
	v_fmac_f32_e32 v229, v118, v118
	v_add_f32_e32 v228, v228, v229
	v_add_f32_e32 v234, v238, v228
	v_lshlrev_b32_e32 v228, 16, v236
	v_and_b32_e32 v229, 0xffff0000, v236
	v_lshlrev_b32_e32 v230, 16, v237
	v_and_b32_e32 v231, 0xffff0000, v237
	v_pk_add_f32 v[230:231], v[114:115], v[230:231]
	v_pk_add_f32 v[228:229], v[112:113], v[228:229]
	v_mul_f32_e32 v113, v231, v231
	v_mul_f32_e32 v112, v229, v229
	v_fmac_f32_e32 v112, v228, v228
	v_fmac_f32_e32 v113, v230, v230
	v_add_f32_e32 v112, v112, v113
	v_lshlrev_b32_e32 v227, 2, v227
	v_add_f32_e32 v113, v234, v112
	ds_bpermute_b32 v236, v227, v113
	v_lshlrev_b64 v[114:115], 12, v[212:213]
	v_lshlrev_b32_e32 v112, 2, v233
	v_lshl_add_u64 v[114:115], s[52:53], 0, v[114:115]
	v_lshl_add_u64 v[234:235], v[140:141], 2, v[114:115]
	s_waitcnt lgkmcnt(0)
	v_add_f32_e32 v113, v113, v236
	ds_bpermute_b32 v114, v112, v113
	global_store_dwordx4 v[234:235], v[124:127], off
	global_store_dwordx4 v[234:235], v[120:123], off offset:64
	global_store_dwordx4 v[234:235], v[116:119], off offset:512
	global_store_dwordx4 v[234:235], v[228:231], off offset:576
	s_and_saveexec_b64 s[20:21], s[2:3]
	s_cbranch_execz .LBB0_719
	v_lshl_add_u64 v[116:117], v[212:213], 2, s[8:9]
	s_waitcnt lgkmcnt(0)
	v_add_f32_e32 v113, v113, v114
	global_atomic_add_f32 v[116:117], v113, off

; #define PG8_STAGE(bufoff, gbase, voff) do { _Pragma("unroll") for (int _i = 0; _i < 2; ++_i) \
;         __builtin_amdgcn_global_load_lds((const unsigned*)((const char*)(gbase) + (voff)[_i]), (PG8_LAS unsigned*)(lds + (bufoff) + ldsw + _i * 8192), 16, 0, 0); } while (0)
; #define PG8_LDA(dst, b, h) do { _Pragma("unroll") for (int m = 0; m < 4; ++m) _Pragma("unroll") for (int k = 0; k < 2; ++k) dst[m][k] = *(const PG8_LAS bf16x8*)(lds + PG8_SA(b, h) + aoff + m * 2048 + k * 1024); } while (0)
; #define PG8_LDB(dst, b, h) do { _Pragma("unroll") for (int n = 0; n < 2; ++n) _Pragma("unroll") for (int k = 0; k < 2; ++k) dst[n][k] = *(const PG8_LAS bf16x8*)(lds + PG8_SB(b, h) + boff + n * 2048 + k * 1024); } while (0)
; #define PG8_MMA(ai, bj, At, Bt) do { __builtin_amdgcn_s_setprio(1); _Pragma("unroll") for (int m = 0; m < 4; ++m) _Pragma("unroll") for (int n = 0; n < 2; ++n) _Pragma("unroll") for (int k = 0; k < 2; ++k) \
;         acc[ai][bj][m][n] = __builtin_amdgcn_mfma_f32_16x16x32_bf16(Bt[n][k], At[m][k], acc[ai][bj][m][n], 0, 0, 0); __builtin_amdgcn_s_setprio(0); } while (0)
; #define PG8_BAR __builtin_amdgcn_s_barrier()
; template <class Epi, class Sched, bool ALIGN_EPI = false, bool SP2 = false>
; __device__ __forceinline__ void gemm_phase(PG8_LAS unsigned char* lds, const Gemm g, const Sched& S, const Epi& E) {
;     ...
;         const bool has_next = S.next(ui + 1, nxt);
;         const char* nA = has_next ? (const char*)g.A + (size_t)nxt.pm * tstep : cA; const char* nB = has_next ? (const char*)g.Bt + (size_t)nxt.pn * tstep : cB;
;         for (int t = 0; t < nt; t += 2) {
;             const bool last = (t == nt - 2);
;             const char* a1 = cA + (size_t)(t + 1) * kstep;
;             const char* a2 = last ? nA : cA + (size_t)(t + 2) * kstep; const char* b2 = last ? nB : cB + (size_t)(t + 2) * kstep;
;             const char* a3 = a2 + kstep; const char* b3 = b2 + kstep;
;             if (last && has_next) S.a_ready(nxt);
;             if constexpr (SP2) {
;             PG8_LDB(B0, 0, 0); PG8_LDB(B1, 0, 1); PG8_SCHED; PG8_LDA(At, 0, 0); PG8_STAGE(PG8_SA(1, 1), a1 + hstep, voffA);
;             PG8_WAIT_V(8); PG8_WAIT_L(0); PG8_BAR; PG8_MMA(0, 0, At, B0); PG8_MMA(0, 1, At, B1); PG8_BAR; PG8_SCHED;
;             PG8_LDA(At, 0, 1); PG8_STAGE(PG8_SB(0, 0), b2, voffB); PG8_STAGE(PG8_SB(0, 1), b2 + hstep, voffB); PG8_STAGE(PG8_SA(0, 0), a2, voffA);
.LBB0_808:
	s_add_u32 s21, s24, 0x100
	s_addc_u32 s51, s25, 0
	s_ashr_i32 s17, s16, 31
	s_lshl_b64 s[18:19], s[16:17], 19
	s_add_u32 s22, s30, s18
	s_addc_u32 s23, s31, s19
	s_and_b64 s[18:19], s[2:3], exec
	s_cselect_b32 s17, s23, s11
	s_cselect_b32 s56, s22, s10
	s_ashr_i32 s15, s14, 31
	s_lshl_b64 s[18:19], s[14:15], 19
	s_add_u32 s18, s34, s18
	s_addc_u32 s19, s35, s19
	s_and_b64 s[26:27], s[2:3], exec
	s_cselect_b32 s15, s19, s25
	s_cselect_b32 s57, s18, s24
	v_lshl_add_u64 v[140:141], s[10:11], 0, v[132:133]
	v_lshl_add_u64 v[142:143], s[10:11], 0, v[134:135]
	s_mov_b32 s58, -2
	s_mov_b64 s[24:25], 0
	s_bitcmp1_b32 s60, 2
	s_cbranch_scc0 .Lgprio_5
	s_setprio 1
.Lgprio_5:
.LBB0_809:
	v_add_u32_e32 v147, s49, v145
	ds_read_b128 v[148:151], v147
	ds_read_b128 v[152:155], v147 offset:1024
	ds_read_b128 v[156:159], v147 offset:2048
	ds_read_b128 v[160:163], v147 offset:3072
	v_add_u32_e32 v147, s50, v145
	s_add_u32 s26, s10, s24
	ds_read_b128 v[164:167], v147
	ds_read_b128 v[168:171], v147 offset:1024
	ds_read_b128 v[172:175], v147 offset:2048
	ds_read_b128 v[176:179], v147 offset:3072
	s_addc_u32 s27, s11, s25
	s_add_u32 s26, s26, 0x100
	s_addc_u32 s27, s27, 0
	s_add_u32 s59, s21, s24
	s_addc_u32 s60, s51, s25
	s_cmpk_eq_i32 s24, 0x700
	s_cselect_b32 s29, s17, s27
	s_cselect_b32 s28, s56, s26
	s_cselect_b32 s27, s15, s60
	s_cselect_b32 s26, s57, s59
	v_lshl_add_u64 v[184:185], v[140:141], 0, s[24:25]
	s_add_i32 m0, s39, 0xc000
	ds_read_b128 v[180:183], v146
	ds_read_b128 v[188:191], v146 offset:1024
	ds_read_b128 v[192:195], v146 offset:2048
	ds_read_b128 v[196:199], v146 offset:3072
	ds_read_b128 v[200:203], v146 offset:4096
	ds_read_b128 v[204:207], v146 offset:5120
	ds_read_b128 v[208:211], v146 offset:6144
	ds_read_b128 v[212:215], v146 offset:7168
	global_load_lds_dwordx4 v[184:185], off
	v_lshl_add_u64 v[184:185], v[142:143], 0, s[24:25]
	s_add_i32 m0, s39, 0xe000
	s_nop 0
	global_load_lds_dwordx4 v[184:185], off
	s_waitcnt vmcnt(8)
	s_waitcnt lgkmcnt(0)
	s_barrier
	s_waitcnt lgkmcnt(0)
	v_mfma_f32_16x16x32_bf16 v[124:127], v[148:151], v[180:183], v[124:127]
	v_mfma_f32_16x16x32_bf16 v[120:123], v[156:159], v[180:183], v[120:123]
	v_mfma_f32_16x16x32_bf16 v[108:111], v[148:151], v[192:195], v[108:111]
	v_mfma_f32_16x16x32_bf16 v[104:107], v[156:159], v[192:195], v[104:107]
	v_mfma_f32_16x16x32_bf16 v[92:95], v[148:151], v[200:203], v[92:95]
	v_mfma_f32_16x16x32_bf16 v[88:91], v[156:159], v[200:203], v[88:91]
	v_mfma_f32_16x16x32_bf16 v[76:79], v[148:151], v[208:211], v[76:79]
	v_mfma_f32_16x16x32_bf16 v[72:75], v[156:159], v[208:211], v[72:75]
	v_mfma_f32_16x16x32_bf16 v[124:127], v[152:155], v[188:191], v[124:127]
	v_mfma_f32_16x16x32_bf16 v[120:123], v[160:163], v[188:191], v[120:123]
	v_mfma_f32_16x16x32_bf16 v[108:111], v[152:155], v[196:199], v[108:111]
	v_mfma_f32_16x16x32_bf16 v[104:107], v[160:163], v[196:199], v[104:107]
	v_mfma_f32_16x16x32_bf16 v[92:95], v[152:155], v[204:207], v[92:95]
	v_mfma_f32_16x16x32_bf16 v[88:91], v[160:163], v[204:207], v[88:91]
	v_mfma_f32_16x16x32_bf16 v[76:79], v[152:155], v[212:215], v[76:79]
	v_mfma_f32_16x16x32_bf16 v[72:75], v[160:163], v[212:215], v[72:75]
	v_mfma_f32_16x16x32_bf16 v[116:119], v[164:167], v[180:183], v[116:119]
	v_mfma_f32_16x16x32_bf16 v[112:115], v[172:175], v[180:183], v[112:115]
	v_mfma_f32_16x16x32_bf16 v[100:103], v[164:167], v[192:195], v[100:103]
	v_mfma_f32_16x16x32_bf16 v[96:99], v[172:175], v[192:195], v[96:99]
	v_mfma_f32_16x16x32_bf16 v[84:87], v[164:167], v[200:203], v[84:87]
	v_mfma_f32_16x16x32_bf16 v[80:83], v[172:175], v[200:203], v[80:83]
	v_mfma_f32_16x16x32_bf16 v[68:71], v[164:167], v[208:211], v[68:71]
	v_mfma_f32_16x16x32_bf16 v[64:67], v[172:175], v[208:211], v[64:67]
	v_mfma_f32_16x16x32_bf16 v[116:119], v[168:171], v[188:191], v[116:119]
	v_mfma_f32_16x16x32_bf16 v[112:115], v[176:179], v[188:191], v[112:115]
	v_mfma_f32_16x16x32_bf16 v[100:103], v[168:171], v[196:199], v[100:103]
	v_mfma_f32_16x16x32_bf16 v[96:99], v[176:179], v[196:199], v[96:99]
	v_mfma_f32_16x16x32_bf16 v[84:87], v[168:171], v[204:207], v[84:87]
	v_mfma_f32_16x16x32_bf16 v[80:83], v[176:179], v[204:207], v[80:83]
	v_mfma_f32_16x16x32_bf16 v[68:71], v[168:171], v[212:215], v[68:71]
	v_mfma_f32_16x16x32_bf16 v[64:67], v[176:179], v[212:215], v[64:67]
	s_barrier
	s_add_i32 s59, s49, s38
	v_lshl_add_u64 v[184:185], s[26:27], 0, v[128:129]
	s_mov_b32 m0, s59
	ds_read_b128 v[180:183], v146 offset:16384
	ds_read_b128 v[188:191], v146 offset:17408
	ds_read_b128 v[192:195], v146 offset:18432
	ds_read_b128 v[196:199], v146 offset:19456
	ds_read_b128 v[200:203], v146 offset:20480
	ds_read_b128 v[204:207], v146 offset:21504
	ds_read_b128 v[208:211], v146 offset:22528
	ds_read_b128 v[212:215], v146 offset:23552
	global_load_lds_dwordx4 v[184:185], off
	s_add_i32 m0, s59, 0x2000
	s_add_u32 s60, s26, 0x40000
	v_lshl_add_u64 v[218:219], s[26:27], 0, v[130:131]
	s_addc_u32 s61, s27, 0
	s_add_i32 s59, s50, s38
	global_load_lds_dwordx4 v[218:219], off
	v_lshl_add_u64 v[220:221], s[60:61], 0, v[128:129]
	s_mov_b32 m0, s59
	v_lshl_add_u64 v[222:223], s[28:29], 0, v[130:131]
	global_load_lds_dwordx4 v[220:221], off
	v_lshl_add_u64 v[220:221], s[60:61], 0, v[130:131]
	s_add_i32 m0, s59, 0x2000
	s_nop 0
	global_load_lds_dwordx4 v[220:221], off
	v_lshl_add_u64 v[220:221], s[28:29], 0, v[128:129]
	s_mov_b32 m0, s39
	s_nop 0
	global_load_lds_dwordx4 v[220:221], off
	s_mov_b32 m0, s42
	s_nop 0
	global_load_lds_dwordx4 v[222:223], off
	s_waitcnt vmcnt(8)
	s_waitcnt lgkmcnt(0)
	s_barrier
; #define PG8_STAGE(bufoff, gbase, voff) do { _Pragma("unroll") for (int _i = 0; _i < 2; ++_i) \
;         __builtin_amdgcn_global_load_lds((const unsigned*)((const char*)(gbase) + (voff)[_i]), (PG8_LAS unsigned*)(lds + (bufoff) + ldsw + _i * 8192), 16, 0, 0); } while (0)
; #define PG8_LDA(dst, b, h) do { _Pragma("unroll") for (int m = 0; m < 4; ++m) _Pragma("unroll") for (int k = 0; k < 2; ++k) dst[m][k] = *(const PG8_LAS bf16x8*)(lds + PG8_SA(b, h) + aoff + m * 2048 + k * 1024); } while (0)
; #define PG8_LDB(dst, b, h) do { _Pragma("unroll") for (int n = 0; n < 2; ++n) _Pragma("unroll") for (int k = 0; k < 2; ++k) dst[n][k] = *(const PG8_LAS bf16x8*)(lds + PG8_SB(b, h) + boff + n * 2048 + k * 1024); } while (0)
; #define PG8_MMA(ai, bj, At, Bt) do { __builtin_amdgcn_s_setprio(1); _Pragma("unroll") for (int m = 0; m < 4; ++m) _Pragma("unroll") for (int n = 0; n < 2; ++n) _Pragma("unroll") for (int k = 0; k < 2; ++k) \
;         acc[ai][bj][m][n] = __builtin_amdgcn_mfma_f32_16x16x32_bf16(Bt[n][k], At[m][k], acc[ai][bj][m][n], 0, 0, 0); __builtin_amdgcn_s_setprio(0); } while (0)
; #define PG8_WAIT_V(n) asm volatile("s_waitcnt vmcnt(" #n ")" ::: "memory")
; #define PG8_WAIT_L(n) asm volatile("s_waitcnt lgkmcnt(" #n ")" ::: "memory")
; #define PG8_BAR __builtin_amdgcn_s_barrier()
; #define PG8_SCHED __builtin_amdgcn_sched_barrier(0)
; template <class Epi, class Sched, bool ALIGN_EPI = false, bool SP2 = false>
; __device__ __forceinline__ void gemm_phase(PG8_LAS unsigned char* lds, const Gemm g, const Sched& S, const Epi& E) {
;     ...
;             PG8_WAIT_V(8); PG8_WAIT_L(0); PG8_BAR; PG8_MMA(1, 0, At, B0); PG8_MMA(1, 1, At, B1); PG8_BAR; PG8_SCHED;
;             PG8_LDB(B0, 1, 0); PG8_LDB(B1, 1, 1); PG8_SCHED; PG8_LDA(At, 1, 0); PG8_STAGE(PG8_SA(0, 1), a2 + hstep, voffA);
;             PG8_WAIT_V(8); PG8_WAIT_L(0); PG8_BAR; PG8_MMA(0, 0, At, B0); PG8_MMA(0, 1, At, B1); PG8_BAR; PG8_SCHED;
	s_waitcnt lgkmcnt(0)
	v_mfma_f32_16x16x32_bf16 v[60:63], v[148:151], v[180:183], v[60:63]
	v_mfma_f32_16x16x32_bf16 v[56:59], v[156:159], v[180:183], v[56:59]
	v_mfma_f32_16x16x32_bf16 v[44:47], v[148:151], v[192:195], v[44:47]
	v_mfma_f32_16x16x32_bf16 v[40:43], v[156:159], v[192:195], v[40:43]
	v_mfma_f32_16x16x32_bf16 v[28:31], v[148:151], v[200:203], v[28:31]
	v_mfma_f32_16x16x32_bf16 v[24:27], v[156:159], v[200:203], v[24:27]
	v_mfma_f32_16x16x32_bf16 v[12:15], v[148:151], v[208:211], v[12:15]
	v_mfma_f32_16x16x32_bf16 v[8:11], v[156:159], v[208:211], v[8:11]
	v_mfma_f32_16x16x32_bf16 v[60:63], v[152:155], v[188:191], v[60:63]
	v_mfma_f32_16x16x32_bf16 v[56:59], v[160:163], v[188:191], v[56:59]
	v_mfma_f32_16x16x32_bf16 v[44:47], v[152:155], v[196:199], v[44:47]
	v_mfma_f32_16x16x32_bf16 v[40:43], v[160:163], v[196:199], v[40:43]
	v_mfma_f32_16x16x32_bf16 v[28:31], v[152:155], v[204:207], v[28:31]
	v_mfma_f32_16x16x32_bf16 v[24:27], v[160:163], v[204:207], v[24:27]
	v_mfma_f32_16x16x32_bf16 v[12:15], v[152:155], v[212:215], v[12:15]
	v_mfma_f32_16x16x32_bf16 v[8:11], v[160:163], v[212:215], v[8:11]
	v_mfma_f32_16x16x32_bf16 v[52:55], v[164:167], v[180:183], v[52:55]
	v_mfma_f32_16x16x32_bf16 v[48:51], v[172:175], v[180:183], v[48:51]
	v_mfma_f32_16x16x32_bf16 v[36:39], v[164:167], v[192:195], v[36:39]
	v_mfma_f32_16x16x32_bf16 v[32:35], v[172:175], v[192:195], v[32:35]
	v_mfma_f32_16x16x32_bf16 v[20:23], v[164:167], v[200:203], v[20:23]
	v_mfma_f32_16x16x32_bf16 v[16:19], v[172:175], v[200:203], v[16:19]
	v_mfma_f32_16x16x32_bf16 v[4:7], v[164:167], v[208:211], v[4:7]
	v_mfma_f32_16x16x32_bf16 v[0:3], v[172:175], v[208:211], v[0:3]
	v_mfma_f32_16x16x32_bf16 v[52:55], v[168:171], v[188:191], v[52:55]
	v_mfma_f32_16x16x32_bf16 v[48:51], v[176:179], v[188:191], v[48:51]
	v_mfma_f32_16x16x32_bf16 v[36:39], v[168:171], v[196:199], v[36:39]
	v_mfma_f32_16x16x32_bf16 v[32:35], v[176:179], v[196:199], v[32:35]
	v_mfma_f32_16x16x32_bf16 v[20:23], v[168:171], v[204:207], v[20:23]
	v_mfma_f32_16x16x32_bf16 v[16:19], v[176:179], v[204:207], v[16:19]
	v_mfma_f32_16x16x32_bf16 v[4:7], v[168:171], v[212:215], v[4:7]
	v_mfma_f32_16x16x32_bf16 v[0:3], v[176:179], v[212:215], v[0:3]
	s_barrier
	s_add_i32 s59, 0, 0x18000
	v_add_u32_e32 v147, s59, v145
	s_add_i32 s60, 0, 0x1c000
	ds_read_b128 v[148:151], v147
	ds_read_b128 v[152:155], v147 offset:1024
	ds_read_b128 v[156:159], v147 offset:2048
	ds_read_b128 v[160:163], v147 offset:3072
	v_add_u32_e32 v147, s60, v145
	ds_read_b128 v[164:167], v147
	ds_read_b128 v[168:171], v147 offset:1024
	ds_read_b128 v[172:175], v147 offset:2048
	ds_read_b128 v[176:179], v147 offset:3072
	s_add_u32 s28, s28, 0x40000
	s_addc_u32 s29, s29, 0
	s_mov_b32 m0, s43
	v_lshl_add_u64 v[224:225], s[28:29], 0, v[128:129]
	ds_read_b128 v[180:183], v146 offset:32768
	ds_read_b128 v[188:191], v146 offset:33792
	ds_read_b128 v[192:195], v146 offset:34816
	ds_read_b128 v[196:199], v146 offset:35840
	ds_read_b128 v[200:203], v146 offset:36864
	ds_read_b128 v[204:207], v146 offset:37888
	ds_read_b128 v[208:211], v146 offset:38912
	ds_read_b128 v[212:215], v146 offset:39936
	global_load_lds_dwordx4 v[224:225], off
	v_lshl_add_u64 v[224:225], s[28:29], 0, v[130:131]
	s_mov_b32 m0, s44
	s_nop 0
	global_load_lds_dwordx4 v[224:225], off
	s_waitcnt vmcnt(8)
	s_waitcnt lgkmcnt(0)
	s_barrier
	s_waitcnt lgkmcnt(0)
	v_mfma_f32_16x16x32_bf16 v[124:127], v[148:151], v[180:183], v[124:127]
	v_mfma_f32_16x16x32_bf16 v[120:123], v[156:159], v[180:183], v[120:123]
	v_mfma_f32_16x16x32_bf16 v[108:111], v[148:151], v[192:195], v[108:111]
	v_mfma_f32_16x16x32_bf16 v[104:107], v[156:159], v[192:195], v[104:107]
	v_mfma_f32_16x16x32_bf16 v[92:95], v[148:151], v[200:203], v[92:95]
	v_mfma_f32_16x16x32_bf16 v[88:91], v[156:159], v[200:203], v[88:91]
	v_mfma_f32_16x16x32_bf16 v[76:79], v[148:151], v[208:211], v[76:79]
	v_mfma_f32_16x16x32_bf16 v[72:75], v[156:159], v[208:211], v[72:75]
	v_mfma_f32_16x16x32_bf16 v[124:127], v[152:155], v[188:191], v[124:127]
	v_mfma_f32_16x16x32_bf16 v[120:123], v[160:163], v[188:191], v[120:123]
	v_mfma_f32_16x16x32_bf16 v[108:111], v[152:155], v[196:199], v[108:111]
	v_mfma_f32_16x16x32_bf16 v[104:107], v[160:163], v[196:199], v[104:107]
	v_mfma_f32_16x16x32_bf16 v[92:95], v[152:155], v[204:207], v[92:95]
	v_mfma_f32_16x16x32_bf16 v[88:91], v[160:163], v[204:207], v[88:91]
	v_mfma_f32_16x16x32_bf16 v[76:79], v[152:155], v[212:215], v[76:79]
	v_mfma_f32_16x16x32_bf16 v[72:75], v[160:163], v[212:215], v[72:75]
	v_mfma_f32_16x16x32_bf16 v[116:119], v[164:167], v[180:183], v[116:119]
	v_mfma_f32_16x16x32_bf16 v[112:115], v[172:175], v[180:183], v[112:115]
	v_mfma_f32_16x16x32_bf16 v[100:103], v[164:167], v[192:195], v[100:103]
	v_mfma_f32_16x16x32_bf16 v[96:99], v[172:175], v[192:195], v[96:99]
	v_mfma_f32_16x16x32_bf16 v[84:87], v[164:167], v[200:203], v[84:87]
	v_mfma_f32_16x16x32_bf16 v[80:83], v[172:175], v[200:203], v[80:83]
	v_mfma_f32_16x16x32_bf16 v[68:71], v[164:167], v[208:211], v[68:71]
	v_mfma_f32_16x16x32_bf16 v[64:67], v[172:175], v[208:211], v[64:67]
	v_mfma_f32_16x16x32_bf16 v[116:119], v[168:171], v[188:191], v[116:119]
	v_mfma_f32_16x16x32_bf16 v[112:115], v[176:179], v[188:191], v[112:115]
	v_mfma_f32_16x16x32_bf16 v[100:103], v[168:171], v[196:199], v[100:103]
	v_mfma_f32_16x16x32_bf16 v[96:99], v[176:179], v[196:199], v[96:99]
	v_mfma_f32_16x16x32_bf16 v[84:87], v[168:171], v[204:207], v[84:87]
	v_mfma_f32_16x16x32_bf16 v[80:83], v[176:179], v[204:207], v[80:83]
	v_mfma_f32_16x16x32_bf16 v[68:71], v[168:171], v[212:215], v[68:71]
	v_mfma_f32_16x16x32_bf16 v[64:67], v[176:179], v[212:215], v[64:67]
	s_barrier
; #define PG8_STAGE(bufoff, gbase, voff) do { _Pragma("unroll") for (int _i = 0; _i < 2; ++_i) \
;         __builtin_amdgcn_global_load_lds((const unsigned*)((const char*)(gbase) + (voff)[_i]), (PG8_LAS unsigned*)(lds + (bufoff) + ldsw + _i * 8192), 16, 0, 0); } while (0)
; #define PG8_LDA(dst, b, h) do { _Pragma("unroll") for (int m = 0; m < 4; ++m) _Pragma("unroll") for (int k = 0; k < 2; ++k) dst[m][k] = *(const PG8_LAS bf16x8*)(lds + PG8_SA(b, h) + aoff + m * 2048 + k * 1024); } while (0)
; #define PG8_MMA(ai, bj, At, Bt) do { __builtin_amdgcn_s_setprio(1); _Pragma("unroll") for (int m = 0; m < 4; ++m) _Pragma("unroll") for (int n = 0; n < 2; ++n) _Pragma("unroll") for (int k = 0; k < 2; ++k) \
;         acc[ai][bj][m][n] = __builtin_amdgcn_mfma_f32_16x16x32_bf16(Bt[n][k], At[m][k], acc[ai][bj][m][n], 0, 0, 0); __builtin_amdgcn_s_setprio(0); } while (0)
; #define PG8_WAIT_V(n) asm volatile("s_waitcnt vmcnt(" #n ")" ::: "memory")
; #define PG8_WAIT_L(n) asm volatile("s_waitcnt lgkmcnt(" #n ")" ::: "memory")
; #define PG8_BAR __builtin_amdgcn_s_barrier()
; #define PG8_SCHED __builtin_amdgcn_sched_barrier(0)
; template <class Epi, class Sched, bool ALIGN_EPI = false, bool SP2 = false>
; __device__ __forceinline__ void gemm_phase(PG8_LAS unsigned char* lds, const Gemm g, const Sched& S, const Epi& E) {
;     ...
;             PG8_LDA(At, 1, 1); PG8_STAGE(PG8_SB(1, 0), b3, voffB); PG8_STAGE(PG8_SB(1, 1), b3 + hstep, voffB); PG8_STAGE(PG8_SA(1, 0), a3, voffA);
;             PG8_WAIT_V(8); PG8_WAIT_L(0); PG8_BAR; PG8_MMA(1, 0, At, B0); PG8_MMA(1, 1, At, B1); PG8_BAR; PG8_SCHED;
;     ...
;         if (!has_next) break;
; #pragma unroll
;         for (int a = 0; a < 2; ++a)
; #pragma unroll
;             for (int b = 0; b < 2; ++b)
; #pragma unroll
;                 for (int m = 0; m < 4; ++m)
; #pragma unroll
;                     for (int n = 0; n < 2; ++n) acc[a][b][m][n] = (f32x4){0.f, 0.f, 0.f, 0.f};
;         cur = nxt; cA = nA; cB = nB; ++ui;
	s_add_i32 s28, s59, s38
	v_lshl_add_u64 v[184:185], v[184:185], 0, s[12:13]
	s_mov_b32 m0, s28
	ds_read_b128 v[180:183], v146 offset:49152
	ds_read_b128 v[188:191], v146 offset:50176
	ds_read_b128 v[192:195], v146 offset:51200
	ds_read_b128 v[196:199], v146 offset:52224
	ds_read_b128 v[200:203], v146 offset:53248
	ds_read_b128 v[204:207], v146 offset:54272
	ds_read_b128 v[208:211], v146 offset:55296
	ds_read_b128 v[212:215], v146 offset:56320
	global_load_lds_dwordx4 v[184:185], off
	s_add_i32 m0, s28, 0x2000
	s_add_u32 s26, s26, 0x40080
	v_lshl_add_u64 v[184:185], v[218:219], 0, s[12:13]
	s_addc_u32 s27, s27, 0
	s_add_i32 s28, s60, s38
	global_load_lds_dwordx4 v[184:185], off
	v_lshl_add_u64 v[184:185], s[26:27], 0, v[128:129]
	s_mov_b32 m0, s28
	s_nop 0
	global_load_lds_dwordx4 v[184:185], off
	v_lshl_add_u64 v[184:185], s[26:27], 0, v[130:131]
	s_add_i32 m0, s28, 0x2000
	s_nop 0
	global_load_lds_dwordx4 v[184:185], off
	v_lshl_add_u64 v[184:185], v[220:221], 0, s[12:13]
	s_mov_b32 m0, s46
	s_nop 0
	global_load_lds_dwordx4 v[184:185], off
	v_lshl_add_u64 v[184:185], v[222:223], 0, s[12:13]
	s_mov_b32 m0, s47
	s_nop 0
	global_load_lds_dwordx4 v[184:185], off
	s_waitcnt vmcnt(8)
	s_waitcnt lgkmcnt(0)
	s_barrier
	s_waitcnt lgkmcnt(0)
	v_mfma_f32_16x16x32_bf16 v[60:63], v[148:151], v[180:183], v[60:63]
	v_mfma_f32_16x16x32_bf16 v[56:59], v[156:159], v[180:183], v[56:59]
	v_mfma_f32_16x16x32_bf16 v[44:47], v[148:151], v[192:195], v[44:47]
	v_mfma_f32_16x16x32_bf16 v[40:43], v[156:159], v[192:195], v[40:43]
	v_mfma_f32_16x16x32_bf16 v[28:31], v[148:151], v[200:203], v[28:31]
	v_mfma_f32_16x16x32_bf16 v[24:27], v[156:159], v[200:203], v[24:27]
	v_mfma_f32_16x16x32_bf16 v[12:15], v[148:151], v[208:211], v[12:15]
	v_mfma_f32_16x16x32_bf16 v[8:11], v[156:159], v[208:211], v[8:11]
	v_mfma_f32_16x16x32_bf16 v[60:63], v[152:155], v[188:191], v[60:63]
	v_mfma_f32_16x16x32_bf16 v[56:59], v[160:163], v[188:191], v[56:59]
	v_mfma_f32_16x16x32_bf16 v[44:47], v[152:155], v[196:199], v[44:47]
	v_mfma_f32_16x16x32_bf16 v[40:43], v[160:163], v[196:199], v[40:43]
	v_mfma_f32_16x16x32_bf16 v[28:31], v[152:155], v[204:207], v[28:31]
	v_mfma_f32_16x16x32_bf16 v[24:27], v[160:163], v[204:207], v[24:27]
	v_mfma_f32_16x16x32_bf16 v[12:15], v[152:155], v[212:215], v[12:15]
	v_mfma_f32_16x16x32_bf16 v[8:11], v[160:163], v[212:215], v[8:11]
	v_mfma_f32_16x16x32_bf16 v[52:55], v[164:167], v[180:183], v[52:55]
	v_mfma_f32_16x16x32_bf16 v[48:51], v[172:175], v[180:183], v[48:51]
	v_mfma_f32_16x16x32_bf16 v[36:39], v[164:167], v[192:195], v[36:39]
	v_mfma_f32_16x16x32_bf16 v[32:35], v[172:175], v[192:195], v[32:35]
	v_mfma_f32_16x16x32_bf16 v[20:23], v[164:167], v[200:203], v[20:23]
	v_mfma_f32_16x16x32_bf16 v[16:19], v[172:175], v[200:203], v[16:19]
	v_mfma_f32_16x16x32_bf16 v[4:7], v[164:167], v[208:211], v[4:7]
	v_mfma_f32_16x16x32_bf16 v[0:3], v[172:175], v[208:211], v[0:3]
	v_mfma_f32_16x16x32_bf16 v[52:55], v[168:171], v[188:191], v[52:55]
	v_mfma_f32_16x16x32_bf16 v[48:51], v[176:179], v[188:191], v[48:51]
	v_mfma_f32_16x16x32_bf16 v[36:39], v[168:171], v[196:199], v[36:39]
	v_mfma_f32_16x16x32_bf16 v[32:35], v[176:179], v[196:199], v[32:35]
	v_mfma_f32_16x16x32_bf16 v[20:23], v[168:171], v[204:207], v[20:23]
	v_mfma_f32_16x16x32_bf16 v[16:19], v[176:179], v[204:207], v[16:19]
	v_mfma_f32_16x16x32_bf16 v[4:7], v[168:171], v[212:215], v[4:7]
	v_mfma_f32_16x16x32_bf16 v[0:3], v[176:179], v[212:215], v[0:3]
	s_barrier
	s_add_i32 s58, s58, 2
	s_add_u32 s24, s24, 0x100
	s_addc_u32 s25, s25, 0
	s_cmp_gt_u32 s58, 13
	s_cbranch_scc0 .LBB0_809
	s_setprio 0
	s_add_u32 s24, s21, 0xffffff00
	s_addc_u32 s25, s51, -1
	s_andn2_b64 vcc, exec, s[2:3]
	s_cbranch_vccnz .LBB0_812
	v_mov_b32_e32 v0, 0
	s_mov_b32 s4, s14
	s_mov_b32 s8, s16
	s_mov_b64 s[10:11], s[22:23]
	s_mov_b32 s48, s20
	v_mov_b32_e32 v1, v0
	v_mov_b32_e32 v2, v0
	v_mov_b32_e32 v3, v0
	v_mov_b32_e32 v4, v0
	v_mov_b32_e32 v5, v0
	v_mov_b32_e32 v6, v0
	v_mov_b32_e32 v7, v0
	v_mov_b32_e32 v16, v0
	v_mov_b32_e32 v17, v0
	v_mov_b32_e32 v18, v0
	v_mov_b32_e32 v19, v0
	v_mov_b32_e32 v20, v0
	v_mov_b32_e32 v21, v0
	v_mov_b32_e32 v22, v0
	v_mov_b32_e32 v23, v0
	v_mov_b32_e32 v32, v0
	v_mov_b32_e32 v33, v0
	v_mov_b32_e32 v34, v0
	v_mov_b32_e32 v35, v0
	v_mov_b32_e32 v36, v0
	v_mov_b32_e32 v37, v0
	v_mov_b32_e32 v38, v0
	v_mov_b32_e32 v39, v0
	v_mov_b32_e32 v48, v0
	v_mov_b32_e32 v49, v0
	v_mov_b32_e32 v50, v0
	v_mov_b32_e32 v51, v0
	v_mov_b32_e32 v52, v0
	v_mov_b32_e32 v53, v0
	v_mov_b32_e32 v54, v0
	v_mov_b32_e32 v55, v0
	v_mov_b32_e32 v8, v0
	v_mov_b32_e32 v9, v0
	v_mov_b32_e32 v10, v0
	v_mov_b32_e32 v11, v0
	v_mov_b32_e32 v12, v0
	v_mov_b32_e32 v13, v0
	v_mov_b32_e32 v14, v0
	v_mov_b32_e32 v15, v0
	v_mov_b32_e32 v24, v0
	v_mov_b32_e32 v25, v0
	v_mov_b32_e32 v26, v0
	v_mov_b32_e32 v27, v0
	v_mov_b32_e32 v28, v0
	v_mov_b32_e32 v29, v0
	v_mov_b32_e32 v30, v0
	v_mov_b32_e32 v31, v0
	v_mov_b32_e32 v40, v0
	v_mov_b32_e32 v41, v0
	v_mov_b32_e32 v42, v0
	v_mov_b32_e32 v43, v0
	v_mov_b32_e32 v44, v0
	v_mov_b32_e32 v45, v0
	v_mov_b32_e32 v46, v0
	v_mov_b32_e32 v47, v0
	v_mov_b32_e32 v56, v0
	v_mov_b32_e32 v57, v0
	v_mov_b32_e32 v58, v0
	v_mov_b32_e32 v59, v0
	v_mov_b32_e32 v60, v0
	v_mov_b32_e32 v61, v0
	v_mov_b32_e32 v62, v0
	v_mov_b32_e32 v63, v0
	v_mov_b32_e32 v64, v0
	v_mov_b32_e32 v65, v0
	v_mov_b32_e32 v66, v0
	v_mov_b32_e32 v67, v0
	v_mov_b32_e32 v68, v0
	v_mov_b32_e32 v69, v0
	v_mov_b32_e32 v70, v0
	v_mov_b32_e32 v71, v0
	v_mov_b32_e32 v80, v0
	v_mov_b32_e32 v81, v0
	v_mov_b32_e32 v82, v0
	v_mov_b32_e32 v83, v0
	v_mov_b32_e32 v84, v0
	v_mov_b32_e32 v85, v0
	v_mov_b32_e32 v86, v0
	v_mov_b32_e32 v87, v0
	v_mov_b32_e32 v96, v0
	v_mov_b32_e32 v97, v0
	v_mov_b32_e32 v98, v0
	v_mov_b32_e32 v99, v0
	v_mov_b32_e32 v100, v0
	v_mov_b32_e32 v101, v0
	v_mov_b32_e32 v102, v0
	v_mov_b32_e32 v103, v0
	v_mov_b32_e32 v112, v0
	v_mov_b32_e32 v113, v0
	v_mov_b32_e32 v114, v0
	v_mov_b32_e32 v115, v0
	v_mov_b32_e32 v116, v0
	v_mov_b32_e32 v117, v0
	v_mov_b32_e32 v118, v0
	v_mov_b32_e32 v119, v0
	v_mov_b32_e32 v72, v0
	v_mov_b32_e32 v73, v0
	v_mov_b32_e32 v74, v0
	v_mov_b32_e32 v75, v0
	v_mov_b32_e32 v76, v0
	v_mov_b32_e32 v77, v0
	v_mov_b32_e32 v78, v0
	v_mov_b32_e32 v79, v0
	v_mov_b32_e32 v88, v0
	v_mov_b32_e32 v89, v0
	v_mov_b32_e32 v90, v0
	v_mov_b32_e32 v91, v0
	v_mov_b32_e32 v92, v0
	v_mov_b32_e32 v93, v0
	v_mov_b32_e32 v94, v0
	v_mov_b32_e32 v95, v0
	v_mov_b32_e32 v104, v0
	v_mov_b32_e32 v105, v0
	v_mov_b32_e32 v106, v0
	v_mov_b32_e32 v107, v0
	v_mov_b32_e32 v108, v0
	v_mov_b32_e32 v109, v0
	v_mov_b32_e32 v110, v0
	v_mov_b32_e32 v111, v0
	v_mov_b32_e32 v120, v0
	v_mov_b32_e32 v121, v0
	v_mov_b32_e32 v122, v0
	v_mov_b32_e32 v123, v0
	v_mov_b32_e32 v124, v0
	v_mov_b32_e32 v125, v0
	v_mov_b32_e32 v126, v0
	v_mov_b32_e32 v127, v0
	s_andn2_b64 vcc, exec, s[0:1]
	s_cbranch_vccnz .LBB0_813
	s_branch .LBB0_814
